# v75 + branch-free far-tile bias constant + GEMM mid-segment setprio pairs deleted + LayerNorm gamma/beta loaded once per wave
# speedup vs baseline: 1.0018x; 1.0000x over previous
; #define GAS __attribute__((address_space(1)))
; __device__ __forceinline__ void ln_rows(const Frame& F, const float* src, float* dstf, bf16* dstb, float* must, const float* gam, const float* bet, int nrows, bool poison) {
;     const int gw = F.vcu * NWAVES + F.wave, NGW = F.G * NWAVES;
;     f32x4 vn[8];
;     if (gw < nrows) { const GAS f32x4* xr = (const GAS f32x4*)(src + (size_t)gw * DM) + F.lane;
; #pragma unroll
;         for (int j = 0; j < 8; ++j) vn[j] = xr[64 * j]; }
;     ...
;         for (int j = 0; j < 8; ++j) { const f32x4 g = ((const GAS f32x4*)gam)[64 * j + F.lane], b = ((const GAS f32x4*)bet)[64 * j + F.lane];
.LBB0_201:
	s_lshl_b32 s8, s33, 3
	s_add_i32 s8, s8, s28
	s_lshl_b32 s10, s97, 3
	s_cmpk_lt_i32 s8, 0x4000
	s_mov_b32 s14, 21
	s_mov_b32 s16, 32
	s_mov_b32 s18, 3
	s_mov_b32 s20, 4
	s_cselect_b64 s[12:13], -1, 0
	s_cmpk_gt_i32 s8, 0x3fff
	s_cbranch_scc1 .LBB0_210
	s_ashr_i32 s15, s14, 31
	s_lshl_b64 s[14:15], s[14:15], 3
	s_add_u32 s14, s0, s14
	s_addc_u32 s15, s1, s15
	s_ashr_i32 s17, s16, 31
	s_lshl_b64 s[16:17], s[16:17], 3
	s_add_u32 s16, s0, s16
	s_addc_u32 s17, s1, s17
	s_ashr_i32 s19, s18, 31
	s_lshl_b64 s[18:19], s[18:19], 3
	s_add_u32 s18, s0, s18
	s_addc_u32 s19, s1, s19
	s_ashr_i32 s21, s20, 31
	s_lshl_b64 s[20:21], s[20:21], 3
	s_add_u32 s20, s0, s20
	s_addc_u32 s21, s1, s21
	s_ashr_i32 s9, s8, 31
	s_lshl_b64 s[22:23], s[8:9], 13
	s_add_u32 s22, s6, s22
	s_addc_u32 s23, s7, s23
	v_lshlrev_b64 v[14:15], 4, v[226:227]
	v_lshl_add_u64 v[16:17], s[22:23], 0, v[14:15]
	s_movk_i32 s11, 0x1000
	v_add_co_u32_e32 v18, vcc, s11, v16
	global_load_dwordx4 v[58:61], v[16:17], off offset:1024 nt
	global_load_dwordx4 v[54:57], v[16:17], off offset:2048 nt
	global_load_dwordx4 v[50:53], v[16:17], off offset:3072 nt
	v_addc_co_u32_e32 v19, vcc, 0, v17, vcc
	global_load_dwordx4 v[2:5], v[18:19], off offset:3072 nt
	global_load_dwordx4 v[6:9], v[18:19], off offset:2048 nt
	global_load_dwordx4 v[10:13], v[18:19], off offset:1024 nt
	global_load_dwordx4 v[30:33], v[18:19], off nt
	global_load_dwordx4 v[62:65], v[16:17], off nt
	s_load_dwordx2 s[18:19], s[18:19], 0x0
	s_nop 0
	s_load_dwordx2 s[22:23], s[14:15], 0x0
	s_nop 0
	s_load_dwordx2 s[14:15], s[20:21], 0x0
	s_nop 0
	s_load_dwordx2 s[20:21], s[16:17], 0x0
	v_lshlrev_b32_e32 v16, 2, v226
	v_lshlrev_b32_e32 v22, 4, v226
	v_cmp_eq_u32_e32 vcc, 0, v226
	v_mov_b32_e32 v17, v227
	s_waitcnt lgkmcnt(0)
	s_cmp_lg_u64 s[20:21], 0
	v_mov_b32_e32 v19, v227
	v_mov_b32_e32 v21, v227
	v_mov_b32_e32 v23, v227
	v_xor_b32_e32 v1, 4, v16
	v_xor_b32_e32 v92, 8, v16
	v_xor_b32_e32 v93, 16, v16
	v_xor_b32_e32 v94, 32, v16
	v_xor_b32_e32 v95, 64, v16
	v_xor_b32_e32 v96, 0x80, v16
	v_or_b32_e32 v16, 0x1000, v22
	v_or_b32_e32 v18, 0x1400, v22
	v_or_b32_e32 v20, 0x1800, v22
	v_or_b32_e32 v22, 0x1c00, v22
	s_cselect_b64 s[16:17], -1, 0
	s_cmp_lg_u64 s[22:23], 0
	v_lshl_add_u64 v[66:67], s[18:19], 0, v[14:15]
	v_lshl_add_u64 v[68:69], s[18:19], 0, v[16:17]
	v_lshl_add_u64 v[70:71], s[18:19], 0, v[18:19]
	v_lshl_add_u64 v[72:73], s[18:19], 0, v[20:21]
	v_lshl_add_u64 v[74:75], s[18:19], 0, v[22:23]
	v_lshl_add_u64 v[76:77], s[14:15], 0, v[14:15]
	v_lshl_add_u64 v[78:79], s[14:15], 0, v[16:17]
	v_lshl_add_u64 v[80:81], s[14:15], 0, v[18:19]
	v_lshl_add_u64 v[82:83], s[14:15], 0, v[20:21]
	v_lshl_add_u64 v[84:85], s[14:15], 0, v[22:23]
	s_cselect_b64 s[14:15], -1, 0
	s_and_b64 s[16:17], s[16:17], vcc
	s_lshl_b64 s[18:19], s[8:9], 3
	s_add_u32 s18, s20, s18
	s_addc_u32 s19, s21, s19
	s_ashr_i32 s11, s10, 31
	s_lshl_b64 s[24:25], s[8:9], 12
	s_lshl_b64 s[20:21], s[10:11], 3
	s_add_u32 s24, s22, s24
	s_addc_u32 s25, s23, s25
	s_add_i32 s26, s8, s10
	v_lshlrev_b32_e32 v24, 3, v226
	v_mov_b32_e32 v25, v227
	s_ashr_i32 s27, s26, 31
	s_lshl_b64 s[22:23], s[10:11], 12
	v_lshl_add_u64 v[86:87], s[24:25], 0, v[24:25]
	s_lshl_b64 s[24:25], s[26:27], 13
	s_add_u32 s6, s6, s24
	s_addc_u32 s7, s7, s25
	v_lshl_add_u64 v[14:15], s[6:7], 0, v[14:15]
	s_mov_b64 s[6:7], 0x1000
	v_lshl_add_u64 v[88:89], v[14:15], 0, s[6:7]
	s_mov_b32 s28, s8
	s_lshl_b64 s[24:25], s[10:11], 13
	global_load_dwordx4 v[112:115], v[66:67], off
	global_load_dwordx4 v[144:147], v[76:77], off
	global_load_dwordx4 v[116:119], v[66:67], off offset:1024
	global_load_dwordx4 v[148:151], v[76:77], off offset:1024
	global_load_dwordx4 v[120:123], v[66:67], off offset:2048
	global_load_dwordx4 v[152:155], v[76:77], off offset:2048
	global_load_dwordx4 v[124:127], v[66:67], off offset:3072
	global_load_dwordx4 v[156:159], v[76:77], off offset:3072
	global_load_dwordx4 v[128:131], v[68:69], off
	global_load_dwordx4 v[160:163], v[78:79], off
	global_load_dwordx4 v[132:135], v[70:71], off
	global_load_dwordx4 v[164:167], v[80:81], off
	global_load_dwordx4 v[136:139], v[72:73], off
	global_load_dwordx4 v[168:171], v[82:83], off
	global_load_dwordx4 v[140:143], v[74:75], off
	global_load_dwordx4 v[172:175], v[84:85], off
	s_waitcnt vmcnt(0)
	v_mov_b64_e32 v[22:23], v[58:59]
	v_mov_b64_e32 v[18:19], v[54:55]
	v_mov_b64_e32 v[14:15], v[50:51]
	v_mov_b64_e32 v[36:37], v[4:5]
	v_mov_b64_e32 v[40:41], v[8:9]
	v_mov_b64_e32 v[44:45], v[12:13]
	v_mov_b64_e32 v[48:49], v[32:33]
	v_mov_b64_e32 v[26:27], v[62:63]
	v_mov_b64_e32 v[16:17], v[52:53]
	v_mov_b64_e32 v[20:21], v[56:57]
	v_mov_b64_e32 v[24:25], v[60:61]
	v_mov_b64_e32 v[34:35], v[2:3]
	v_mov_b64_e32 v[38:39], v[6:7]
	v_mov_b64_e32 v[42:43], v[10:11]
	v_mov_b64_e32 v[46:47], v[30:31]
	v_mov_b64_e32 v[28:29], v[64:65]
	s_branch .LBB0_204

; #define GAS __attribute__((address_space(1)))
; __device__ __forceinline__ unsigned pk2(float lo, float hi) { return f2bf(lo) | (f2bf(hi) << 16); }
; __device__ __forceinline__ void ln_rows(const Frame& F, const float* src, float* dstf, bf16* dstb, float* must, const float* gam, const float* bet, int nrows, bool poison) {
;     ...
;         GAS f32x4* of = (GAS f32x4*)(dstf + (size_t)m * DM) + F.lane;
; #pragma unroll
;         for (int j = 0; j < 8; ++j) { const f32x4 g = ((const GAS f32x4*)gam)[64 * j + F.lane], b = ((const GAS f32x4*)bet)[64 * j + F.lane];
;             f32x4 o = v[j] * rstd * g + b;
;             if (poison) { const float q = __builtin_nanf(""); o = (f32x4){q, q, q, q}; }
;             if (dstf) of[64 * j] = o;
;             if (dstb) { v2u w; w.x = pk2(o.x, o.y); w.y = pk2(o.z, o.w); ((GAS v2u*)(dstb + (size_t)m * DM))[64 * j + F.lane] = w; } }
.LBB0_208:
	s_or_b64 exec, exec, s[6:7]
	s_andn2_b64 vcc, exec, s[14:15]
	s_cbranch_vccnz .LBB0_203
	v_mov_b32_e32 v90, v91
	v_pk_mul_f32 v[64:65], v[64:65], v[90:91] op_sel_hi:[1,0]
	v_pk_mul_f32 v[62:63], v[62:63], v[90:91] op_sel_hi:[1,0]
	v_pk_fma_f32 v[64:65], v[64:65], v[114:115], v[146:147]
	v_pk_fma_f32 v[62:63], v[62:63], v[112:113], v[144:145]
	v_bfe_u32 v98, v64, 16, 1
	v_bfe_u32 v91, v62, 16, 1
	v_bfe_u32 v97, v63, 16, 1
	v_bfe_u32 v99, v65, 16, 1
	v_add3_u32 v62, v62, v91, s72
	v_add3_u32 v64, v64, v98, s72
	v_add3_u32 v63, v63, v97, s72
	v_add3_u32 v65, v65, v99, s72
	v_lshrrev_b32_e32 v62, 16, v62
	v_lshrrev_b32_e32 v64, 16, v64
	v_and_or_b32 v62, v63, s46, v62
	v_and_or_b32 v63, v65, s46, v64
	global_store_dwordx2 v[86:87], v[62:63], off
	v_pk_mul_f32 v[60:61], v[60:61], v[90:91] op_sel_hi:[1,0]
	v_pk_mul_f32 v[58:59], v[58:59], v[90:91] op_sel_hi:[1,0]
	v_pk_mul_f32 v[56:57], v[56:57], v[90:91] op_sel_hi:[1,0]
	v_pk_mul_f32 v[54:55], v[54:55], v[90:91] op_sel_hi:[1,0]
	v_pk_mul_f32 v[52:53], v[52:53], v[90:91] op_sel_hi:[1,0]
	v_pk_mul_f32 v[50:51], v[50:51], v[90:91] op_sel_hi:[1,0]
	v_pk_mul_f32 v[32:33], v[32:33], v[90:91] op_sel_hi:[1,0]
	v_pk_mul_f32 v[30:31], v[30:31], v[90:91] op_sel_hi:[1,0]
	v_pk_mul_f32 v[12:13], v[12:13], v[90:91] op_sel_hi:[1,0]
	v_pk_mul_f32 v[10:11], v[10:11], v[90:91] op_sel_hi:[1,0]
	v_pk_mul_f32 v[8:9], v[8:9], v[90:91] op_sel_hi:[1,0]
	v_pk_mul_f32 v[6:7], v[6:7], v[90:91] op_sel_hi:[1,0]
	v_pk_mul_f32 v[4:5], v[4:5], v[90:91] op_sel_hi:[1,0]
	v_pk_mul_f32 v[2:3], v[2:3], v[90:91] op_sel_hi:[1,0]
	v_pk_fma_f32 v[60:61], v[60:61], v[118:119], v[150:151]
	v_pk_fma_f32 v[58:59], v[58:59], v[116:117], v[148:149]
	v_bfe_u32 v64, v60, 16, 1
	v_bfe_u32 v62, v58, 16, 1
	v_bfe_u32 v63, v59, 16, 1
	v_bfe_u32 v65, v61, 16, 1
	v_add3_u32 v58, v58, v62, s72
	v_add3_u32 v60, v60, v64, s72
	v_add3_u32 v59, v59, v63, s72
	v_add3_u32 v61, v61, v65, s72
	v_lshrrev_b32_e32 v58, 16, v58
	v_lshrrev_b32_e32 v60, 16, v60
	v_and_or_b32 v58, v59, s46, v58
	v_and_or_b32 v59, v61, s46, v60
	global_store_dwordx2 v[86:87], v[58:59], off offset:512
	v_pk_fma_f32 v[56:57], v[56:57], v[122:123], v[154:155]
	v_pk_fma_f32 v[54:55], v[54:55], v[120:121], v[152:153]
	v_bfe_u32 v60, v56, 16, 1
	v_bfe_u32 v58, v54, 16, 1
	v_bfe_u32 v59, v55, 16, 1
	v_bfe_u32 v61, v57, 16, 1
	v_add3_u32 v54, v54, v58, s72
	v_add3_u32 v56, v56, v60, s72
	v_add3_u32 v55, v55, v59, s72
	v_add3_u32 v57, v57, v61, s72
	v_lshrrev_b32_e32 v54, 16, v54
	v_lshrrev_b32_e32 v56, 16, v56
	v_and_or_b32 v54, v55, s46, v54
	v_and_or_b32 v55, v57, s46, v56
	global_store_dwordx2 v[86:87], v[54:55], off offset:1024
	v_pk_fma_f32 v[52:53], v[52:53], v[126:127], v[158:159]
	v_pk_fma_f32 v[50:51], v[50:51], v[124:125], v[156:157]
	v_bfe_u32 v56, v52, 16, 1
	v_bfe_u32 v54, v50, 16, 1
	v_bfe_u32 v55, v51, 16, 1
	v_bfe_u32 v57, v53, 16, 1
	v_add3_u32 v50, v50, v54, s72
	v_add3_u32 v52, v52, v56, s72
	v_add3_u32 v51, v51, v55, s72
	v_add3_u32 v53, v53, v57, s72
	v_lshrrev_b32_e32 v50, 16, v50
	v_lshrrev_b32_e32 v52, 16, v52
	v_and_or_b32 v50, v51, s46, v50
	v_and_or_b32 v51, v53, s46, v52
	global_store_dwordx2 v[86:87], v[50:51], off offset:1536
	v_pk_fma_f32 v[32:33], v[32:33], v[130:131], v[162:163]
	v_pk_fma_f32 v[30:31], v[30:31], v[128:129], v[160:161]
	v_bfe_u32 v52, v32, 16, 1
	v_bfe_u32 v50, v30, 16, 1
	v_bfe_u32 v51, v31, 16, 1
	v_bfe_u32 v53, v33, 16, 1
	v_add3_u32 v30, v30, v50, s72
	v_add3_u32 v32, v32, v52, s72
	v_add3_u32 v31, v31, v51, s72
	v_add3_u32 v33, v33, v53, s72
	v_lshrrev_b32_e32 v30, 16, v30
	v_lshrrev_b32_e32 v32, 16, v32
	v_and_or_b32 v30, v31, s46, v30
	v_and_or_b32 v31, v33, s46, v32
	global_store_dwordx2 v[86:87], v[30:31], off offset:2048
	v_pk_fma_f32 v[12:13], v[12:13], v[134:135], v[166:167]
	v_pk_fma_f32 v[10:11], v[10:11], v[132:133], v[164:165]
	v_bfe_u32 v32, v12, 16, 1
	v_bfe_u32 v30, v10, 16, 1
	v_bfe_u32 v31, v11, 16, 1
	v_bfe_u32 v33, v13, 16, 1
	v_add3_u32 v10, v10, v30, s72
	v_add3_u32 v12, v12, v32, s72
	v_add3_u32 v11, v11, v31, s72
	v_add3_u32 v13, v13, v33, s72
	v_lshrrev_b32_e32 v10, 16, v10
	v_lshrrev_b32_e32 v12, 16, v12
	v_and_or_b32 v10, v11, s46, v10
	v_and_or_b32 v11, v13, s46, v12
	global_store_dwordx2 v[86:87], v[10:11], off offset:2560
	v_pk_fma_f32 v[8:9], v[8:9], v[138:139], v[170:171]
	v_pk_fma_f32 v[6:7], v[6:7], v[136:137], v[168:169]
	v_bfe_u32 v12, v8, 16, 1
	v_bfe_u32 v10, v6, 16, 1
	v_bfe_u32 v11, v7, 16, 1
	v_bfe_u32 v13, v9, 16, 1
	v_add3_u32 v6, v6, v10, s72
	v_add3_u32 v8, v8, v12, s72
	v_add3_u32 v7, v7, v11, s72
	v_add3_u32 v9, v9, v13, s72
	v_lshrrev_b32_e32 v6, 16, v6
	v_lshrrev_b32_e32 v8, 16, v8
	v_and_or_b32 v6, v7, s46, v6
	v_and_or_b32 v7, v9, s46, v8
	global_store_dwordx2 v[86:87], v[6:7], off offset:3072
	v_pk_fma_f32 v[4:5], v[4:5], v[142:143], v[174:175]
	v_pk_fma_f32 v[2:3], v[2:3], v[140:141], v[172:173]
	v_bfe_u32 v8, v4, 16, 1
	v_bfe_u32 v6, v2, 16, 1
	v_bfe_u32 v7, v3, 16, 1
	v_bfe_u32 v9, v5, 16, 1
	v_add3_u32 v2, v2, v6, s72
	v_add3_u32 v4, v4, v8, s72
	v_add3_u32 v3, v3, v7, s72
	v_add3_u32 v5, v5, v9, s72
	v_lshrrev_b32_e32 v2, 16, v2
	v_lshrrev_b32_e32 v4, 16, v4
	v_and_or_b32 v2, v3, s46, v2
	v_and_or_b32 v3, v5, s46, v4
	global_store_dwordx2 v[86:87], v[2:3], off offset:3584
	s_branch .LBB0_203

; #define PG8_STAGE(bufoff, gbase, voff) do { _Pragma("unroll") for (int _i = 0; _i < 2; ++_i) \
;         __builtin_amdgcn_global_load_lds((const unsigned*)((const char*)(gbase) + (voff)[_i]), (PG8_LAS unsigned*)(lds + (bufoff) + ldsw + _i * 8192), 16, 0, 0); } while (0)
; #define PG8_LDA(dst, b, h) do { _Pragma("unroll") for (int m = 0; m < 4; ++m) _Pragma("unroll") for (int k = 0; k < 2; ++k) dst[m][k] = *(const PG8_LAS bf16x8*)(lds + PG8_SA(b, h) + aoff + m * 2048 + k * 1024); } while (0)
; #define PG8_LDB(dst, b, h) do { _Pragma("unroll") for (int n = 0; n < 2; ++n) _Pragma("unroll") for (int k = 0; k < 2; ++k) dst[n][k] = *(const PG8_LAS bf16x8*)(lds + PG8_SB(b, h) + boff + n * 2048 + k * 1024); } while (0)
; #define PG8_MMA(ai, bj, At, Bt) do { __builtin_amdgcn_s_setprio(1); _Pragma("unroll") for (int m = 0; m < 4; ++m) _Pragma("unroll") for (int n = 0; n < 2; ++n) _Pragma("unroll") for (int k = 0; k < 2; ++k) \
;         acc[ai][bj][m][n] = __builtin_amdgcn_mfma_f32_16x16x32_bf16(Bt[n][k], At[m][k], acc[ai][bj][m][n], 0, 0, 0); __builtin_amdgcn_s_setprio(0); } while (0)
; #define PG8_WAIT_V(n) asm volatile("s_waitcnt vmcnt(" #n ")" ::: "memory")
; #define PG8_WAIT_L(n) asm volatile("s_waitcnt lgkmcnt(" #n ")" ::: "memory")
; #define PG8_BAR __builtin_amdgcn_s_barrier()
; #define PG8_SCHED __builtin_amdgcn_sched_barrier(0)
; template <class Prob, class Epi, class Sched>
; __device__ __forceinline__ void gemm_phase(PG8_LAS unsigned char* lds, const Prob g, const Sched& S, const Epi& E) {
;     ...
;             PG8_LDB(B0, 0, 0); PG8_LDB(B1, 0, 1); PG8_SCHED; PG8_LDA(At, 0, 0); PG8_STAGE(PG8_SA(1, 1), a1 + hstepA, voffA);
;             PG8_WAIT_V(8); PG8_WAIT_L(0); PG8_BAR; PG8_MMA(0, 0, At, B0); PG8_MMA(0, 1, At, B1); PG8_BAR; PG8_SCHED;
;             PG8_LDA(At, 0, 1); PG8_STAGE(PG8_SB(0, 0), b2, voffB); PG8_STAGE(PG8_SB(0, 1), b2 + hstepB, voffB); PG8_STAGE(PG8_SA(0, 0), a2, voffA);
;             PG8_WAIT_V(8); PG8_WAIT_L(0); PG8_BAR; PG8_MMA(1, 0, At, B0); PG8_MMA(1, 1, At, B1); PG8_BAR; PG8_SCHED;
.LBB0_271:
	s_add_u32 s34, s8, 0xfff80080
	s_addc_u32 s35, s9, -1
	s_add_i32 s40, 0, 0x10000
	s_cmp_eq_u32 s66, 28
	s_cselect_b32 s37, s27, s35
	s_cselect_b32 s36, s38, s34
	v_add_u32_e32 v1, s40, v163
	s_cselect_b32 s35, s25, s45
	s_cselect_b32 s34, s39, s44
	s_add_i32 s48, 0, 0x14000
	ds_read_b128 v[66:69], v1
	ds_read_b128 v[70:73], v1 offset:1024
	ds_read_b128 v[74:77], v1 offset:2048
	ds_read_b128 v[78:81], v1 offset:3072
	v_add_u32_e32 v1, s48, v163
	ds_read_b128 v[156:159], v1
	ds_read_b128 v[166:169], v1 offset:1024
	ds_read_b128 v[170:173], v1 offset:2048
	ds_read_b128 v[174:177], v1 offset:3072
	s_add_i32 m0, s43, 0xc000
	ds_read_b128 v[178:181], v165
	ds_read_b128 v[182:185], v165 offset:1024
	ds_read_b128 v[186:189], v165 offset:2048
	ds_read_b128 v[190:193], v165 offset:3072
	ds_read_b128 v[194:197], v165 offset:4096
	ds_read_b128 v[198:201], v165 offset:5120
	ds_read_b128 v[202:205], v165 offset:6144
	ds_read_b128 v[206:209], v165 offset:7168
	global_load_lds_dwordx4 v152, s[8:9]
	s_add_i32 m0, s43, 0xe000
	s_nop 0
	global_load_lds_dwordx4 v154, s[8:9]
	s_waitcnt vmcnt(8)
	s_waitcnt lgkmcnt(0)
	s_setprio 1
	s_barrier
	v_mfma_f32_16x16x32_bf16 v[142:145], v[66:69], v[178:181], v[142:145]
	v_mfma_f32_16x16x32_bf16 v[138:141], v[74:77], v[178:181], v[138:141]
	v_mfma_f32_16x16x32_bf16 v[126:129], v[66:69], v[186:189], v[126:129]
	v_mfma_f32_16x16x32_bf16 v[122:125], v[74:77], v[186:189], v[122:125]
	v_mfma_f32_16x16x32_bf16 v[110:113], v[66:69], v[194:197], v[110:113]
	v_mfma_f32_16x16x32_bf16 v[106:109], v[74:77], v[194:197], v[106:109]
	v_mfma_f32_16x16x32_bf16 v[94:97], v[66:69], v[202:205], v[94:97]
	v_mfma_f32_16x16x32_bf16 v[90:93], v[74:77], v[202:205], v[90:93]
	v_mfma_f32_16x16x32_bf16 v[142:145], v[70:73], v[182:185], v[142:145]
	v_mfma_f32_16x16x32_bf16 v[138:141], v[78:81], v[182:185], v[138:141]
	v_mfma_f32_16x16x32_bf16 v[126:129], v[70:73], v[190:193], v[126:129]
	v_mfma_f32_16x16x32_bf16 v[122:125], v[78:81], v[190:193], v[122:125]
	v_mfma_f32_16x16x32_bf16 v[110:113], v[70:73], v[198:201], v[110:113]
	v_mfma_f32_16x16x32_bf16 v[106:109], v[78:81], v[198:201], v[106:109]
	v_mfma_f32_16x16x32_bf16 v[94:97], v[70:73], v[206:209], v[94:97]
	v_mfma_f32_16x16x32_bf16 v[90:93], v[78:81], v[206:209], v[90:93]
	v_mfma_f32_16x16x32_bf16 v[134:137], v[156:159], v[178:181], v[134:137]
	v_mfma_f32_16x16x32_bf16 v[130:133], v[170:173], v[178:181], v[130:133]
	v_mfma_f32_16x16x32_bf16 v[118:121], v[156:159], v[186:189], v[118:121]
	v_mfma_f32_16x16x32_bf16 v[114:117], v[170:173], v[186:189], v[114:117]
	v_mfma_f32_16x16x32_bf16 v[102:105], v[156:159], v[194:197], v[102:105]
	v_mfma_f32_16x16x32_bf16 v[98:101], v[170:173], v[194:197], v[98:101]
	v_mfma_f32_16x16x32_bf16 v[86:89], v[156:159], v[202:205], v[86:89]
	v_mfma_f32_16x16x32_bf16 v[82:85], v[170:173], v[202:205], v[82:85]
	v_mfma_f32_16x16x32_bf16 v[134:137], v[166:169], v[182:185], v[134:137]
	v_mfma_f32_16x16x32_bf16 v[130:133], v[174:177], v[182:185], v[130:133]
	v_mfma_f32_16x16x32_bf16 v[118:121], v[166:169], v[190:193], v[118:121]
	v_mfma_f32_16x16x32_bf16 v[114:117], v[174:177], v[190:193], v[114:117]
	v_mfma_f32_16x16x32_bf16 v[102:105], v[166:169], v[198:201], v[102:105]
	v_mfma_f32_16x16x32_bf16 v[98:101], v[174:177], v[198:201], v[98:101]
	v_mfma_f32_16x16x32_bf16 v[86:89], v[166:169], v[206:209], v[86:89]
	v_mfma_f32_16x16x32_bf16 v[82:85], v[174:177], v[206:209], v[82:85]
	s_barrier
	s_setprio 0
	s_add_i32 s40, s40, s42
	s_mov_b32 m0, s40
	ds_read_b128 v[178:181], v165 offset:16384
	ds_read_b128 v[182:185], v165 offset:17408
	ds_read_b128 v[186:189], v165 offset:18432
	ds_read_b128 v[190:193], v165 offset:19456
	ds_read_b128 v[194:197], v165 offset:20480
	ds_read_b128 v[198:201], v165 offset:21504
	ds_read_b128 v[202:205], v165 offset:22528
	ds_read_b128 v[206:209], v165 offset:23552
	global_load_lds_dwordx4 v226, s[34:35]
	s_add_i32 m0, s40, 0x2000
	s_add_u32 s40, s34, 0x80000
	s_addc_u32 s41, s35, 0
	s_add_i32 s48, s48, s42
	global_load_lds_dwordx4 v146, s[34:35]
	s_mov_b32 m0, s48
	v_lshl_add_u64 v[214:215], s[36:37], 0, v[148:149]
	global_load_lds_dwordx4 v226, s[40:41]
	s_add_i32 m0, s48, 0x2000
	s_nop 0
	global_load_lds_dwordx4 v146, s[40:41]
	v_lshl_add_u64 v[212:213], s[36:37], 0, v[150:151]
	s_mov_b32 m0, s43
	s_nop 0
	global_load_lds_dwordx4 v150, s[36:37]
	s_mov_b32 m0, s51
	s_nop 0
	global_load_lds_dwordx4 v148, s[36:37]
	s_waitcnt vmcnt(8)
	s_waitcnt lgkmcnt(0)
	s_setprio 1
	s_barrier
	v_mfma_f32_16x16x32_bf16 v[62:65], v[66:69], v[178:181], v[62:65]
	v_mfma_f32_16x16x32_bf16 v[58:61], v[74:77], v[178:181], v[58:61]
	v_mfma_f32_16x16x32_bf16 v[46:49], v[66:69], v[186:189], v[46:49]
	v_mfma_f32_16x16x32_bf16 v[42:45], v[74:77], v[186:189], v[42:45]
	v_mfma_f32_16x16x32_bf16 v[30:33], v[66:69], v[194:197], v[30:33]
	v_mfma_f32_16x16x32_bf16 v[26:29], v[74:77], v[194:197], v[26:29]
	v_mfma_f32_16x16x32_bf16 v[14:17], v[66:69], v[202:205], v[14:17]
	v_mfma_f32_16x16x32_bf16 v[10:13], v[74:77], v[202:205], v[10:13]
	v_mfma_f32_16x16x32_bf16 v[62:65], v[70:73], v[182:185], v[62:65]
	v_mfma_f32_16x16x32_bf16 v[58:61], v[78:81], v[182:185], v[58:61]
	v_mfma_f32_16x16x32_bf16 v[46:49], v[70:73], v[190:193], v[46:49]
	v_mfma_f32_16x16x32_bf16 v[42:45], v[78:81], v[190:193], v[42:45]
	v_mfma_f32_16x16x32_bf16 v[30:33], v[70:73], v[198:201], v[30:33]
	v_mfma_f32_16x16x32_bf16 v[26:29], v[78:81], v[198:201], v[26:29]
	v_mfma_f32_16x16x32_bf16 v[14:17], v[70:73], v[206:209], v[14:17]
	v_mfma_f32_16x16x32_bf16 v[10:13], v[78:81], v[206:209], v[10:13]
	v_mfma_f32_16x16x32_bf16 v[54:57], v[156:159], v[178:181], v[54:57]
	v_mfma_f32_16x16x32_bf16 v[50:53], v[170:173], v[178:181], v[50:53]
	v_mfma_f32_16x16x32_bf16 v[38:41], v[156:159], v[186:189], v[38:41]
	v_mfma_f32_16x16x32_bf16 v[34:37], v[170:173], v[186:189], v[34:37]
	v_mfma_f32_16x16x32_bf16 v[22:25], v[156:159], v[194:197], v[22:25]
	v_mfma_f32_16x16x32_bf16 v[18:21], v[170:173], v[194:197], v[18:21]
	v_mfma_f32_16x16x32_bf16 v[6:9], v[156:159], v[202:205], v[6:9]
	v_mfma_f32_16x16x32_bf16 v[2:5], v[170:173], v[202:205], v[2:5]
	v_mfma_f32_16x16x32_bf16 v[54:57], v[166:169], v[182:185], v[54:57]
	v_mfma_f32_16x16x32_bf16 v[50:53], v[174:177], v[182:185], v[50:53]
	v_mfma_f32_16x16x32_bf16 v[38:41], v[166:169], v[190:193], v[38:41]
	v_mfma_f32_16x16x32_bf16 v[34:37], v[174:177], v[190:193], v[34:37]
	v_mfma_f32_16x16x32_bf16 v[22:25], v[166:169], v[198:201], v[22:25]
	v_mfma_f32_16x16x32_bf16 v[18:21], v[174:177], v[198:201], v[18:21]
	v_mfma_f32_16x16x32_bf16 v[6:9], v[166:169], v[206:209], v[6:9]
	v_mfma_f32_16x16x32_bf16 v[2:5], v[174:177], v[206:209], v[2:5]
	s_barrier
; #define PG8_STAGE(bufoff, gbase, voff) do { _Pragma("unroll") for (int _i = 0; _i < 2; ++_i) \
;         __builtin_amdgcn_global_load_lds((const unsigned*)((const char*)(gbase) + (voff)[_i]), (PG8_LAS unsigned*)(lds + (bufoff) + ldsw + _i * 8192), 16, 0, 0); } while (0)
; #define PG8_LDA(dst, b, h) do { _Pragma("unroll") for (int m = 0; m < 4; ++m) _Pragma("unroll") for (int k = 0; k < 2; ++k) dst[m][k] = *(const PG8_LAS bf16x8*)(lds + PG8_SA(b, h) + aoff + m * 2048 + k * 1024); } while (0)
; #define PG8_LDB(dst, b, h) do { _Pragma("unroll") for (int n = 0; n < 2; ++n) _Pragma("unroll") for (int k = 0; k < 2; ++k) dst[n][k] = *(const PG8_LAS bf16x8*)(lds + PG8_SB(b, h) + boff + n * 2048 + k * 1024); } while (0)
; #define PG8_MMA(ai, bj, At, Bt) do { __builtin_amdgcn_s_setprio(1); _Pragma("unroll") for (int m = 0; m < 4; ++m) _Pragma("unroll") for (int n = 0; n < 2; ++n) _Pragma("unroll") for (int k = 0; k < 2; ++k) \
;         acc[ai][bj][m][n] = __builtin_amdgcn_mfma_f32_16x16x32_bf16(Bt[n][k], At[m][k], acc[ai][bj][m][n], 0, 0, 0); __builtin_amdgcn_s_setprio(0); } while (0)
; #define PG8_WAIT_V(n) asm volatile("s_waitcnt vmcnt(" #n ")" ::: "memory")
; #define PG8_WAIT_L(n) asm volatile("s_waitcnt lgkmcnt(" #n ")" ::: "memory")
; #define PG8_BAR __builtin_amdgcn_s_barrier()
; #define PG8_SCHED __builtin_amdgcn_sched_barrier(0)
; template <class Prob, class Epi, class Sched>
; __device__ __forceinline__ void gemm_phase(PG8_LAS unsigned char* lds, const Prob g, const Sched& S, const Epi& E) {
;     ...
;             PG8_LDB(B0, 1, 0); PG8_LDB(B1, 1, 1); PG8_SCHED; PG8_LDA(At, 1, 0); PG8_STAGE(PG8_SA(0, 1), a2 + hstepA, voffA);
;             PG8_WAIT_V(8); PG8_WAIT_L(0); PG8_BAR; PG8_MMA(0, 0, At, B0); PG8_MMA(0, 1, At, B1); PG8_BAR; PG8_SCHED;
;             PG8_LDA(At, 1, 1); PG8_STAGE(PG8_SB(1, 0), b3, voffB); PG8_STAGE(PG8_SB(1, 1), b3 + hstepB, voffB); PG8_STAGE(PG8_SA(1, 0), a3, voffA);
;             PG8_WAIT_V(8); PG8_WAIT_L(0); PG8_BAR; PG8_MMA(1, 0, At, B0); PG8_MMA(1, 1, At, B1); PG8_BAR; PG8_SCHED;
;         }
;         if (wr == 0) PG8_BAR;
	s_setprio 0
	s_add_i32 s40, 0, 0x18000
	v_add_u32_e32 v1, s40, v163
	s_add_i32 s41, 0, 0x1c000
	ds_read_b128 v[66:69], v1
	ds_read_b128 v[70:73], v1 offset:1024
	ds_read_b128 v[74:77], v1 offset:2048
	ds_read_b128 v[78:81], v1 offset:3072
	v_add_u32_e32 v1, s41, v163
	ds_read_b128 v[156:159], v1
	ds_read_b128 v[166:169], v1 offset:1024
	ds_read_b128 v[170:173], v1 offset:2048
	ds_read_b128 v[174:177], v1 offset:3072
	s_add_u32 s36, s36, 0x80000
	s_addc_u32 s37, s37, 0
	s_mov_b32 m0, s56
	ds_read_b128 v[178:181], v165 offset:32768
	ds_read_b128 v[182:185], v165 offset:33792
	ds_read_b128 v[186:189], v165 offset:34816
	ds_read_b128 v[190:193], v165 offset:35840
	ds_read_b128 v[194:197], v165 offset:36864
	ds_read_b128 v[198:201], v165 offset:37888
	ds_read_b128 v[202:205], v165 offset:38912
	ds_read_b128 v[206:209], v165 offset:39936
	global_load_lds_dwordx4 v150, s[36:37]
	s_mov_b32 m0, s57
	s_nop 0
	global_load_lds_dwordx4 v148, s[36:37]
	s_waitcnt vmcnt(8)
	s_waitcnt lgkmcnt(0)
	s_setprio 1
	s_barrier
	v_mfma_f32_16x16x32_bf16 v[142:145], v[66:69], v[178:181], v[142:145]
	v_mfma_f32_16x16x32_bf16 v[138:141], v[74:77], v[178:181], v[138:141]
	v_mfma_f32_16x16x32_bf16 v[126:129], v[66:69], v[186:189], v[126:129]
	v_mfma_f32_16x16x32_bf16 v[122:125], v[74:77], v[186:189], v[122:125]
	v_mfma_f32_16x16x32_bf16 v[110:113], v[66:69], v[194:197], v[110:113]
	v_mfma_f32_16x16x32_bf16 v[106:109], v[74:77], v[194:197], v[106:109]
	v_mfma_f32_16x16x32_bf16 v[94:97], v[66:69], v[202:205], v[94:97]
	v_mfma_f32_16x16x32_bf16 v[90:93], v[74:77], v[202:205], v[90:93]
	v_mfma_f32_16x16x32_bf16 v[142:145], v[70:73], v[182:185], v[142:145]
	v_mfma_f32_16x16x32_bf16 v[138:141], v[78:81], v[182:185], v[138:141]
	v_mfma_f32_16x16x32_bf16 v[126:129], v[70:73], v[190:193], v[126:129]
	v_mfma_f32_16x16x32_bf16 v[122:125], v[78:81], v[190:193], v[122:125]
	v_mfma_f32_16x16x32_bf16 v[110:113], v[70:73], v[198:201], v[110:113]
	v_mfma_f32_16x16x32_bf16 v[106:109], v[78:81], v[198:201], v[106:109]
	v_mfma_f32_16x16x32_bf16 v[94:97], v[70:73], v[206:209], v[94:97]
	v_mfma_f32_16x16x32_bf16 v[90:93], v[78:81], v[206:209], v[90:93]
	v_mfma_f32_16x16x32_bf16 v[134:137], v[156:159], v[178:181], v[134:137]
	v_mfma_f32_16x16x32_bf16 v[130:133], v[170:173], v[178:181], v[130:133]
	v_mfma_f32_16x16x32_bf16 v[118:121], v[156:159], v[186:189], v[118:121]
	v_mfma_f32_16x16x32_bf16 v[114:117], v[170:173], v[186:189], v[114:117]
	v_mfma_f32_16x16x32_bf16 v[102:105], v[156:159], v[194:197], v[102:105]
	v_mfma_f32_16x16x32_bf16 v[98:101], v[170:173], v[194:197], v[98:101]
	v_mfma_f32_16x16x32_bf16 v[86:89], v[156:159], v[202:205], v[86:89]
	v_mfma_f32_16x16x32_bf16 v[82:85], v[170:173], v[202:205], v[82:85]
	v_mfma_f32_16x16x32_bf16 v[134:137], v[166:169], v[182:185], v[134:137]
	v_mfma_f32_16x16x32_bf16 v[130:133], v[174:177], v[182:185], v[130:133]
	v_mfma_f32_16x16x32_bf16 v[118:121], v[166:169], v[190:193], v[118:121]
	v_mfma_f32_16x16x32_bf16 v[114:117], v[174:177], v[190:193], v[114:117]
	v_mfma_f32_16x16x32_bf16 v[102:105], v[166:169], v[198:201], v[102:105]
	v_mfma_f32_16x16x32_bf16 v[98:101], v[174:177], v[198:201], v[98:101]
	v_mfma_f32_16x16x32_bf16 v[86:89], v[166:169], v[206:209], v[86:89]
	v_mfma_f32_16x16x32_bf16 v[82:85], v[174:177], v[206:209], v[82:85]
	s_barrier
	s_setprio 0
	s_add_i32 s36, s40, s42
	s_mov_b32 m0, s36
	ds_read_b128 v[178:181], v165 offset:49152
	ds_read_b128 v[182:185], v165 offset:50176
	ds_read_b128 v[186:189], v165 offset:51200
	ds_read_b128 v[190:193], v165 offset:52224
	ds_read_b128 v[194:197], v165 offset:53248
	ds_read_b128 v[198:201], v165 offset:54272
	ds_read_b128 v[202:205], v165 offset:55296
	ds_read_b128 v[206:209], v165 offset:56320
	s_add_u32 s100, s34, 0x80
	s_addc_u32 s101, s35, 0
	global_load_lds_dwordx4 v226, s[100:101]
	s_add_i32 m0, s36, 0x2000
	s_add_u32 s34, s34, 0x80080
	s_addc_u32 s35, s35, 0
	s_add_i32 s36, s41, s42
	global_load_lds_dwordx4 v146, s[100:101]
	s_mov_b32 m0, s36
	s_nop 0
	global_load_lds_dwordx4 v226, s[34:35]
	s_add_i32 m0, s36, 0x2000
	s_nop 0
	global_load_lds_dwordx4 v146, s[34:35]
	v_lshl_add_u64 v[160:161], v[212:213], 0, s[88:89]
	s_mov_b32 m0, s52
	s_nop 0
	global_load_lds_dwordx4 v[160:161], off
	v_lshl_add_u64 v[160:161], v[214:215], 0, s[88:89]
	s_mov_b32 m0, s53
	s_nop 0
	global_load_lds_dwordx4 v[160:161], off
	s_waitcnt vmcnt(8)
	s_waitcnt lgkmcnt(0)
	s_setprio 1
	s_barrier
	v_mfma_f32_16x16x32_bf16 v[62:65], v[66:69], v[178:181], v[62:65]
	v_mfma_f32_16x16x32_bf16 v[58:61], v[74:77], v[178:181], v[58:61]
	v_mfma_f32_16x16x32_bf16 v[46:49], v[66:69], v[186:189], v[46:49]
	v_mfma_f32_16x16x32_bf16 v[42:45], v[74:77], v[186:189], v[42:45]
	v_mfma_f32_16x16x32_bf16 v[30:33], v[66:69], v[194:197], v[30:33]
	v_mfma_f32_16x16x32_bf16 v[26:29], v[74:77], v[194:197], v[26:29]
	v_mfma_f32_16x16x32_bf16 v[14:17], v[66:69], v[202:205], v[14:17]
	v_mfma_f32_16x16x32_bf16 v[10:13], v[74:77], v[202:205], v[10:13]
	v_mfma_f32_16x16x32_bf16 v[62:65], v[70:73], v[182:185], v[62:65]
	v_mfma_f32_16x16x32_bf16 v[58:61], v[78:81], v[182:185], v[58:61]
	v_mfma_f32_16x16x32_bf16 v[46:49], v[70:73], v[190:193], v[46:49]
	v_mfma_f32_16x16x32_bf16 v[42:45], v[78:81], v[190:193], v[42:45]
	v_mfma_f32_16x16x32_bf16 v[30:33], v[70:73], v[198:201], v[30:33]
	v_mfma_f32_16x16x32_bf16 v[26:29], v[78:81], v[198:201], v[26:29]
	v_mfma_f32_16x16x32_bf16 v[14:17], v[70:73], v[206:209], v[14:17]
	v_mfma_f32_16x16x32_bf16 v[10:13], v[78:81], v[206:209], v[10:13]
	v_mfma_f32_16x16x32_bf16 v[54:57], v[156:159], v[178:181], v[54:57]
	v_mfma_f32_16x16x32_bf16 v[50:53], v[170:173], v[178:181], v[50:53]
	v_mfma_f32_16x16x32_bf16 v[38:41], v[156:159], v[186:189], v[38:41]
	v_mfma_f32_16x16x32_bf16 v[34:37], v[170:173], v[186:189], v[34:37]
	v_mfma_f32_16x16x32_bf16 v[22:25], v[156:159], v[194:197], v[22:25]
	v_mfma_f32_16x16x32_bf16 v[18:21], v[170:173], v[194:197], v[18:21]
	v_mfma_f32_16x16x32_bf16 v[6:9], v[156:159], v[202:205], v[6:9]
	v_mfma_f32_16x16x32_bf16 v[2:5], v[170:173], v[202:205], v[2:5]
	v_mfma_f32_16x16x32_bf16 v[54:57], v[166:169], v[182:185], v[54:57]
	v_mfma_f32_16x16x32_bf16 v[50:53], v[174:177], v[182:185], v[50:53]
	v_mfma_f32_16x16x32_bf16 v[38:41], v[166:169], v[190:193], v[38:41]
	v_mfma_f32_16x16x32_bf16 v[34:37], v[174:177], v[190:193], v[34:37]
	v_mfma_f32_16x16x32_bf16 v[22:25], v[166:169], v[198:201], v[22:25]
	v_mfma_f32_16x16x32_bf16 v[18:21], v[174:177], v[198:201], v[18:21]
	v_mfma_f32_16x16x32_bf16 v[6:9], v[166:169], v[206:209], v[6:9]
	v_mfma_f32_16x16x32_bf16 v[2:5], v[174:177], v[206:209], v[2:5]
	s_barrier
	s_setprio 0
	s_add_i32 s66, s66, 2
	s_add_u32 s8, s8, 0x100
	s_addc_u32 s9, s9, 0
	s_add_u32 s44, s44, 0x100
	s_addc_u32 s45, s45, 0
	s_cmp_gt_u32 s66, 29
	s_cbranch_scc0 .LBB0_271
	s_and_b64 vcc, exec, s[22:23]
	s_cbranch_vccz .LBB0_274
	s_barrier

; #define PG8_STAGE(bufoff, gbase, voff) do { _Pragma("unroll") for (int _i = 0; _i < 2; ++_i) \
;         __builtin_amdgcn_global_load_lds((const unsigned*)((const char*)(gbase) + (voff)[_i]), (PG8_LAS unsigned*)(lds + (bufoff) + ldsw + _i * 8192), 16, 0, 0); } while (0)
; #define PG8_LDA(dst, b, h) do { _Pragma("unroll") for (int m = 0; m < 4; ++m) _Pragma("unroll") for (int k = 0; k < 2; ++k) dst[m][k] = *(const PG8_LAS bf16x8*)(lds + PG8_SA(b, h) + aoff + m * 2048 + k * 1024); } while (0)
; #define PG8_LDB(dst, b, h) do { _Pragma("unroll") for (int n = 0; n < 2; ++n) _Pragma("unroll") for (int k = 0; k < 2; ++k) dst[n][k] = *(const PG8_LAS bf16x8*)(lds + PG8_SB(b, h) + boff + n * 2048 + k * 1024); } while (0)
; #define PG8_MMA(ai, bj, At, Bt) do { __builtin_amdgcn_s_setprio(1); _Pragma("unroll") for (int m = 0; m < 4; ++m) _Pragma("unroll") for (int n = 0; n < 2; ++n) _Pragma("unroll") for (int k = 0; k < 2; ++k) \
;         acc[ai][bj][m][n] = __builtin_amdgcn_mfma_f32_16x16x32_bf16(Bt[n][k], At[m][k], acc[ai][bj][m][n], 0, 0, 0); __builtin_amdgcn_s_setprio(0); } while (0)
; #define PG8_WAIT_V(n) asm volatile("s_waitcnt vmcnt(" #n ")" ::: "memory")
; #define PG8_WAIT_L(n) asm volatile("s_waitcnt lgkmcnt(" #n ")" ::: "memory")
; #define PG8_BAR __builtin_amdgcn_s_barrier()
; #define PG8_SCHED __builtin_amdgcn_sched_barrier(0)
; template <class Prob, class Epi, class Sched>
; __device__ __forceinline__ void gemm_phase(PG8_LAS unsigned char* lds, const Prob g, const Sched& S, const Epi& E) {
;     ...
;             PG8_LDB(B0, 0, 0); PG8_LDB(B1, 0, 1); PG8_SCHED; PG8_LDA(At, 0, 0); PG8_STAGE(PG8_SA(1, 1), a1 + hstepA, voffA);
;             PG8_WAIT_V(8); PG8_WAIT_L(0); PG8_BAR; PG8_MMA(0, 0, At, B0); PG8_MMA(0, 1, At, B1); PG8_BAR; PG8_SCHED;
;             PG8_LDA(At, 0, 1); PG8_STAGE(PG8_SB(0, 0), b2, voffB); PG8_STAGE(PG8_SB(0, 1), b2 + hstepB, voffB); PG8_STAGE(PG8_SA(0, 0), a2, voffA);
;             PG8_WAIT_V(8); PG8_WAIT_L(0); PG8_BAR; PG8_MMA(1, 0, At, B0); PG8_MMA(1, 1, At, B1); PG8_BAR; PG8_SCHED;
.LBB0_365:
	s_add_u32 s10, s8, 0xfff80080
	s_addc_u32 s11, s9, -1
	s_add_i32 s21, 0, 0x10000
	s_cmp_eq_u32 s20, 28
	s_cselect_b32 s13, s16, s11
	s_cselect_b32 s12, s17, s10
	v_add_u32_e32 v1, s21, v147
	s_cselect_b32 s11, s57, s19
	s_cselect_b32 s10, s56, s18
	s_add_i32 s24, 0, 0x14000
	ds_read_b128 v[148:151], v1
	ds_read_b128 v[154:157], v1 offset:1024
	ds_read_b128 v[158:161], v1 offset:2048
	ds_read_b128 v[162:165], v1 offset:3072
	v_add_u32_e32 v1, s24, v147
	ds_read_b128 v[166:169], v1
	ds_read_b128 v[170:173], v1 offset:1024
	ds_read_b128 v[174:177], v1 offset:2048
	ds_read_b128 v[178:181], v1 offset:3072
	s_add_i32 m0, s58, 0xc000
	ds_read_b128 v[182:185], v152
	ds_read_b128 v[186:189], v152 offset:1024
	ds_read_b128 v[190:193], v152 offset:2048
	ds_read_b128 v[194:197], v152 offset:3072
	ds_read_b128 v[198:201], v152 offset:4096
	ds_read_b128 v[202:205], v152 offset:5120
	ds_read_b128 v[206:209], v152 offset:6144
	ds_read_b128 v[210:213], v152 offset:7168
	global_load_lds_dwordx4 v142, s[8:9]
	s_add_i32 m0, s58, 0xe000
	s_nop 0
	global_load_lds_dwordx4 v144, s[8:9]
	s_waitcnt vmcnt(8)
	s_waitcnt lgkmcnt(0)
	s_setprio 1
	s_barrier
	v_mfma_f32_16x16x32_bf16 v[126:129], v[148:151], v[182:185], v[126:129]
	v_mfma_f32_16x16x32_bf16 v[122:125], v[158:161], v[182:185], v[122:125]
	v_mfma_f32_16x16x32_bf16 v[118:121], v[148:151], v[190:193], v[118:121]
	v_mfma_f32_16x16x32_bf16 v[114:117], v[158:161], v[190:193], v[114:117]
	v_mfma_f32_16x16x32_bf16 v[110:113], v[148:151], v[198:201], v[110:113]
	v_mfma_f32_16x16x32_bf16 v[106:109], v[158:161], v[198:201], v[106:109]
	v_mfma_f32_16x16x32_bf16 v[102:105], v[148:151], v[206:209], v[102:105]
	v_mfma_f32_16x16x32_bf16 v[98:101], v[158:161], v[206:209], v[98:101]
	v_mfma_f32_16x16x32_bf16 v[126:129], v[154:157], v[186:189], v[126:129]
	v_mfma_f32_16x16x32_bf16 v[122:125], v[162:165], v[186:189], v[122:125]
	v_mfma_f32_16x16x32_bf16 v[118:121], v[154:157], v[194:197], v[118:121]
	v_mfma_f32_16x16x32_bf16 v[114:117], v[162:165], v[194:197], v[114:117]
	v_mfma_f32_16x16x32_bf16 v[110:113], v[154:157], v[202:205], v[110:113]
	v_mfma_f32_16x16x32_bf16 v[106:109], v[162:165], v[202:205], v[106:109]
	v_mfma_f32_16x16x32_bf16 v[102:105], v[154:157], v[210:213], v[102:105]
	v_mfma_f32_16x16x32_bf16 v[98:101], v[162:165], v[210:213], v[98:101]
	v_mfma_f32_16x16x32_bf16 v[62:65], v[166:169], v[182:185], v[62:65]
	v_mfma_f32_16x16x32_bf16 v[58:61], v[174:177], v[182:185], v[58:61]
	v_mfma_f32_16x16x32_bf16 v[54:57], v[166:169], v[190:193], v[54:57]
	v_mfma_f32_16x16x32_bf16 v[50:53], v[174:177], v[190:193], v[50:53]
	v_mfma_f32_16x16x32_bf16 v[46:49], v[166:169], v[198:201], v[46:49]
	v_mfma_f32_16x16x32_bf16 v[42:45], v[174:177], v[198:201], v[42:45]
	v_mfma_f32_16x16x32_bf16 v[38:41], v[166:169], v[206:209], v[38:41]
	v_mfma_f32_16x16x32_bf16 v[34:37], v[174:177], v[206:209], v[34:37]
	v_mfma_f32_16x16x32_bf16 v[62:65], v[170:173], v[186:189], v[62:65]
	v_mfma_f32_16x16x32_bf16 v[58:61], v[178:181], v[186:189], v[58:61]
	v_mfma_f32_16x16x32_bf16 v[54:57], v[170:173], v[194:197], v[54:57]
	v_mfma_f32_16x16x32_bf16 v[50:53], v[178:181], v[194:197], v[50:53]
	v_mfma_f32_16x16x32_bf16 v[46:49], v[170:173], v[202:205], v[46:49]
	v_mfma_f32_16x16x32_bf16 v[42:45], v[178:181], v[202:205], v[42:45]
	v_mfma_f32_16x16x32_bf16 v[38:41], v[170:173], v[210:213], v[38:41]
	v_mfma_f32_16x16x32_bf16 v[34:37], v[178:181], v[210:213], v[34:37]
	s_barrier
	s_setprio 0
	s_add_i32 s21, s21, s43
	s_mov_b32 m0, s21
	ds_read_b128 v[182:185], v152 offset:16384
	ds_read_b128 v[186:189], v152 offset:17408
	ds_read_b128 v[190:193], v152 offset:18432
	ds_read_b128 v[194:197], v152 offset:19456
	ds_read_b128 v[198:201], v152 offset:20480
	ds_read_b128 v[202:205], v152 offset:21504
	ds_read_b128 v[206:209], v152 offset:22528
	ds_read_b128 v[210:213], v152 offset:23552
	global_load_lds_dwordx4 v134, s[10:11]
	s_add_i32 m0, s21, 0x2000
	s_add_u32 s22, s10, 0x1000
	s_addc_u32 s23, s11, 0
	s_add_i32 s21, s24, s43
	global_load_lds_dwordx4 v130, s[10:11]
	s_mov_b32 m0, s21
	v_lshl_add_u64 v[220:221], s[12:13], 0, v[132:133]
	global_load_lds_dwordx4 v134, s[22:23]
	s_add_i32 m0, s21, 0x2000
	s_nop 0
	global_load_lds_dwordx4 v130, s[22:23]
	v_lshl_add_u64 v[218:219], s[12:13], 0, v[136:137]
	s_mov_b32 m0, s58
	s_nop 0
	global_load_lds_dwordx4 v136, s[12:13]
	s_mov_b32 m0, s64
	s_nop 0
	global_load_lds_dwordx4 v132, s[12:13]
	s_waitcnt vmcnt(8)
	s_waitcnt lgkmcnt(0)
	s_setprio 1
	s_barrier
	v_mfma_f32_16x16x32_bf16 v[94:97], v[148:151], v[182:185], v[94:97]
	v_mfma_f32_16x16x32_bf16 v[90:93], v[158:161], v[182:185], v[90:93]
	v_mfma_f32_16x16x32_bf16 v[86:89], v[148:151], v[190:193], v[86:89]
	v_mfma_f32_16x16x32_bf16 v[82:85], v[158:161], v[190:193], v[82:85]
	v_mfma_f32_16x16x32_bf16 v[78:81], v[148:151], v[198:201], v[78:81]
	v_mfma_f32_16x16x32_bf16 v[74:77], v[158:161], v[198:201], v[74:77]
	v_mfma_f32_16x16x32_bf16 v[70:73], v[148:151], v[206:209], v[70:73]
	v_mfma_f32_16x16x32_bf16 v[66:69], v[158:161], v[206:209], v[66:69]
	v_mfma_f32_16x16x32_bf16 v[94:97], v[154:157], v[186:189], v[94:97]
	v_mfma_f32_16x16x32_bf16 v[90:93], v[162:165], v[186:189], v[90:93]
	v_mfma_f32_16x16x32_bf16 v[86:89], v[154:157], v[194:197], v[86:89]
	v_mfma_f32_16x16x32_bf16 v[82:85], v[162:165], v[194:197], v[82:85]
	v_mfma_f32_16x16x32_bf16 v[78:81], v[154:157], v[202:205], v[78:81]
	v_mfma_f32_16x16x32_bf16 v[74:77], v[162:165], v[202:205], v[74:77]
	v_mfma_f32_16x16x32_bf16 v[70:73], v[154:157], v[210:213], v[70:73]
	v_mfma_f32_16x16x32_bf16 v[66:69], v[162:165], v[210:213], v[66:69]
	v_mfma_f32_16x16x32_bf16 v[30:33], v[166:169], v[182:185], v[30:33]
	v_mfma_f32_16x16x32_bf16 v[26:29], v[174:177], v[182:185], v[26:29]
	v_mfma_f32_16x16x32_bf16 v[22:25], v[166:169], v[190:193], v[22:25]
	v_mfma_f32_16x16x32_bf16 v[18:21], v[174:177], v[190:193], v[18:21]
	v_mfma_f32_16x16x32_bf16 v[14:17], v[166:169], v[198:201], v[14:17]
	v_mfma_f32_16x16x32_bf16 v[10:13], v[174:177], v[198:201], v[10:13]
	v_mfma_f32_16x16x32_bf16 v[6:9], v[166:169], v[206:209], v[6:9]
	v_mfma_f32_16x16x32_bf16 v[2:5], v[174:177], v[206:209], v[2:5]
	v_mfma_f32_16x16x32_bf16 v[30:33], v[170:173], v[186:189], v[30:33]
	v_mfma_f32_16x16x32_bf16 v[26:29], v[178:181], v[186:189], v[26:29]
	v_mfma_f32_16x16x32_bf16 v[22:25], v[170:173], v[194:197], v[22:25]
	v_mfma_f32_16x16x32_bf16 v[18:21], v[178:181], v[194:197], v[18:21]
	v_mfma_f32_16x16x32_bf16 v[14:17], v[170:173], v[202:205], v[14:17]
	v_mfma_f32_16x16x32_bf16 v[10:13], v[178:181], v[202:205], v[10:13]
	v_mfma_f32_16x16x32_bf16 v[6:9], v[170:173], v[210:213], v[6:9]
	v_mfma_f32_16x16x32_bf16 v[2:5], v[178:181], v[210:213], v[2:5]
	s_barrier
; #define PG8_STAGE(bufoff, gbase, voff) do { _Pragma("unroll") for (int _i = 0; _i < 2; ++_i) \
;         __builtin_amdgcn_global_load_lds((const unsigned*)((const char*)(gbase) + (voff)[_i]), (PG8_LAS unsigned*)(lds + (bufoff) + ldsw + _i * 8192), 16, 0, 0); } while (0)
; #define PG8_LDA(dst, b, h) do { _Pragma("unroll") for (int m = 0; m < 4; ++m) _Pragma("unroll") for (int k = 0; k < 2; ++k) dst[m][k] = *(const PG8_LAS bf16x8*)(lds + PG8_SA(b, h) + aoff + m * 2048 + k * 1024); } while (0)
; #define PG8_LDB(dst, b, h) do { _Pragma("unroll") for (int n = 0; n < 2; ++n) _Pragma("unroll") for (int k = 0; k < 2; ++k) dst[n][k] = *(const PG8_LAS bf16x8*)(lds + PG8_SB(b, h) + boff + n * 2048 + k * 1024); } while (0)
; #define PG8_MMA(ai, bj, At, Bt) do { __builtin_amdgcn_s_setprio(1); _Pragma("unroll") for (int m = 0; m < 4; ++m) _Pragma("unroll") for (int n = 0; n < 2; ++n) _Pragma("unroll") for (int k = 0; k < 2; ++k) \
;         acc[ai][bj][m][n] = __builtin_amdgcn_mfma_f32_16x16x32_bf16(Bt[n][k], At[m][k], acc[ai][bj][m][n], 0, 0, 0); __builtin_amdgcn_s_setprio(0); } while (0)
; #define PG8_WAIT_V(n) asm volatile("s_waitcnt vmcnt(" #n ")" ::: "memory")
; #define PG8_WAIT_L(n) asm volatile("s_waitcnt lgkmcnt(" #n ")" ::: "memory")
; #define PG8_BAR __builtin_amdgcn_s_barrier()
; #define PG8_SCHED __builtin_amdgcn_sched_barrier(0)
; template <class Prob, class Epi, class Sched>
; __device__ __forceinline__ void gemm_phase(PG8_LAS unsigned char* lds, const Prob g, const Sched& S, const Epi& E) {
;     ...
;             PG8_LDB(B0, 1, 0); PG8_LDB(B1, 1, 1); PG8_SCHED; PG8_LDA(At, 1, 0); PG8_STAGE(PG8_SA(0, 1), a2 + hstepA, voffA);
;             PG8_WAIT_V(8); PG8_WAIT_L(0); PG8_BAR; PG8_MMA(0, 0, At, B0); PG8_MMA(0, 1, At, B1); PG8_BAR; PG8_SCHED;
;             PG8_LDA(At, 1, 1); PG8_STAGE(PG8_SB(1, 0), b3, voffB); PG8_STAGE(PG8_SB(1, 1), b3 + hstepB, voffB); PG8_STAGE(PG8_SA(1, 0), a3, voffA);
;             PG8_WAIT_V(8); PG8_WAIT_L(0); PG8_BAR; PG8_MMA(1, 0, At, B0); PG8_MMA(1, 1, At, B1); PG8_BAR; PG8_SCHED;
;         }
;         if (wr == 0) PG8_BAR;
	s_setprio 0
	s_add_i32 s21, 0, 0x18000
	v_add_u32_e32 v1, s21, v147
	s_add_i32 s22, 0, 0x1c000
	ds_read_b128 v[148:151], v1
	ds_read_b128 v[154:157], v1 offset:1024
	ds_read_b128 v[158:161], v1 offset:2048
	ds_read_b128 v[162:165], v1 offset:3072
	v_add_u32_e32 v1, s22, v147
	ds_read_b128 v[166:169], v1
	ds_read_b128 v[170:173], v1 offset:1024
	ds_read_b128 v[174:177], v1 offset:2048
	ds_read_b128 v[178:181], v1 offset:3072
	s_add_u32 s12, s12, 0x80000
	s_addc_u32 s13, s13, 0
	s_mov_b32 m0, s66
	ds_read_b128 v[182:185], v152 offset:32768
	ds_read_b128 v[186:189], v152 offset:33792
	ds_read_b128 v[190:193], v152 offset:34816
	ds_read_b128 v[194:197], v152 offset:35840
	ds_read_b128 v[198:201], v152 offset:36864
	ds_read_b128 v[202:205], v152 offset:37888
	ds_read_b128 v[206:209], v152 offset:38912
	ds_read_b128 v[210:213], v152 offset:39936
	global_load_lds_dwordx4 v136, s[12:13]
	s_mov_b32 m0, s71
	s_nop 0
	global_load_lds_dwordx4 v132, s[12:13]
	s_waitcnt vmcnt(8)
	s_waitcnt lgkmcnt(0)
	s_setprio 1
	s_barrier
	v_mfma_f32_16x16x32_bf16 v[126:129], v[148:151], v[182:185], v[126:129]
	v_mfma_f32_16x16x32_bf16 v[122:125], v[158:161], v[182:185], v[122:125]
	v_mfma_f32_16x16x32_bf16 v[118:121], v[148:151], v[190:193], v[118:121]
	v_mfma_f32_16x16x32_bf16 v[114:117], v[158:161], v[190:193], v[114:117]
	v_mfma_f32_16x16x32_bf16 v[110:113], v[148:151], v[198:201], v[110:113]
	v_mfma_f32_16x16x32_bf16 v[106:109], v[158:161], v[198:201], v[106:109]
	v_mfma_f32_16x16x32_bf16 v[102:105], v[148:151], v[206:209], v[102:105]
	v_mfma_f32_16x16x32_bf16 v[98:101], v[158:161], v[206:209], v[98:101]
	v_mfma_f32_16x16x32_bf16 v[126:129], v[154:157], v[186:189], v[126:129]
	v_mfma_f32_16x16x32_bf16 v[122:125], v[162:165], v[186:189], v[122:125]
	v_mfma_f32_16x16x32_bf16 v[118:121], v[154:157], v[194:197], v[118:121]
	v_mfma_f32_16x16x32_bf16 v[114:117], v[162:165], v[194:197], v[114:117]
	v_mfma_f32_16x16x32_bf16 v[110:113], v[154:157], v[202:205], v[110:113]
	v_mfma_f32_16x16x32_bf16 v[106:109], v[162:165], v[202:205], v[106:109]
	v_mfma_f32_16x16x32_bf16 v[102:105], v[154:157], v[210:213], v[102:105]
	v_mfma_f32_16x16x32_bf16 v[98:101], v[162:165], v[210:213], v[98:101]
	v_mfma_f32_16x16x32_bf16 v[62:65], v[166:169], v[182:185], v[62:65]
	v_mfma_f32_16x16x32_bf16 v[58:61], v[174:177], v[182:185], v[58:61]
	v_mfma_f32_16x16x32_bf16 v[54:57], v[166:169], v[190:193], v[54:57]
	v_mfma_f32_16x16x32_bf16 v[50:53], v[174:177], v[190:193], v[50:53]
	v_mfma_f32_16x16x32_bf16 v[46:49], v[166:169], v[198:201], v[46:49]
	v_mfma_f32_16x16x32_bf16 v[42:45], v[174:177], v[198:201], v[42:45]
	v_mfma_f32_16x16x32_bf16 v[38:41], v[166:169], v[206:209], v[38:41]
	v_mfma_f32_16x16x32_bf16 v[34:37], v[174:177], v[206:209], v[34:37]
	v_mfma_f32_16x16x32_bf16 v[62:65], v[170:173], v[186:189], v[62:65]
	v_mfma_f32_16x16x32_bf16 v[58:61], v[178:181], v[186:189], v[58:61]
	v_mfma_f32_16x16x32_bf16 v[54:57], v[170:173], v[194:197], v[54:57]
	v_mfma_f32_16x16x32_bf16 v[50:53], v[178:181], v[194:197], v[50:53]
	v_mfma_f32_16x16x32_bf16 v[46:49], v[170:173], v[202:205], v[46:49]
	v_mfma_f32_16x16x32_bf16 v[42:45], v[178:181], v[202:205], v[42:45]
	v_mfma_f32_16x16x32_bf16 v[38:41], v[170:173], v[210:213], v[38:41]
	v_mfma_f32_16x16x32_bf16 v[34:37], v[178:181], v[210:213], v[34:37]
	s_barrier
	s_setprio 0
	s_add_i32 s12, s21, s43
	s_mov_b32 m0, s12
	ds_read_b128 v[182:185], v152 offset:49152
	ds_read_b128 v[186:189], v152 offset:50176
	ds_read_b128 v[190:193], v152 offset:51200
	ds_read_b128 v[194:197], v152 offset:52224
	ds_read_b128 v[198:201], v152 offset:53248
	ds_read_b128 v[202:205], v152 offset:54272
	ds_read_b128 v[206:209], v152 offset:55296
	ds_read_b128 v[210:213], v152 offset:56320
	s_add_u32 s100, s10, 0x80
	s_addc_u32 s101, s11, 0
	global_load_lds_dwordx4 v134, s[100:101]
	s_add_i32 m0, s12, 0x2000
	s_add_u32 s10, s10, 0x1080
	s_addc_u32 s11, s11, 0
	s_add_i32 s12, s22, s43
	global_load_lds_dwordx4 v130, s[100:101]
	s_mov_b32 m0, s12
	s_nop 0
	global_load_lds_dwordx4 v134, s[10:11]
	s_add_i32 m0, s12, 0x2000
	s_nop 0
	global_load_lds_dwordx4 v130, s[10:11]
	v_lshl_add_u64 v[214:215], v[218:219], 0, s[88:89]
	s_mov_b32 m0, s87
	s_nop 0
	global_load_lds_dwordx4 v[214:215], off
	v_lshl_add_u64 v[214:215], v[220:221], 0, s[88:89]
	s_mov_b32 m0, s52
	s_nop 0
	global_load_lds_dwordx4 v[214:215], off
	s_waitcnt vmcnt(8)
	s_waitcnt lgkmcnt(0)
	s_setprio 1
	s_barrier
	v_mfma_f32_16x16x32_bf16 v[94:97], v[148:151], v[182:185], v[94:97]
	v_mfma_f32_16x16x32_bf16 v[90:93], v[158:161], v[182:185], v[90:93]
	v_mfma_f32_16x16x32_bf16 v[86:89], v[148:151], v[190:193], v[86:89]
	v_mfma_f32_16x16x32_bf16 v[82:85], v[158:161], v[190:193], v[82:85]
	v_mfma_f32_16x16x32_bf16 v[78:81], v[148:151], v[198:201], v[78:81]
	v_mfma_f32_16x16x32_bf16 v[74:77], v[158:161], v[198:201], v[74:77]
	v_mfma_f32_16x16x32_bf16 v[70:73], v[148:151], v[206:209], v[70:73]
	v_mfma_f32_16x16x32_bf16 v[66:69], v[158:161], v[206:209], v[66:69]
	v_mfma_f32_16x16x32_bf16 v[94:97], v[154:157], v[186:189], v[94:97]
	v_mfma_f32_16x16x32_bf16 v[90:93], v[162:165], v[186:189], v[90:93]
	v_mfma_f32_16x16x32_bf16 v[86:89], v[154:157], v[194:197], v[86:89]
	v_mfma_f32_16x16x32_bf16 v[82:85], v[162:165], v[194:197], v[82:85]
	v_mfma_f32_16x16x32_bf16 v[78:81], v[154:157], v[202:205], v[78:81]
	v_mfma_f32_16x16x32_bf16 v[74:77], v[162:165], v[202:205], v[74:77]
	v_mfma_f32_16x16x32_bf16 v[70:73], v[154:157], v[210:213], v[70:73]
	v_mfma_f32_16x16x32_bf16 v[66:69], v[162:165], v[210:213], v[66:69]
	v_mfma_f32_16x16x32_bf16 v[30:33], v[166:169], v[182:185], v[30:33]
	v_mfma_f32_16x16x32_bf16 v[26:29], v[174:177], v[182:185], v[26:29]
	v_mfma_f32_16x16x32_bf16 v[22:25], v[166:169], v[190:193], v[22:25]
	v_mfma_f32_16x16x32_bf16 v[18:21], v[174:177], v[190:193], v[18:21]
	v_mfma_f32_16x16x32_bf16 v[14:17], v[166:169], v[198:201], v[14:17]
	v_mfma_f32_16x16x32_bf16 v[10:13], v[174:177], v[198:201], v[10:13]
	v_mfma_f32_16x16x32_bf16 v[6:9], v[166:169], v[206:209], v[6:9]
	v_mfma_f32_16x16x32_bf16 v[2:5], v[174:177], v[206:209], v[2:5]
	v_mfma_f32_16x16x32_bf16 v[30:33], v[170:173], v[186:189], v[30:33]
	v_mfma_f32_16x16x32_bf16 v[26:29], v[178:181], v[186:189], v[26:29]
	v_mfma_f32_16x16x32_bf16 v[22:25], v[170:173], v[194:197], v[22:25]
	v_mfma_f32_16x16x32_bf16 v[18:21], v[178:181], v[194:197], v[18:21]
	v_mfma_f32_16x16x32_bf16 v[14:17], v[170:173], v[202:205], v[14:17]
	v_mfma_f32_16x16x32_bf16 v[10:13], v[178:181], v[202:205], v[10:13]
	v_mfma_f32_16x16x32_bf16 v[6:9], v[170:173], v[210:213], v[6:9]
	v_mfma_f32_16x16x32_bf16 v[2:5], v[178:181], v[210:213], v[2:5]
	s_barrier
	s_setprio 0
	s_add_i32 s20, s20, 2
	s_add_u32 s8, s8, 0x100
	s_addc_u32 s9, s9, 0
	s_add_u32 s18, s18, 0x100
	s_addc_u32 s19, s19, 0
	s_cmp_gt_u32 s20, 29
	s_cbranch_scc0 .LBB0_365
	s_and_b64 vcc, exec, s[34:35]
	s_cbranch_vccz .LBB0_368
	s_barrier

; #define SBAR() __builtin_amdgcn_sched_barrier(0)
; #define KF(a, o) (*(const __attribute__((address_space(3))) bf16x8*)((a) + (o)))
; template <class Hook> __device__ __forceinline__ void qk_sub(f32x16& p, ldsc_t k0, ldsc_t k1, ldsc_t k2, ldsc_t k3, int kd, const bf16x8* qr, const Hook& hook) {
;     ...
;   SBAR();
;   bf16x8 f0 = KF(k0, 0), f1 = KF(k1, 0), f2 = KF(k2, 0), f3 = KF(k3, 0); SBAR(); __builtin_amdgcn_s_setprio(1);
;   p = __builtin_amdgcn_mfma_f32_32x32x16_bf16(f0, qr[0], f32x16{}, 0, 0, 0); f0 = KF(k0 + kd, 0); SBAR();
;   p = __builtin_amdgcn_mfma_f32_32x32x16_bf16(f1, qr[1], p, 0, 0, 0); f1 = KF(k1 + kd, 0); hook(0); SBAR();
;   p = __builtin_amdgcn_mfma_f32_32x32x16_bf16(f2, qr[2], p, 0, 0, 0); f2 = KF(k2 + kd, 0); SBAR();
;   p = __builtin_amdgcn_mfma_f32_32x32x16_bf16(f3, qr[3], p, 0, 0, 0); f3 = KF(k3 + kd, 0); hook(1); SBAR();
;   p = __builtin_amdgcn_mfma_f32_32x32x16_bf16(f0, qr[4], p, 0, 0, 0); SBAR();
;   p = __builtin_amdgcn_mfma_f32_32x32x16_bf16(f1, qr[5], p, 0, 0, 0); hook(2); SBAR();
;   p = __builtin_amdgcn_mfma_f32_32x32x16_bf16(f2, qr[6], p, 0, 0, 0); SBAR();
;   p = __builtin_amdgcn_mfma_f32_32x32x16_bf16(f3, qr[7], p, 0, 0, 0); hook(3); __builtin_amdgcn_s_setprio(0); SBAR();
; __device__ __forceinline__ void softmax_sub(f32x16& p, float& m_reg, float& l_reg, bf16x8& pa0, bf16x8& pa1, f32x16 (&o)[8], float* al_l, int r32, int hi, int dj, const float* tab, float cL, float cR) {
;   constexpr float C = SCALE * 1.4426950408889634f;
;   float cb;
;   if (dj <= -159) cb = cL;
;   else if (dj >= 159) cb = cR;
;   else { cb = 0.f; const int ib = dj - r32 + 4 * hi + 128;
; #pragma unroll
;     for (int r = 0; r < 16; ++r) { const int i0 = ib + (r & 3) + 8 * (r >> 2); p[r] += tab[min(max(i0, 0), 256)]; } }
.LBB0_548:
	s_waitcnt vmcnt(0)
	s_add_i32 s4, s27, 0xffff0000
	s_barrier
	s_and_b32 s29, s4, 0x10000
	v_add_u32_e32 v1, s29, v252
	v_add_u32_e32 v198, s29, v253
	v_add_u32_e32 v199, s29, v241
	v_add_u32_e32 v202, s29, v244
	ds_read_b128 v[130:133], v1
	ds_read_b128 v[134:137], v198
	ds_read_b128 v[138:141], v199
	ds_read_b128 v[142:145], v202
	s_setprio 1
	s_waitcnt lgkmcnt(0)
	v_mfma_f32_32x32x16_bf16 v[146:161], v[130:133], v[190:193], 0
	v_add_u32_e32 v206, v1, v251
	ds_read_b128 v[130:133], v206
	s_and_b32 s24, s27, 0x10000
	s_add_i32 s28, s23, s24
	v_add_u32_e32 v210, v198, v251
	v_mfma_f32_32x32x16_bf16 v[146:161], v[134:137], v[186:189], v[146:161]
	ds_read_b128 v[134:137], v210
	s_mov_b32 m0, s28
	s_add_u32 s4, s8, 0xc0000
	s_addc_u32 s5, s9, 0
	s_add_u32 s100, s8, 0x120000
	s_addc_u32 s101, s9, 0
	global_load_lds_dwordx4 v226, s[4:5]
	v_mfma_f32_32x32x16_bf16 v[146:161], v[138:141], v[182:185], v[146:161]
	v_add_u32_e32 v212, v199, v251
	ds_read_b128 v[138:141], v212
	v_add_u32_e32 v213, v202, v251
	v_mfma_f32_32x32x16_bf16 v[146:161], v[142:145], v[178:181], v[146:161]
	s_add_i32 m0, s28, 0x2000
	ds_read_b128 v[142:145], v213
	global_load_lds_dwordx4 v226, s[100:101]
	s_waitcnt lgkmcnt(0)
	s_add_i32 m0, s28, 0x3f00
	v_mfma_f32_32x32x16_bf16 v[146:161], v[130:133], v[174:177], v[146:161]
	global_load_lds_dwordx4 v226, s[4:5] offset:256
	v_mfma_f32_32x32x16_bf16 v[146:161], v[134:137], v[170:173], v[146:161]
	s_add_i32 m0, s28, 0x5f00
	v_mfma_f32_32x32x16_bf16 v[146:161], v[138:141], v[166:169], v[146:161]
	global_load_lds_dwordx4 v226, s[100:101] offset:256
	v_mfma_f32_32x32x16_bf16 v[146:161], v[142:145], v[162:165], v[146:161]
	s_setprio 0
	ds_read_b128 v[130:133], v1 offset:8192
	ds_read_b128 v[194:197], v198 offset:8192
	ds_read_b128 v[198:201], v199 offset:8192
	ds_read_b128 v[202:205], v202 offset:8192
	s_setprio 1
	s_waitcnt lgkmcnt(0)
	v_mfma_f32_32x32x16_bf16 v[130:145], v[130:133], v[190:193], 0
	ds_read_b128 v[206:209], v206 offset:8192
	v_mfma_f32_32x32x16_bf16 v[130:145], v[194:197], v[186:189], v[130:145]
	ds_read_b128 v[194:197], v210 offset:8192
	v_mfma_f32_32x32x16_bf16 v[130:145], v[198:201], v[182:185], v[130:145]
	ds_read_b128 v[198:201], v212 offset:8192
	v_mfma_f32_32x32x16_bf16 v[130:145], v[202:205], v[178:181], v[130:145]
	ds_read_b128 v[202:205], v213 offset:8192
	s_waitcnt lgkmcnt(0)
	v_mfma_f32_32x32x16_bf16 v[130:145], v[206:209], v[174:177], v[130:145]
	v_mfma_f32_32x32x16_bf16 v[130:145], v[194:197], v[170:173], v[130:145]
	v_mfma_f32_32x32x16_bf16 v[130:145], v[198:201], v[166:169], v[130:145]
	v_mfma_f32_32x32x16_bf16 v[130:145], v[202:205], v[162:165], v[130:145]
	s_setprio 0
	v_add_u32_e32 v1, s29, v250
	ds_read_b64_tr_b16 v[206:207], v1 offset:32768
	ds_read_b64_tr_b16 v[208:209], v1 offset:36864
	ds_read_b64_tr_b16 v[200:201], v1 offset:37376
	ds_read_b64_tr_b16 v[198:199], v1 offset:33280
	ds_read_b64_tr_b16 v[202:203], v1 offset:40960
	ds_read_b64_tr_b16 v[204:205], v1 offset:45056
	ds_read_b64_tr_b16 v[196:197], v1 offset:45568
	ds_read_b64_tr_b16 v[194:195], v1 offset:41472
	s_cmpk_lt_i32 s26, 0xff62
	s_cselect_b32 s29, s19, s22
	s_add_i32 s4, s26, 0x9e
	s_cmp_lt_u32 s4, 0x13d
	s_cbranch_scc1 .Lattn_near0

; #define SBAR() __builtin_amdgcn_sched_barrier(0)
; template <int D0, int S> __device__ __forceinline__ VG vload(ldsc_t vb) { VG g; g.l0 = vtr(vb + v_rd_off(D0, 2 * S, 0)); g.h0 = vtr(vb + v_rd_off(D0, 2 * S, 1)); g.l1 = vtr(vb + v_rd_off(D0, 2 * S + 1, 0)); g.h1 = vtr(vb + v_rd_off(D0, 2 * S + 1, 1)); return g; }
; __device__ __forceinline__ void softmax_sub(f32x16& p, float& m_reg, float& l_reg, bf16x8& pa0, bf16x8& pa1, f32x16 (&o)[8], float* al_l, int r32, int hi, int dj, const float* tab, float cL, float cR) {
;     ...
;   const float mnC = (cb - mn) * C;
;   float ps = 0;
; #pragma unroll
;   for (int r = 0; r < 16; ++r) { p[r] = __builtin_amdgcn_exp2f(fmaf(p[r], C, mnC)); ps += p[r]; }
;   { auto rr = __builtin_amdgcn_permlane32_swap(__float_as_uint(ps), __float_as_uint(ps), false, false);
;     ps = __uint_as_float(rr[0]) + __uint_as_float(rr[1]); }
;   l_reg = l_reg * alpha + ps;
;     ...
;   PK4(p, 0, pa0); PK4(p, 8, pa1);
; template <int S, class Dma> __device__ __forceinline__ void pv_run(f32x16 (&o)[8], ldsc_t vb, VG g0, VG g1, bf16x8 pa0, bf16x8 pa1, const Dma& dma) {
;   SBAR(); __builtin_amdgcn_s_setprio(1);
;   vmma(o[0], g0, pa0, pa1); dma(0); SBAR(); g0 = vload<2, S>(vb); SBAR();
;   vmma(o[1], g1, pa0, pa1); dma(1); SBAR(); g1 = vload<3, S>(vb); SBAR();
;   vmma(o[2], g0, pa0, pa1); dma(2); SBAR(); g0 = vload<4, S>(vb); SBAR();
;   vmma(o[3], g1, pa0, pa1); dma(3); SBAR(); g1 = vload<5, S>(vb); SBAR();
;   vmma(o[4], g0, pa0, pa1); dma(4); SBAR(); g0 = vload<6, S>(vb); SBAR();
;   vmma(o[5], g1, pa0, pa1); dma(5); SBAR(); g1 = vload<7, S>(vb); SBAR();
;   vmma(o[6], g0, pa0, pa1); dma(6); SBAR(); vmma(o[7], g1, pa0, pa1); dma(7); __builtin_amdgcn_s_setprio(0); SBAR();
.LBB0_555:
	v_sub_f32_e32 v211, s29, v210
	v_mul_f32_e32 v211, 0x3e0293ee, v211
	v_fmamk_f32 v146, v146, 0x3e0293ee, v211
	v_exp_f32_e32 v146, v146
	v_fmamk_f32 v147, v147, 0x3e0293ee, v211
	v_exp_f32_e32 v147, v147
	v_fmamk_f32 v148, v148, 0x3e0293ee, v211
	v_exp_f32_e32 v148, v148
	v_fmamk_f32 v149, v149, 0x3e0293ee, v211
	v_exp_f32_e32 v149, v149
	v_fmamk_f32 v150, v150, 0x3e0293ee, v211
	v_exp_f32_e32 v150, v150
	v_fmamk_f32 v151, v151, 0x3e0293ee, v211
	v_add_f32_e32 v212, v147, v146
	v_exp_f32_e32 v151, v151
	v_fmamk_f32 v152, v152, 0x3e0293ee, v211
	v_add_f32_e32 v212, v148, v212
	v_exp_f32_e32 v152, v152
	v_fmamk_f32 v153, v153, 0x3e0293ee, v211
	v_add_f32_e32 v212, v149, v212
	v_exp_f32_e32 v153, v153
	v_fmamk_f32 v154, v154, 0x3e0293ee, v211
	v_add_f32_e32 v212, v150, v212
	v_exp_f32_e32 v154, v154
	v_fmamk_f32 v155, v155, 0x3e0293ee, v211
	v_add_f32_e32 v212, v151, v212
	v_exp_f32_e32 v155, v155
	v_fmamk_f32 v156, v156, 0x3e0293ee, v211
	v_add_f32_e32 v212, v152, v212
	v_exp_f32_e32 v156, v156
	v_fmamk_f32 v157, v157, 0x3e0293ee, v211
	v_add_f32_e32 v212, v153, v212
	v_exp_f32_e32 v157, v157
	v_fmamk_f32 v158, v158, 0x3e0293ee, v211
	v_add_f32_e32 v212, v154, v212
	v_exp_f32_e32 v158, v158
	v_fmamk_f32 v159, v159, 0x3e0293ee, v211
	v_add_f32_e32 v212, v155, v212
	v_exp_f32_e32 v159, v159
	v_fmamk_f32 v160, v160, 0x3e0293ee, v211
	v_add_f32_e32 v212, v156, v212
	v_exp_f32_e32 v160, v160
	v_fmac_f32_e32 v211, 0x3e0293ee, v161
	v_add_f32_e32 v212, v157, v212
	v_exp_f32_e32 v161, v211
	v_add_f32_e32 v211, v158, v212
	v_add_f32_e32 v211, v159, v211
	v_add_f32_e32 v211, v160, v211
	v_add_f32_e32 v212, v161, v211
	v_mov_b32_e32 v213, v212
	v_cvt_pk_bf16_f32 v146, v146, v147
	v_cvt_pk_bf16_f32 v147, v148, v149
	v_cvt_pk_bf16_f32 v148, v150, v151
	v_cvt_pk_bf16_f32 v149, v152, v153
	v_cvt_pk_bf16_f32 v150, v154, v155
	v_cvt_pk_bf16_f32 v151, v156, v157
	v_cvt_pk_bf16_f32 v152, v158, v159
	v_cvt_pk_bf16_f32 v153, v160, v161
	s_nop 1
	v_permlane32_swap_b32_e32 v212, v213
	v_permlane32_swap_b32_e32 v146, v148
	v_permlane32_swap_b32_e32 v147, v149
	v_permlane32_swap_b32_e32 v150, v152
	v_permlane32_swap_b32_e32 v151, v153
	s_setprio 1
	s_waitcnt lgkmcnt(0)
	v_mfma_f32_32x32x16_bf16 v[98:113], v[146:149], v[206:209], v[98:113]
	s_add_i32 m0, s28, 0x8000
	s_add_u32 s4, s8, 0xc0000
	s_addc_u32 s5, s9, 0
	global_load_lds_dwordx4 v238, s[4:5]
	v_mfma_f32_32x32x16_bf16 v[98:113], v[150:153], v[202:205], v[98:113]
	ds_read_b64_tr_b16 v[154:155], v1 offset:33792
	ds_read_b64_tr_b16 v[156:157], v1 offset:37888
	ds_read_b64_tr_b16 v[158:159], v1 offset:41984
	ds_read_b64_tr_b16 v[160:161], v1 offset:46080
	s_add_i32 m0, s28, 0xa000
	v_mfma_f32_32x32x16_bf16 v[114:129], v[146:149], v[198:201], v[114:129]
	global_load_lds_dwordx4 v239, s[4:5]
	v_mfma_f32_32x32x16_bf16 v[114:129], v[150:153], v[194:197], v[114:129]
	ds_read_b64_tr_b16 v[194:195], v1 offset:34304
	ds_read_b64_tr_b16 v[196:197], v1 offset:38400
	ds_read_b64_tr_b16 v[198:199], v1 offset:42496
	ds_read_b64_tr_b16 v[200:201], v1 offset:46592
	s_waitcnt lgkmcnt(0)
	s_add_i32 m0, s28, 0xc000
	v_mfma_f32_32x32x16_bf16 v[66:81], v[146:149], v[154:157], v[66:81]
	global_load_lds_dwordx4 v238, s[100:101]
	v_mfma_f32_32x32x16_bf16 v[66:81], v[150:153], v[158:161], v[66:81]
	ds_read_b64_tr_b16 v[154:155], v1 offset:34816
	ds_read_b64_tr_b16 v[156:157], v1 offset:38912
	ds_read_b64_tr_b16 v[158:159], v1 offset:43008
	ds_read_b64_tr_b16 v[160:161], v1 offset:47104
	s_add_i32 m0, s28, 0xe000
	v_mfma_f32_32x32x16_bf16 v[82:97], v[146:149], v[194:197], v[82:97]
	global_load_lds_dwordx4 v239, s[100:101]
	v_mfma_f32_32x32x16_bf16 v[82:97], v[150:153], v[198:201], v[82:97]
	ds_read_b64_tr_b16 v[194:195], v1 offset:35328
	ds_read_b64_tr_b16 v[196:197], v1 offset:39424
	ds_read_b64_tr_b16 v[198:199], v1 offset:43520
	ds_read_b64_tr_b16 v[200:201], v1 offset:47616
	s_waitcnt lgkmcnt(0)
	v_mfma_f32_32x32x16_bf16 v[34:49], v[146:149], v[154:157], v[34:49]
	v_mfma_f32_32x32x16_bf16 v[34:49], v[150:153], v[158:161], v[34:49]
	ds_read_b64_tr_b16 v[154:155], v1 offset:35840
	ds_read_b64_tr_b16 v[156:157], v1 offset:39936
	ds_read_b64_tr_b16 v[158:159], v1 offset:44032
	ds_read_b64_tr_b16 v[160:161], v1 offset:48128
	v_mfma_f32_32x32x16_bf16 v[50:65], v[146:149], v[194:197], v[50:65]
	v_mfma_f32_32x32x16_bf16 v[50:65], v[150:153], v[198:201], v[50:65]
	ds_read_b64_tr_b16 v[194:195], v1 offset:36352
	ds_read_b64_tr_b16 v[196:197], v1 offset:40448
	ds_read_b64_tr_b16 v[198:199], v1 offset:44544
	ds_read_b64_tr_b16 v[200:201], v1 offset:48640
	s_waitcnt lgkmcnt(0)
	v_mfma_f32_32x32x16_bf16 v[18:33], v[146:149], v[154:157], v[18:33]
	v_mfma_f32_32x32x16_bf16 v[18:33], v[150:153], v[158:161], v[18:33]
	v_mfma_f32_32x32x16_bf16 v[2:17], v[146:149], v[194:197], v[2:17]
	v_mfma_f32_32x32x16_bf16 v[2:17], v[150:153], v[198:201], v[2:17]
	s_setprio 0
	ds_read_b64_tr_b16 v[154:155], v1 offset:49152
	ds_read_b64_tr_b16 v[156:157], v1 offset:53248
	ds_read_b64_tr_b16 v[152:153], v1 offset:53760
	ds_read_b64_tr_b16 v[150:151], v1 offset:49664
	ds_read_b64_tr_b16 v[158:159], v1 offset:57344
	ds_read_b64_tr_b16 v[160:161], v1 offset:61440
	ds_read_b64_tr_b16 v[148:149], v1 offset:61952
	ds_read_b64_tr_b16 v[146:147], v1 offset:57856
	s_add_i32 s4, s26, 32
	s_cmpk_lt_i32 s4, 0xff62
	s_cselect_b32 s28, s19, s22
	s_add_i32 s5, s4, 0x9e
	s_cmp_lt_u32 s5, 0x13d
	s_cbranch_scc1 .Lattn_near1

; #define PG8_STAGE(bufoff, gbase, voff) do { _Pragma("unroll") for (int _i = 0; _i < 2; ++_i) \
;         __builtin_amdgcn_global_load_lds((const unsigned*)((const char*)(gbase) + (voff)[_i]), (PG8_LAS unsigned*)(lds + (bufoff) + ldsw + _i * 8192), 16, 0, 0); } while (0)
; #define PG8_LDA(dst, b, h) do { _Pragma("unroll") for (int m = 0; m < 4; ++m) _Pragma("unroll") for (int k = 0; k < 2; ++k) dst[m][k] = *(const PG8_LAS bf16x8*)(lds + PG8_SA(b, h) + aoff + m * 2048 + k * 1024); } while (0)
; #define PG8_LDB(dst, b, h) do { _Pragma("unroll") for (int n = 0; n < 2; ++n) _Pragma("unroll") for (int k = 0; k < 2; ++k) dst[n][k] = *(const PG8_LAS bf16x8*)(lds + PG8_SB(b, h) + boff + n * 2048 + k * 1024); } while (0)
; #define PG8_MMA(ai, bj, At, Bt) do { __builtin_amdgcn_s_setprio(1); _Pragma("unroll") for (int m = 0; m < 4; ++m) _Pragma("unroll") for (int n = 0; n < 2; ++n) _Pragma("unroll") for (int k = 0; k < 2; ++k) \
;         acc[ai][bj][m][n] = __builtin_amdgcn_mfma_f32_16x16x32_bf16(Bt[n][k], At[m][k], acc[ai][bj][m][n], 0, 0, 0); __builtin_amdgcn_s_setprio(0); } while (0)
; #define PG8_WAIT_V(n) asm volatile("s_waitcnt vmcnt(" #n ")" ::: "memory")
; #define PG8_WAIT_L(n) asm volatile("s_waitcnt lgkmcnt(" #n ")" ::: "memory")
; #define PG8_BAR __builtin_amdgcn_s_barrier()
; #define PG8_SCHED __builtin_amdgcn_sched_barrier(0)
; template <class Prob, class Epi, class Sched>
; __device__ __forceinline__ void gemm_phase(PG8_LAS unsigned char* lds, const Prob g, const Sched& S, const Epi& E) {
;     ...
;             PG8_LDB(B0, 0, 0); PG8_LDB(B1, 0, 1); PG8_SCHED; PG8_LDA(At, 0, 0); PG8_STAGE(PG8_SA(1, 1), a1 + hstepA, voffA);
;             PG8_WAIT_V(8); PG8_WAIT_L(0); PG8_BAR; PG8_MMA(0, 0, At, B0); PG8_MMA(0, 1, At, B1); PG8_BAR; PG8_SCHED;
;             PG8_LDA(At, 0, 1); PG8_STAGE(PG8_SB(0, 0), b2, voffB); PG8_STAGE(PG8_SB(0, 1), b2 + hstepB, voffB); PG8_STAGE(PG8_SA(0, 0), a2, voffA);
;             PG8_WAIT_V(8); PG8_WAIT_L(0); PG8_BAR; PG8_MMA(1, 0, At, B0); PG8_MMA(1, 1, At, B1); PG8_BAR; PG8_SCHED;
.LBB0_608:
	s_add_u32 s37, s28, s36
	s_addc_u32 s39, s29, 0
	s_add_u32 s38, s37, 0x100
	s_addc_u32 s40, s39, 0
	s_and_b64 s[4:5], s[34:35], exec
	s_cselect_b32 s57, s21, s40
	s_cselect_b32 s56, s70, s38
	s_add_u32 s4, s22, s36
	s_addc_u32 s5, s23, 0
	s_add_u32 s36, s4, 0x100
	s_addc_u32 s38, s5, 0
	s_add_i32 s49, 0, 0x10000
	s_and_b64 s[4:5], s[34:35], exec
	s_cselect_b32 s69, s19, s38
	s_cselect_b32 s68, s44, s36
	s_add_i32 s4, 0, 0x14000
	s_add_u32 s38, s37, 0x10080
	s_addc_u32 s39, s39, 0
	s_add_i32 s40, s49, s52
	s_add_i32 m0, s53, 0xc000
	s_add_i32 s5, s53, 0xe000
	s_add_i32 s48, s40, 0x2000
	s_add_u32 vcc_lo, s68, 0x10000
	v_add_u32_e32 v160, s49, v1
	v_add_u32_e32 v176, s4, v1
	s_addc_u32 vcc_hi, s69, 0
	s_add_i32 s41, s4, s52
	ds_read_b128 v[148:151], v160
	ds_read_b128 v[152:155], v160 offset:1024
	ds_read_b128 v[156:159], v160 offset:2048
	ds_read_b128 v[160:163], v160 offset:3072
	ds_read_b128 v[164:167], v176
	ds_read_b128 v[168:171], v176 offset:1024
	ds_read_b128 v[172:175], v176 offset:2048
	ds_read_b128 v[176:179], v176 offset:3072
	s_add_i32 s75, s41, 0x2000
	s_add_i32 s45, 0, 0x18000
	s_add_i32 s82, 0, 0x1c000
	s_add_u32 s36, s56, 0x10000
	s_addc_u32 s37, s57, 0
	s_add_i32 s59, s45, s52
	s_add_i32 s83, s59, 0x2000
	s_add_u32 s34, s68, 0x10080
	s_addc_u32 s35, s69, 0
	s_add_i32 s49, s82, s52
	s_add_i32 s4, s49, 0x2000
	v_lshl_add_u64 v[212:213], s[38:39], 0, v[136:137]
	ds_read_b128 v[180:183], v147
	ds_read_b128 v[184:187], v147 offset:1024
	ds_read_b128 v[188:191], v147 offset:2048
	ds_read_b128 v[192:195], v147 offset:3072
	ds_read_b128 v[196:199], v147 offset:4096
	ds_read_b128 v[200:203], v147 offset:5120
	ds_read_b128 v[204:207], v147 offset:6144
	ds_read_b128 v[208:211], v147 offset:7168
	global_load_lds_dwordx4 v[212:213], off
	v_lshl_add_u64 v[212:213], s[38:39], 0, v[132:133]
	s_mov_b32 m0, s5
	s_nop 0
	global_load_lds_dwordx4 v[212:213], off
	s_waitcnt vmcnt(8)
	s_waitcnt lgkmcnt(0)
	s_setprio 1
	s_barrier
	v_mfma_f32_16x16x32_bf16 v[126:129], v[148:151], v[180:183], v[126:129]
	v_mfma_f32_16x16x32_bf16 v[122:125], v[156:159], v[180:183], v[122:125]
	v_mfma_f32_16x16x32_bf16 v[118:121], v[148:151], v[188:191], v[118:121]
	v_mfma_f32_16x16x32_bf16 v[114:117], v[156:159], v[188:191], v[114:117]
	v_mfma_f32_16x16x32_bf16 v[110:113], v[148:151], v[196:199], v[110:113]
	v_mfma_f32_16x16x32_bf16 v[106:109], v[156:159], v[196:199], v[106:109]
	v_mfma_f32_16x16x32_bf16 v[102:105], v[148:151], v[204:207], v[102:105]
	v_mfma_f32_16x16x32_bf16 v[98:101], v[156:159], v[204:207], v[98:101]
	v_mfma_f32_16x16x32_bf16 v[126:129], v[152:155], v[184:187], v[126:129]
	v_mfma_f32_16x16x32_bf16 v[122:125], v[160:163], v[184:187], v[122:125]
	v_mfma_f32_16x16x32_bf16 v[118:121], v[152:155], v[192:195], v[118:121]
	v_mfma_f32_16x16x32_bf16 v[114:117], v[160:163], v[192:195], v[114:117]
	v_mfma_f32_16x16x32_bf16 v[110:113], v[152:155], v[200:203], v[110:113]
	v_mfma_f32_16x16x32_bf16 v[106:109], v[160:163], v[200:203], v[106:109]
	v_mfma_f32_16x16x32_bf16 v[102:105], v[152:155], v[208:211], v[102:105]
	v_mfma_f32_16x16x32_bf16 v[98:101], v[160:163], v[208:211], v[98:101]
	v_mfma_f32_16x16x32_bf16 v[82:85], v[164:167], v[180:183], v[82:85]
	v_mfma_f32_16x16x32_bf16 v[74:77], v[172:175], v[180:183], v[74:77]
	v_mfma_f32_16x16x32_bf16 v[66:69], v[164:167], v[188:191], v[66:69]
	v_mfma_f32_16x16x32_bf16 v[58:61], v[172:175], v[188:191], v[58:61]
	v_mfma_f32_16x16x32_bf16 v[50:53], v[164:167], v[196:199], v[50:53]
	v_mfma_f32_16x16x32_bf16 v[42:45], v[172:175], v[196:199], v[42:45]
	v_mfma_f32_16x16x32_bf16 v[38:41], v[164:167], v[204:207], v[38:41]
	v_mfma_f32_16x16x32_bf16 v[34:37], v[172:175], v[204:207], v[34:37]
	v_mfma_f32_16x16x32_bf16 v[82:85], v[168:171], v[184:187], v[82:85]
	v_mfma_f32_16x16x32_bf16 v[74:77], v[176:179], v[184:187], v[74:77]
	v_mfma_f32_16x16x32_bf16 v[66:69], v[168:171], v[192:195], v[66:69]
	v_mfma_f32_16x16x32_bf16 v[58:61], v[176:179], v[192:195], v[58:61]
	v_mfma_f32_16x16x32_bf16 v[50:53], v[168:171], v[200:203], v[50:53]
	v_mfma_f32_16x16x32_bf16 v[42:45], v[176:179], v[200:203], v[42:45]
	v_mfma_f32_16x16x32_bf16 v[38:41], v[168:171], v[208:211], v[38:41]
	v_mfma_f32_16x16x32_bf16 v[34:37], v[176:179], v[208:211], v[34:37]
	s_barrier
	s_setprio 0
	s_mov_b32 m0, s40
	v_lshl_add_u64 v[212:213], s[68:69], 0, v[134:135]
	ds_read_b128 v[180:183], v147 offset:16384
	ds_read_b128 v[184:187], v147 offset:17408
	ds_read_b128 v[188:191], v147 offset:18432
	ds_read_b128 v[192:195], v147 offset:19456
	ds_read_b128 v[196:199], v147 offset:20480
	ds_read_b128 v[200:203], v147 offset:21504
	ds_read_b128 v[204:207], v147 offset:22528
	ds_read_b128 v[208:211], v147 offset:23552
	global_load_lds_dwordx4 v[212:213], off
	v_lshl_add_u64 v[214:215], s[68:69], 0, v[130:131]
	s_mov_b32 m0, s48
	v_lshl_add_u64 v[216:217], vcc, 0, v[134:135]
	global_load_lds_dwordx4 v[214:215], off
	s_mov_b32 m0, s41
	v_lshl_add_u64 v[218:219], s[56:57], 0, v[132:133]
	global_load_lds_dwordx4 v[216:217], off
	v_lshl_add_u64 v[216:217], vcc, 0, v[130:131]
	s_mov_b32 m0, s75
	s_nop 0
	global_load_lds_dwordx4 v[216:217], off
	v_lshl_add_u64 v[216:217], s[56:57], 0, v[136:137]
	s_mov_b32 m0, s53
	s_nop 0
	global_load_lds_dwordx4 v[216:217], off
	s_mov_b32 m0, s54
	s_nop 0
	global_load_lds_dwordx4 v[218:219], off
	s_waitcnt vmcnt(8)
	s_waitcnt lgkmcnt(0)
	s_setprio 1
	s_barrier
; #define PG8_STAGE(bufoff, gbase, voff) do { _Pragma("unroll") for (int _i = 0; _i < 2; ++_i) \
;         __builtin_amdgcn_global_load_lds((const unsigned*)((const char*)(gbase) + (voff)[_i]), (PG8_LAS unsigned*)(lds + (bufoff) + ldsw + _i * 8192), 16, 0, 0); } while (0)
; #define PG8_LDA(dst, b, h) do { _Pragma("unroll") for (int m = 0; m < 4; ++m) _Pragma("unroll") for (int k = 0; k < 2; ++k) dst[m][k] = *(const PG8_LAS bf16x8*)(lds + PG8_SA(b, h) + aoff + m * 2048 + k * 1024); } while (0)
; #define PG8_LDB(dst, b, h) do { _Pragma("unroll") for (int n = 0; n < 2; ++n) _Pragma("unroll") for (int k = 0; k < 2; ++k) dst[n][k] = *(const PG8_LAS bf16x8*)(lds + PG8_SB(b, h) + boff + n * 2048 + k * 1024); } while (0)
; #define PG8_MMA(ai, bj, At, Bt) do { __builtin_amdgcn_s_setprio(1); _Pragma("unroll") for (int m = 0; m < 4; ++m) _Pragma("unroll") for (int n = 0; n < 2; ++n) _Pragma("unroll") for (int k = 0; k < 2; ++k) \
;         acc[ai][bj][m][n] = __builtin_amdgcn_mfma_f32_16x16x32_bf16(Bt[n][k], At[m][k], acc[ai][bj][m][n], 0, 0, 0); __builtin_amdgcn_s_setprio(0); } while (0)
; #define PG8_WAIT_V(n) asm volatile("s_waitcnt vmcnt(" #n ")" ::: "memory")
; #define PG8_WAIT_L(n) asm volatile("s_waitcnt lgkmcnt(" #n ")" ::: "memory")
; #define PG8_BAR __builtin_amdgcn_s_barrier()
; #define PG8_SCHED __builtin_amdgcn_sched_barrier(0)
; template <class Prob, class Epi, class Sched>
; __device__ __forceinline__ void gemm_phase(PG8_LAS unsigned char* lds, const Prob g, const Sched& S, const Epi& E) {
;     ...
;             PG8_WAIT_V(8); PG8_WAIT_L(0); PG8_BAR; PG8_MMA(1, 0, At, B0); PG8_MMA(1, 1, At, B1); PG8_BAR; PG8_SCHED;
;             PG8_LDB(B0, 1, 0); PG8_LDB(B1, 1, 1); PG8_SCHED; PG8_LDA(At, 1, 0); PG8_STAGE(PG8_SA(0, 1), a2 + hstepA, voffA);
;             PG8_WAIT_V(8); PG8_WAIT_L(0); PG8_BAR; PG8_MMA(0, 0, At, B0); PG8_MMA(0, 1, At, B1); PG8_BAR; PG8_SCHED;
;             PG8_LDA(At, 1, 1); PG8_STAGE(PG8_SB(1, 0), b3, voffB); PG8_STAGE(PG8_SB(1, 1), b3 + hstepB, voffB); PG8_STAGE(PG8_SA(1, 0), a3, voffA);
	v_mfma_f32_16x16x32_bf16 v[94:97], v[148:151], v[180:183], v[94:97]
	v_mfma_f32_16x16x32_bf16 v[90:93], v[156:159], v[180:183], v[90:93]
	v_mfma_f32_16x16x32_bf16 v[86:89], v[148:151], v[188:191], v[86:89]
	v_mfma_f32_16x16x32_bf16 v[78:81], v[156:159], v[188:191], v[78:81]
	v_mfma_f32_16x16x32_bf16 v[70:73], v[148:151], v[196:199], v[70:73]
	v_mfma_f32_16x16x32_bf16 v[62:65], v[156:159], v[196:199], v[62:65]
	v_mfma_f32_16x16x32_bf16 v[54:57], v[148:151], v[204:207], v[54:57]
	v_mfma_f32_16x16x32_bf16 v[46:49], v[156:159], v[204:207], v[46:49]
	v_mfma_f32_16x16x32_bf16 v[94:97], v[152:155], v[184:187], v[94:97]
	v_mfma_f32_16x16x32_bf16 v[90:93], v[160:163], v[184:187], v[90:93]
	v_mfma_f32_16x16x32_bf16 v[86:89], v[152:155], v[192:195], v[86:89]
	v_mfma_f32_16x16x32_bf16 v[78:81], v[160:163], v[192:195], v[78:81]
	v_mfma_f32_16x16x32_bf16 v[70:73], v[152:155], v[200:203], v[70:73]
	v_mfma_f32_16x16x32_bf16 v[62:65], v[160:163], v[200:203], v[62:65]
	v_mfma_f32_16x16x32_bf16 v[54:57], v[152:155], v[208:211], v[54:57]
	v_mfma_f32_16x16x32_bf16 v[46:49], v[160:163], v[208:211], v[46:49]
	v_mfma_f32_16x16x32_bf16 v[30:33], v[164:167], v[180:183], v[30:33]
	v_mfma_f32_16x16x32_bf16 v[26:29], v[172:175], v[180:183], v[26:29]
	v_mfma_f32_16x16x32_bf16 v[22:25], v[164:167], v[188:191], v[22:25]
	v_mfma_f32_16x16x32_bf16 v[18:21], v[172:175], v[188:191], v[18:21]
	v_mfma_f32_16x16x32_bf16 v[14:17], v[164:167], v[196:199], v[14:17]
	v_mfma_f32_16x16x32_bf16 v[10:13], v[172:175], v[196:199], v[10:13]
	v_mfma_f32_16x16x32_bf16 v[6:9], v[164:167], v[204:207], v[6:9]
	v_mfma_f32_16x16x32_bf16 v[2:5], v[172:175], v[204:207], v[2:5]
	v_mfma_f32_16x16x32_bf16 v[30:33], v[168:171], v[184:187], v[30:33]
	v_mfma_f32_16x16x32_bf16 v[26:29], v[176:179], v[184:187], v[26:29]
	v_mfma_f32_16x16x32_bf16 v[22:25], v[168:171], v[192:195], v[22:25]
	v_mfma_f32_16x16x32_bf16 v[18:21], v[176:179], v[192:195], v[18:21]
	v_mfma_f32_16x16x32_bf16 v[14:17], v[168:171], v[200:203], v[14:17]
	v_mfma_f32_16x16x32_bf16 v[10:13], v[176:179], v[200:203], v[10:13]
	v_mfma_f32_16x16x32_bf16 v[6:9], v[168:171], v[208:211], v[6:9]
	v_mfma_f32_16x16x32_bf16 v[2:5], v[176:179], v[208:211], v[2:5]
	s_barrier
	s_setprio 0
	v_add_u32_e32 v160, s45, v1
	v_add_u32_e32 v176, s82, v1
	ds_read_b128 v[148:151], v160
	ds_read_b128 v[152:155], v160 offset:1024
	ds_read_b128 v[156:159], v160 offset:2048
	ds_read_b128 v[160:163], v160 offset:3072
	ds_read_b128 v[164:167], v176
	ds_read_b128 v[168:171], v176 offset:1024
	ds_read_b128 v[172:175], v176 offset:2048
	ds_read_b128 v[176:179], v176 offset:3072
	s_mov_b32 m0, s55
	v_lshl_add_u64 v[220:221], s[36:37], 0, v[136:137]
	ds_read_b128 v[180:183], v147 offset:32768
	ds_read_b128 v[184:187], v147 offset:33792
	ds_read_b128 v[188:191], v147 offset:34816
	ds_read_b128 v[192:195], v147 offset:35840
	ds_read_b128 v[196:199], v147 offset:36864
	ds_read_b128 v[200:203], v147 offset:37888
	ds_read_b128 v[204:207], v147 offset:38912
	ds_read_b128 v[208:211], v147 offset:39936
	global_load_lds_dwordx4 v[220:221], off
	v_lshl_add_u64 v[220:221], s[36:37], 0, v[132:133]
	s_mov_b32 m0, s64
	s_nop 0
	global_load_lds_dwordx4 v[220:221], off
	s_waitcnt vmcnt(8)
	s_waitcnt lgkmcnt(0)
	s_setprio 1
	s_barrier
	v_mfma_f32_16x16x32_bf16 v[126:129], v[148:151], v[180:183], v[126:129]
	v_mfma_f32_16x16x32_bf16 v[122:125], v[156:159], v[180:183], v[122:125]
	v_mfma_f32_16x16x32_bf16 v[118:121], v[148:151], v[188:191], v[118:121]
	v_mfma_f32_16x16x32_bf16 v[114:117], v[156:159], v[188:191], v[114:117]
	v_mfma_f32_16x16x32_bf16 v[110:113], v[148:151], v[196:199], v[110:113]
	v_mfma_f32_16x16x32_bf16 v[106:109], v[156:159], v[196:199], v[106:109]
	v_mfma_f32_16x16x32_bf16 v[102:105], v[148:151], v[204:207], v[102:105]
	v_mfma_f32_16x16x32_bf16 v[98:101], v[156:159], v[204:207], v[98:101]
	v_mfma_f32_16x16x32_bf16 v[126:129], v[152:155], v[184:187], v[126:129]
	v_mfma_f32_16x16x32_bf16 v[122:125], v[160:163], v[184:187], v[122:125]
	v_mfma_f32_16x16x32_bf16 v[118:121], v[152:155], v[192:195], v[118:121]
	v_mfma_f32_16x16x32_bf16 v[114:117], v[160:163], v[192:195], v[114:117]
	v_mfma_f32_16x16x32_bf16 v[110:113], v[152:155], v[200:203], v[110:113]
	v_mfma_f32_16x16x32_bf16 v[106:109], v[160:163], v[200:203], v[106:109]
	v_mfma_f32_16x16x32_bf16 v[102:105], v[152:155], v[208:211], v[102:105]
	v_mfma_f32_16x16x32_bf16 v[98:101], v[160:163], v[208:211], v[98:101]
	v_mfma_f32_16x16x32_bf16 v[82:85], v[164:167], v[180:183], v[82:85]
	v_mfma_f32_16x16x32_bf16 v[74:77], v[172:175], v[180:183], v[74:77]
	v_mfma_f32_16x16x32_bf16 v[66:69], v[164:167], v[188:191], v[66:69]
	v_mfma_f32_16x16x32_bf16 v[58:61], v[172:175], v[188:191], v[58:61]
	v_mfma_f32_16x16x32_bf16 v[50:53], v[164:167], v[196:199], v[50:53]
	v_mfma_f32_16x16x32_bf16 v[42:45], v[172:175], v[196:199], v[42:45]
	v_mfma_f32_16x16x32_bf16 v[38:41], v[164:167], v[204:207], v[38:41]
	v_mfma_f32_16x16x32_bf16 v[34:37], v[172:175], v[204:207], v[34:37]
	v_mfma_f32_16x16x32_bf16 v[82:85], v[168:171], v[184:187], v[82:85]
	v_mfma_f32_16x16x32_bf16 v[74:77], v[176:179], v[184:187], v[74:77]
	v_mfma_f32_16x16x32_bf16 v[66:69], v[168:171], v[192:195], v[66:69]
	v_mfma_f32_16x16x32_bf16 v[58:61], v[176:179], v[192:195], v[58:61]
	v_mfma_f32_16x16x32_bf16 v[50:53], v[168:171], v[200:203], v[50:53]
	v_mfma_f32_16x16x32_bf16 v[42:45], v[176:179], v[200:203], v[42:45]
	v_mfma_f32_16x16x32_bf16 v[38:41], v[168:171], v[208:211], v[38:41]
	v_mfma_f32_16x16x32_bf16 v[34:37], v[176:179], v[208:211], v[34:37]
	s_barrier
; #define PG8_STAGE(bufoff, gbase, voff) do { _Pragma("unroll") for (int _i = 0; _i < 2; ++_i) \
;         __builtin_amdgcn_global_load_lds((const unsigned*)((const char*)(gbase) + (voff)[_i]), (PG8_LAS unsigned*)(lds + (bufoff) + ldsw + _i * 8192), 16, 0, 0); } while (0)
; #define PG8_LDA(dst, b, h) do { _Pragma("unroll") for (int m = 0; m < 4; ++m) _Pragma("unroll") for (int k = 0; k < 2; ++k) dst[m][k] = *(const PG8_LAS bf16x8*)(lds + PG8_SA(b, h) + aoff + m * 2048 + k * 1024); } while (0)
; #define PG8_MMA(ai, bj, At, Bt) do { __builtin_amdgcn_s_setprio(1); _Pragma("unroll") for (int m = 0; m < 4; ++m) _Pragma("unroll") for (int n = 0; n < 2; ++n) _Pragma("unroll") for (int k = 0; k < 2; ++k) \
;         acc[ai][bj][m][n] = __builtin_amdgcn_mfma_f32_16x16x32_bf16(Bt[n][k], At[m][k], acc[ai][bj][m][n], 0, 0, 0); __builtin_amdgcn_s_setprio(0); } while (0)
; #define PG8_WAIT_V(n) asm volatile("s_waitcnt vmcnt(" #n ")" ::: "memory")
; #define PG8_WAIT_L(n) asm volatile("s_waitcnt lgkmcnt(" #n ")" ::: "memory")
; #define PG8_BAR __builtin_amdgcn_s_barrier()
; #define PG8_SCHED __builtin_amdgcn_sched_barrier(0)
; template <class Prob, class Epi, class Sched>
; __device__ __forceinline__ void gemm_phase(PG8_LAS unsigned char* lds, const Prob g, const Sched& S, const Epi& E) {
;     ...
;             PG8_LDA(At, 1, 1); PG8_STAGE(PG8_SB(1, 0), b3, voffB); PG8_STAGE(PG8_SB(1, 1), b3 + hstepB, voffB); PG8_STAGE(PG8_SA(1, 0), a3, voffA);
;             PG8_WAIT_V(8); PG8_WAIT_L(0); PG8_BAR; PG8_MMA(1, 0, At, B0); PG8_MMA(1, 1, At, B1); PG8_BAR; PG8_SCHED;
;         }
;         if (wr == 0) PG8_BAR;
	s_setprio 0
	s_mov_b32 m0, s59
	v_lshl_add_u64 v[212:213], v[212:213], 0, s[88:89]
	ds_read_b128 v[180:183], v147 offset:49152
	ds_read_b128 v[184:187], v147 offset:50176
	ds_read_b128 v[188:191], v147 offset:51200
	ds_read_b128 v[192:195], v147 offset:52224
	ds_read_b128 v[196:199], v147 offset:53248
	ds_read_b128 v[200:203], v147 offset:54272
	ds_read_b128 v[204:207], v147 offset:55296
	ds_read_b128 v[208:211], v147 offset:56320
	global_load_lds_dwordx4 v[212:213], off
	v_lshl_add_u64 v[212:213], v[214:215], 0, s[88:89]
	s_mov_b32 m0, s83
	s_nop 0
	global_load_lds_dwordx4 v[212:213], off
	v_lshl_add_u64 v[212:213], s[34:35], 0, v[134:135]
	s_mov_b32 m0, s49
	s_nop 0
	global_load_lds_dwordx4 v[212:213], off
	v_lshl_add_u64 v[212:213], s[34:35], 0, v[130:131]
	s_mov_b32 m0, s4
	s_nop 0
	global_load_lds_dwordx4 v[212:213], off
	v_lshl_add_u64 v[212:213], v[216:217], 0, s[88:89]
	s_mov_b32 m0, s66
	s_nop 0
	global_load_lds_dwordx4 v[212:213], off
	v_lshl_add_u64 v[212:213], v[218:219], 0, s[88:89]
	s_mov_b32 m0, s71
	s_nop 0
	global_load_lds_dwordx4 v[212:213], off
	s_waitcnt vmcnt(8)
	s_waitcnt lgkmcnt(0)
	s_setprio 1
	s_barrier
	v_mfma_f32_16x16x32_bf16 v[94:97], v[148:151], v[180:183], v[94:97]
	v_mfma_f32_16x16x32_bf16 v[90:93], v[156:159], v[180:183], v[90:93]
	v_mfma_f32_16x16x32_bf16 v[86:89], v[148:151], v[188:191], v[86:89]
	v_mfma_f32_16x16x32_bf16 v[78:81], v[156:159], v[188:191], v[78:81]
	v_mfma_f32_16x16x32_bf16 v[70:73], v[148:151], v[196:199], v[70:73]
	v_mfma_f32_16x16x32_bf16 v[62:65], v[156:159], v[196:199], v[62:65]
	v_mfma_f32_16x16x32_bf16 v[54:57], v[148:151], v[204:207], v[54:57]
	v_mfma_f32_16x16x32_bf16 v[46:49], v[156:159], v[204:207], v[46:49]
	v_mfma_f32_16x16x32_bf16 v[94:97], v[152:155], v[184:187], v[94:97]
	v_mfma_f32_16x16x32_bf16 v[90:93], v[160:163], v[184:187], v[90:93]
	v_mfma_f32_16x16x32_bf16 v[86:89], v[152:155], v[192:195], v[86:89]
	v_mfma_f32_16x16x32_bf16 v[78:81], v[160:163], v[192:195], v[78:81]
	v_mfma_f32_16x16x32_bf16 v[70:73], v[152:155], v[200:203], v[70:73]
	v_mfma_f32_16x16x32_bf16 v[62:65], v[160:163], v[200:203], v[62:65]
	v_mfma_f32_16x16x32_bf16 v[54:57], v[152:155], v[208:211], v[54:57]
	v_mfma_f32_16x16x32_bf16 v[46:49], v[160:163], v[208:211], v[46:49]
	v_mfma_f32_16x16x32_bf16 v[30:33], v[164:167], v[180:183], v[30:33]
	v_mfma_f32_16x16x32_bf16 v[26:29], v[172:175], v[180:183], v[26:29]
	v_mfma_f32_16x16x32_bf16 v[22:25], v[164:167], v[188:191], v[22:25]
	v_mfma_f32_16x16x32_bf16 v[18:21], v[172:175], v[188:191], v[18:21]
	v_mfma_f32_16x16x32_bf16 v[14:17], v[164:167], v[196:199], v[14:17]
	v_mfma_f32_16x16x32_bf16 v[10:13], v[172:175], v[196:199], v[10:13]
	v_mfma_f32_16x16x32_bf16 v[6:9], v[164:167], v[204:207], v[6:9]
	v_mfma_f32_16x16x32_bf16 v[2:5], v[172:175], v[204:207], v[2:5]
	v_mfma_f32_16x16x32_bf16 v[30:33], v[168:171], v[184:187], v[30:33]
	v_mfma_f32_16x16x32_bf16 v[26:29], v[176:179], v[184:187], v[26:29]
	v_mfma_f32_16x16x32_bf16 v[22:25], v[168:171], v[192:195], v[22:25]
	v_mfma_f32_16x16x32_bf16 v[18:21], v[176:179], v[192:195], v[18:21]
	v_mfma_f32_16x16x32_bf16 v[14:17], v[168:171], v[200:203], v[14:17]
	v_mfma_f32_16x16x32_bf16 v[10:13], v[176:179], v[200:203], v[10:13]
	v_mfma_f32_16x16x32_bf16 v[6:9], v[168:171], v[208:211], v[6:9]
	v_mfma_f32_16x16x32_bf16 v[2:5], v[176:179], v[208:211], v[2:5]
	s_barrier
	s_setprio 0
	s_movk_i32 s36, 0x100
	s_andn2_b64 vcc, exec, s[30:31]
	s_mov_b64 s[34:35], -1
	s_mov_b64 s[30:31], 0
	s_cbranch_vccz .LBB0_608
	s_and_b64 vcc, exec, s[16:17]
	s_cbranch_vccz .LBB0_611
	s_barrier

; #define PG8_STAGE(bufoff, gbase, voff) do { _Pragma("unroll") for (int _i = 0; _i < 2; ++_i) \
;         __builtin_amdgcn_global_load_lds((const unsigned*)((const char*)(gbase) + (voff)[_i]), (PG8_LAS unsigned*)(lds + (bufoff) + ldsw + _i * 8192), 16, 0, 0); } while (0)
; #define PG8_LDA(dst, b, h) do { _Pragma("unroll") for (int m = 0; m < 4; ++m) _Pragma("unroll") for (int k = 0; k < 2; ++k) dst[m][k] = *(const PG8_LAS bf16x8*)(lds + PG8_SA(b, h) + aoff + m * 2048 + k * 1024); } while (0)
; #define PG8_LDB(dst, b, h) do { _Pragma("unroll") for (int n = 0; n < 2; ++n) _Pragma("unroll") for (int k = 0; k < 2; ++k) dst[n][k] = *(const PG8_LAS bf16x8*)(lds + PG8_SB(b, h) + boff + n * 2048 + k * 1024); } while (0)
; #define PG8_MMA(ai, bj, At, Bt) do { __builtin_amdgcn_s_setprio(1); _Pragma("unroll") for (int m = 0; m < 4; ++m) _Pragma("unroll") for (int n = 0; n < 2; ++n) _Pragma("unroll") for (int k = 0; k < 2; ++k) \
;         acc[ai][bj][m][n] = __builtin_amdgcn_mfma_f32_16x16x32_bf16(Bt[n][k], At[m][k], acc[ai][bj][m][n], 0, 0, 0); __builtin_amdgcn_s_setprio(0); } while (0)
; #define PG8_WAIT_V(n) asm volatile("s_waitcnt vmcnt(" #n ")" ::: "memory")
; #define PG8_WAIT_L(n) asm volatile("s_waitcnt lgkmcnt(" #n ")" ::: "memory")
; #define PG8_BAR __builtin_amdgcn_s_barrier()
; #define PG8_SCHED __builtin_amdgcn_sched_barrier(0)
; template <class Prob, class Epi, class Sched>
; __device__ __forceinline__ void gemm_phase(PG8_LAS unsigned char* lds, const Prob g, const Sched& S, const Epi& E) {
;     ...
;             const bool last = (t == nt - 2);
;             const char* a1 = cA + (size_t)(t + 1) * kstep;
;             const char* a2 = last ? nA : cA + (size_t)(t + 2) * kstep; const char* b2 = last ? nB : cB + (size_t)(t + 2) * kstep;
;             const char* a3 = a2 + kstep; const char* b3 = b2 + kstep;
;             PG8_LDB(B0, 0, 0); PG8_LDB(B1, 0, 1); PG8_SCHED; PG8_LDA(At, 0, 0); PG8_STAGE(PG8_SA(1, 1), a1 + hstepA, voffA);
;             PG8_WAIT_V(8); PG8_WAIT_L(0); PG8_BAR; PG8_MMA(0, 0, At, B0); PG8_MMA(0, 1, At, B1); PG8_BAR; PG8_SCHED;
;             PG8_LDA(At, 0, 1); PG8_STAGE(PG8_SB(0, 0), b2, voffB); PG8_STAGE(PG8_SB(0, 1), b2 + hstepB, voffB); PG8_STAGE(PG8_SA(0, 0), a2, voffA);
;             PG8_WAIT_V(8); PG8_WAIT_L(0); PG8_BAR; PG8_MMA(1, 0, At, B0); PG8_MMA(1, 1, At, B1); PG8_BAR; PG8_SCHED;
.LBB0_674:
	s_add_u32 s4, s8, 0xfffe0080
	s_addc_u32 s5, s9, -1
	s_add_i32 s40, 0, 0x10000
	s_cmp_eq_u32 s44, 4
	s_cselect_b32 s35, s25, s5
	s_cselect_b32 s34, s27, s4
	s_cselect_b32 s5, s29, s37
	s_cselect_b32 s4, s28, s36
	s_add_i32 s41, 0, 0x14000
	v_add_u32_e32 v164, s40, v1
	v_add_u32_e32 v180, s41, v1
	ds_read_b128 v[152:155], v164
	ds_read_b128 v[156:159], v164 offset:1024
	ds_read_b128 v[160:163], v164 offset:2048
	ds_read_b128 v[164:167], v164 offset:3072
	ds_read_b128 v[168:171], v180
	ds_read_b128 v[172:175], v180 offset:1024
	ds_read_b128 v[176:179], v180 offset:2048
	ds_read_b128 v[180:183], v180 offset:3072
	s_add_i32 m0, s21, 0xc000
	ds_read_b128 v[184:187], v151
	ds_read_b128 v[188:191], v151 offset:1024
	ds_read_b128 v[192:195], v151 offset:2048
	ds_read_b128 v[196:199], v151 offset:3072
	ds_read_b128 v[200:203], v151 offset:4096
	ds_read_b128 v[204:207], v151 offset:5120
	ds_read_b128 v[208:211], v151 offset:6144
	ds_read_b128 v[212:215], v151 offset:7168
	global_load_lds_dwordx4 v138, s[8:9]
	s_add_i32 m0, s21, 0xe000
	s_nop 0
	global_load_lds_dwordx4 v140, s[8:9]
	s_waitcnt vmcnt(8)
	s_waitcnt lgkmcnt(0)
	s_setprio 1
	s_barrier
	v_mfma_f32_16x16x32_bf16 v[126:129], v[152:155], v[184:187], v[126:129]
	v_mfma_f32_16x16x32_bf16 v[122:125], v[160:163], v[184:187], v[122:125]
	v_mfma_f32_16x16x32_bf16 v[118:121], v[152:155], v[192:195], v[118:121]
	v_mfma_f32_16x16x32_bf16 v[114:117], v[160:163], v[192:195], v[114:117]
	v_mfma_f32_16x16x32_bf16 v[102:105], v[152:155], v[200:203], v[102:105]
	v_mfma_f32_16x16x32_bf16 v[98:101], v[160:163], v[200:203], v[98:101]
	v_mfma_f32_16x16x32_bf16 v[86:89], v[152:155], v[208:211], v[86:89]
	v_mfma_f32_16x16x32_bf16 v[82:85], v[160:163], v[208:211], v[82:85]
	v_mfma_f32_16x16x32_bf16 v[126:129], v[156:159], v[188:191], v[126:129]
	v_mfma_f32_16x16x32_bf16 v[122:125], v[164:167], v[188:191], v[122:125]
	v_mfma_f32_16x16x32_bf16 v[118:121], v[156:159], v[196:199], v[118:121]
	v_mfma_f32_16x16x32_bf16 v[114:117], v[164:167], v[196:199], v[114:117]
	v_mfma_f32_16x16x32_bf16 v[102:105], v[156:159], v[204:207], v[102:105]
	v_mfma_f32_16x16x32_bf16 v[98:101], v[164:167], v[204:207], v[98:101]
	v_mfma_f32_16x16x32_bf16 v[86:89], v[156:159], v[212:215], v[86:89]
	v_mfma_f32_16x16x32_bf16 v[82:85], v[164:167], v[212:215], v[82:85]
	v_mfma_f32_16x16x32_bf16 v[110:113], v[168:171], v[184:187], v[110:113]
	v_mfma_f32_16x16x32_bf16 v[106:109], v[176:179], v[184:187], v[106:109]
	v_mfma_f32_16x16x32_bf16 v[94:97], v[168:171], v[192:195], v[94:97]
	v_mfma_f32_16x16x32_bf16 v[90:93], v[176:179], v[192:195], v[90:93]
	v_mfma_f32_16x16x32_bf16 v[78:81], v[168:171], v[200:203], v[78:81]
	v_mfma_f32_16x16x32_bf16 v[74:77], v[176:179], v[200:203], v[74:77]
	v_mfma_f32_16x16x32_bf16 v[70:73], v[168:171], v[208:211], v[70:73]
	v_mfma_f32_16x16x32_bf16 v[66:69], v[176:179], v[208:211], v[66:69]
	v_mfma_f32_16x16x32_bf16 v[110:113], v[172:175], v[188:191], v[110:113]
	v_mfma_f32_16x16x32_bf16 v[106:109], v[180:183], v[188:191], v[106:109]
	v_mfma_f32_16x16x32_bf16 v[94:97], v[172:175], v[196:199], v[94:97]
	v_mfma_f32_16x16x32_bf16 v[90:93], v[180:183], v[196:199], v[90:93]
	v_mfma_f32_16x16x32_bf16 v[78:81], v[172:175], v[204:207], v[78:81]
	v_mfma_f32_16x16x32_bf16 v[74:77], v[180:183], v[204:207], v[74:77]
	v_mfma_f32_16x16x32_bf16 v[70:73], v[172:175], v[212:215], v[70:73]
	v_mfma_f32_16x16x32_bf16 v[66:69], v[180:183], v[212:215], v[66:69]
	s_barrier
	s_setprio 0
	s_add_i32 s40, s40, s53
	v_lshl_add_u64 v[216:217], s[4:5], 0, v[134:135]
	s_mov_b32 m0, s40
	ds_read_b128 v[184:187], v151 offset:16384
	ds_read_b128 v[188:191], v151 offset:17408
	ds_read_b128 v[192:195], v151 offset:18432
	ds_read_b128 v[196:199], v151 offset:19456
	ds_read_b128 v[200:203], v151 offset:20480
	ds_read_b128 v[204:207], v151 offset:21504
	ds_read_b128 v[208:211], v151 offset:22528
	ds_read_b128 v[212:215], v151 offset:23552
	global_load_lds_dwordx4 v134, s[4:5]
	s_add_i32 m0, s40, 0x2000
	v_lshl_add_u64 v[218:219], s[4:5], 0, v[130:131]
	s_add_u32 s4, s4, s39
	s_addc_u32 s5, s5, 0
	s_add_i32 s40, s41, s53
	global_load_lds_dwordx4 v[218:219], off
	v_lshl_add_u64 v[220:221], s[4:5], 0, v[134:135]
	s_mov_b32 m0, s40
	v_lshl_add_u64 v[222:223], s[4:5], 0, v[130:131]
	global_load_lds_dwordx4 v134, s[4:5]
	s_add_i32 m0, s40, 0x2000
	s_nop 0
	global_load_lds_dwordx4 v130, s[4:5]
	s_mov_b32 m0, s21
	s_nop 0
	global_load_lds_dwordx4 v136, s[34:35]
	s_mov_b32 m0, s23
	s_nop 0
	global_load_lds_dwordx4 v132, s[34:35]
	s_waitcnt vmcnt(8)
	s_waitcnt lgkmcnt(0)
	s_setprio 1
	s_barrier
; #define PG8_STAGE(bufoff, gbase, voff) do { _Pragma("unroll") for (int _i = 0; _i < 2; ++_i) \
;         __builtin_amdgcn_global_load_lds((const unsigned*)((const char*)(gbase) + (voff)[_i]), (PG8_LAS unsigned*)(lds + (bufoff) + ldsw + _i * 8192), 16, 0, 0); } while (0)
; #define PG8_LDA(dst, b, h) do { _Pragma("unroll") for (int m = 0; m < 4; ++m) _Pragma("unroll") for (int k = 0; k < 2; ++k) dst[m][k] = *(const PG8_LAS bf16x8*)(lds + PG8_SA(b, h) + aoff + m * 2048 + k * 1024); } while (0)
; #define PG8_LDB(dst, b, h) do { _Pragma("unroll") for (int n = 0; n < 2; ++n) _Pragma("unroll") for (int k = 0; k < 2; ++k) dst[n][k] = *(const PG8_LAS bf16x8*)(lds + PG8_SB(b, h) + boff + n * 2048 + k * 1024); } while (0)
; #define PG8_MMA(ai, bj, At, Bt) do { __builtin_amdgcn_s_setprio(1); _Pragma("unroll") for (int m = 0; m < 4; ++m) _Pragma("unroll") for (int n = 0; n < 2; ++n) _Pragma("unroll") for (int k = 0; k < 2; ++k) \
;         acc[ai][bj][m][n] = __builtin_amdgcn_mfma_f32_16x16x32_bf16(Bt[n][k], At[m][k], acc[ai][bj][m][n], 0, 0, 0); __builtin_amdgcn_s_setprio(0); } while (0)
; #define PG8_WAIT_V(n) asm volatile("s_waitcnt vmcnt(" #n ")" ::: "memory")
; #define PG8_WAIT_L(n) asm volatile("s_waitcnt lgkmcnt(" #n ")" ::: "memory")
; #define PG8_BAR __builtin_amdgcn_s_barrier()
; #define PG8_SCHED __builtin_amdgcn_sched_barrier(0)
; template <class Prob, class Epi, class Sched>
; __device__ __forceinline__ void gemm_phase(PG8_LAS unsigned char* lds, const Prob g, const Sched& S, const Epi& E) {
;     ...
;             PG8_WAIT_V(8); PG8_WAIT_L(0); PG8_BAR; PG8_MMA(1, 0, At, B0); PG8_MMA(1, 1, At, B1); PG8_BAR; PG8_SCHED;
;             PG8_LDB(B0, 1, 0); PG8_LDB(B1, 1, 1); PG8_SCHED; PG8_LDA(At, 1, 0); PG8_STAGE(PG8_SA(0, 1), a2 + hstepA, voffA);
;             PG8_WAIT_V(8); PG8_WAIT_L(0); PG8_BAR; PG8_MMA(0, 0, At, B0); PG8_MMA(0, 1, At, B1); PG8_BAR; PG8_SCHED;
	v_mfma_f32_16x16x32_bf16 v[62:65], v[152:155], v[184:187], v[62:65]
	v_mfma_f32_16x16x32_bf16 v[58:61], v[160:163], v[184:187], v[58:61]
	v_mfma_f32_16x16x32_bf16 v[54:57], v[152:155], v[192:195], v[54:57]
	v_mfma_f32_16x16x32_bf16 v[50:53], v[160:163], v[192:195], v[50:53]
	v_mfma_f32_16x16x32_bf16 v[38:41], v[152:155], v[200:203], v[38:41]
	v_mfma_f32_16x16x32_bf16 v[34:37], v[160:163], v[200:203], v[34:37]
	v_mfma_f32_16x16x32_bf16 v[22:25], v[152:155], v[208:211], v[22:25]
	v_mfma_f32_16x16x32_bf16 v[18:21], v[160:163], v[208:211], v[18:21]
	v_mfma_f32_16x16x32_bf16 v[62:65], v[156:159], v[188:191], v[62:65]
	v_mfma_f32_16x16x32_bf16 v[58:61], v[164:167], v[188:191], v[58:61]
	v_mfma_f32_16x16x32_bf16 v[54:57], v[156:159], v[196:199], v[54:57]
	v_mfma_f32_16x16x32_bf16 v[50:53], v[164:167], v[196:199], v[50:53]
	v_mfma_f32_16x16x32_bf16 v[38:41], v[156:159], v[204:207], v[38:41]
	v_mfma_f32_16x16x32_bf16 v[34:37], v[164:167], v[204:207], v[34:37]
	v_mfma_f32_16x16x32_bf16 v[22:25], v[156:159], v[212:215], v[22:25]
	v_mfma_f32_16x16x32_bf16 v[18:21], v[164:167], v[212:215], v[18:21]
	v_mfma_f32_16x16x32_bf16 v[46:49], v[168:171], v[184:187], v[46:49]
	v_mfma_f32_16x16x32_bf16 v[42:45], v[176:179], v[184:187], v[42:45]
	v_mfma_f32_16x16x32_bf16 v[30:33], v[168:171], v[192:195], v[30:33]
	v_mfma_f32_16x16x32_bf16 v[26:29], v[176:179], v[192:195], v[26:29]
	v_mfma_f32_16x16x32_bf16 v[14:17], v[168:171], v[200:203], v[14:17]
	v_mfma_f32_16x16x32_bf16 v[10:13], v[176:179], v[200:203], v[10:13]
	v_mfma_f32_16x16x32_bf16 v[6:9], v[168:171], v[208:211], v[6:9]
	v_mfma_f32_16x16x32_bf16 v[2:5], v[176:179], v[208:211], v[2:5]
	v_mfma_f32_16x16x32_bf16 v[46:49], v[172:175], v[188:191], v[46:49]
	v_mfma_f32_16x16x32_bf16 v[42:45], v[180:183], v[188:191], v[42:45]
	v_mfma_f32_16x16x32_bf16 v[30:33], v[172:175], v[196:199], v[30:33]
	v_mfma_f32_16x16x32_bf16 v[26:29], v[180:183], v[196:199], v[26:29]
	v_mfma_f32_16x16x32_bf16 v[14:17], v[172:175], v[204:207], v[14:17]
	v_mfma_f32_16x16x32_bf16 v[10:13], v[180:183], v[204:207], v[10:13]
	v_mfma_f32_16x16x32_bf16 v[6:9], v[172:175], v[212:215], v[6:9]
	v_mfma_f32_16x16x32_bf16 v[2:5], v[180:183], v[212:215], v[2:5]
	s_barrier
	s_setprio 0
	s_add_i32 s40, 0, 0x18000
	s_add_i32 s41, 0, 0x1c000
	v_add_u32_e32 v164, s40, v1
	v_add_u32_e32 v180, s41, v1
	ds_read_b128 v[152:155], v164
	ds_read_b128 v[156:159], v164 offset:1024
	ds_read_b128 v[160:163], v164 offset:2048
	ds_read_b128 v[164:167], v164 offset:3072
	ds_read_b128 v[168:171], v180
	ds_read_b128 v[172:175], v180 offset:1024
	ds_read_b128 v[176:179], v180 offset:2048
	ds_read_b128 v[180:183], v180 offset:3072
	s_add_u32 s4, s34, 0x20000
	s_addc_u32 s5, s35, 0
	s_mov_b32 m0, s64
	ds_read_b128 v[184:187], v151 offset:32768
	ds_read_b128 v[188:191], v151 offset:33792
	ds_read_b128 v[192:195], v151 offset:34816
	ds_read_b128 v[196:199], v151 offset:35840
	ds_read_b128 v[200:203], v151 offset:36864
	ds_read_b128 v[204:207], v151 offset:37888
	ds_read_b128 v[208:211], v151 offset:38912
	ds_read_b128 v[212:215], v151 offset:39936
	global_load_lds_dwordx4 v136, s[4:5]
	s_mov_b32 m0, s66
	s_nop 0
	global_load_lds_dwordx4 v132, s[4:5]
	s_waitcnt vmcnt(8)
	s_waitcnt lgkmcnt(0)
	s_setprio 1
	s_barrier
	v_mfma_f32_16x16x32_bf16 v[126:129], v[152:155], v[184:187], v[126:129]
	v_mfma_f32_16x16x32_bf16 v[122:125], v[160:163], v[184:187], v[122:125]
	v_mfma_f32_16x16x32_bf16 v[118:121], v[152:155], v[192:195], v[118:121]
	v_mfma_f32_16x16x32_bf16 v[114:117], v[160:163], v[192:195], v[114:117]
	v_mfma_f32_16x16x32_bf16 v[102:105], v[152:155], v[200:203], v[102:105]
	v_mfma_f32_16x16x32_bf16 v[98:101], v[160:163], v[200:203], v[98:101]
	v_mfma_f32_16x16x32_bf16 v[86:89], v[152:155], v[208:211], v[86:89]
	v_mfma_f32_16x16x32_bf16 v[82:85], v[160:163], v[208:211], v[82:85]
	v_mfma_f32_16x16x32_bf16 v[126:129], v[156:159], v[188:191], v[126:129]
	v_mfma_f32_16x16x32_bf16 v[122:125], v[164:167], v[188:191], v[122:125]
	v_mfma_f32_16x16x32_bf16 v[118:121], v[156:159], v[196:199], v[118:121]
	v_mfma_f32_16x16x32_bf16 v[114:117], v[164:167], v[196:199], v[114:117]
	v_mfma_f32_16x16x32_bf16 v[102:105], v[156:159], v[204:207], v[102:105]
	v_mfma_f32_16x16x32_bf16 v[98:101], v[164:167], v[204:207], v[98:101]
	v_mfma_f32_16x16x32_bf16 v[86:89], v[156:159], v[212:215], v[86:89]
	v_mfma_f32_16x16x32_bf16 v[82:85], v[164:167], v[212:215], v[82:85]
	v_mfma_f32_16x16x32_bf16 v[110:113], v[168:171], v[184:187], v[110:113]
	v_mfma_f32_16x16x32_bf16 v[106:109], v[176:179], v[184:187], v[106:109]
	v_mfma_f32_16x16x32_bf16 v[94:97], v[168:171], v[192:195], v[94:97]
	v_mfma_f32_16x16x32_bf16 v[90:93], v[176:179], v[192:195], v[90:93]
	v_mfma_f32_16x16x32_bf16 v[78:81], v[168:171], v[200:203], v[78:81]
	v_mfma_f32_16x16x32_bf16 v[74:77], v[176:179], v[200:203], v[74:77]
	v_mfma_f32_16x16x32_bf16 v[70:73], v[168:171], v[208:211], v[70:73]
	v_mfma_f32_16x16x32_bf16 v[66:69], v[176:179], v[208:211], v[66:69]
	v_mfma_f32_16x16x32_bf16 v[110:113], v[172:175], v[188:191], v[110:113]
	v_mfma_f32_16x16x32_bf16 v[106:109], v[180:183], v[188:191], v[106:109]
	v_mfma_f32_16x16x32_bf16 v[94:97], v[172:175], v[196:199], v[94:97]
	v_mfma_f32_16x16x32_bf16 v[90:93], v[180:183], v[196:199], v[90:93]
	v_mfma_f32_16x16x32_bf16 v[78:81], v[172:175], v[204:207], v[78:81]
	v_mfma_f32_16x16x32_bf16 v[74:77], v[180:183], v[204:207], v[74:77]
	v_mfma_f32_16x16x32_bf16 v[70:73], v[172:175], v[212:215], v[70:73]
	v_mfma_f32_16x16x32_bf16 v[66:69], v[180:183], v[212:215], v[66:69]
	s_barrier
; #define PG8_STAGE(bufoff, gbase, voff) do { _Pragma("unroll") for (int _i = 0; _i < 2; ++_i) \
;         __builtin_amdgcn_global_load_lds((const unsigned*)((const char*)(gbase) + (voff)[_i]), (PG8_LAS unsigned*)(lds + (bufoff) + ldsw + _i * 8192), 16, 0, 0); } while (0)
; #define PG8_LDA(dst, b, h) do { _Pragma("unroll") for (int m = 0; m < 4; ++m) _Pragma("unroll") for (int k = 0; k < 2; ++k) dst[m][k] = *(const PG8_LAS bf16x8*)(lds + PG8_SA(b, h) + aoff + m * 2048 + k * 1024); } while (0)
; #define PG8_MMA(ai, bj, At, Bt) do { __builtin_amdgcn_s_setprio(1); _Pragma("unroll") for (int m = 0; m < 4; ++m) _Pragma("unroll") for (int n = 0; n < 2; ++n) _Pragma("unroll") for (int k = 0; k < 2; ++k) \
;         acc[ai][bj][m][n] = __builtin_amdgcn_mfma_f32_16x16x32_bf16(Bt[n][k], At[m][k], acc[ai][bj][m][n], 0, 0, 0); __builtin_amdgcn_s_setprio(0); } while (0)
; #define PG8_WAIT_V(n) asm volatile("s_waitcnt vmcnt(" #n ")" ::: "memory")
; #define PG8_WAIT_L(n) asm volatile("s_waitcnt lgkmcnt(" #n ")" ::: "memory")
; #define PG8_BAR __builtin_amdgcn_s_barrier()
; #define PG8_SCHED __builtin_amdgcn_sched_barrier(0)
; template <class Prob, class Epi, class Sched>
; __device__ __forceinline__ void gemm_phase(PG8_LAS unsigned char* lds, const Prob g, const Sched& S, const Epi& E) {
;     ...
;             PG8_LDA(At, 1, 1); PG8_STAGE(PG8_SB(1, 0), b3, voffB); PG8_STAGE(PG8_SB(1, 1), b3 + hstepB, voffB); PG8_STAGE(PG8_SA(1, 0), a3, voffA);
;             PG8_WAIT_V(8); PG8_WAIT_L(0); PG8_BAR; PG8_MMA(1, 0, At, B0); PG8_MMA(1, 1, At, B1); PG8_BAR; PG8_SCHED;
;         }
;         if (wr == 0) PG8_BAR;
	s_setprio 0
	s_add_i32 s4, s40, s53
	v_lshl_add_u64 v[216:217], v[216:217], 0, s[88:89]
	s_mov_b32 m0, s4
	ds_read_b128 v[184:187], v151 offset:49152
	ds_read_b128 v[188:191], v151 offset:50176
	ds_read_b128 v[192:195], v151 offset:51200
	ds_read_b128 v[196:199], v151 offset:52224
	ds_read_b128 v[200:203], v151 offset:53248
	ds_read_b128 v[204:207], v151 offset:54272
	ds_read_b128 v[208:211], v151 offset:55296
	ds_read_b128 v[212:215], v151 offset:56320
	global_load_lds_dwordx4 v[216:217], off
	v_lshl_add_u64 v[216:217], v[218:219], 0, s[88:89]
	s_add_i32 m0, s4, 0x2000
	s_add_i32 s4, s41, s53
	global_load_lds_dwordx4 v[216:217], off
	v_lshl_add_u64 v[216:217], v[220:221], 0, s[88:89]
	s_mov_b32 m0, s4
	s_nop 0
	global_load_lds_dwordx4 v[216:217], off
	v_lshl_add_u64 v[216:217], v[222:223], 0, s[88:89]
	s_add_i32 m0, s4, 0x2000
	s_nop 0
	global_load_lds_dwordx4 v[216:217], off
	s_mov_b32 m0, s68
	s_nop 0
	s_add_u32 s100, s34, 0x80
	s_addc_u32 s101, s35, 0
	global_load_lds_dwordx4 v136, s[100:101]
	s_mov_b32 m0, s69
	s_nop 0
	global_load_lds_dwordx4 v132, s[100:101]
	s_waitcnt vmcnt(8)
	s_waitcnt lgkmcnt(0)
	s_setprio 1
	s_barrier
	v_mfma_f32_16x16x32_bf16 v[62:65], v[152:155], v[184:187], v[62:65]
	v_mfma_f32_16x16x32_bf16 v[58:61], v[160:163], v[184:187], v[58:61]
	v_mfma_f32_16x16x32_bf16 v[54:57], v[152:155], v[192:195], v[54:57]
	v_mfma_f32_16x16x32_bf16 v[50:53], v[160:163], v[192:195], v[50:53]
	v_mfma_f32_16x16x32_bf16 v[38:41], v[152:155], v[200:203], v[38:41]
	v_mfma_f32_16x16x32_bf16 v[34:37], v[160:163], v[200:203], v[34:37]
	v_mfma_f32_16x16x32_bf16 v[22:25], v[152:155], v[208:211], v[22:25]
	v_mfma_f32_16x16x32_bf16 v[18:21], v[160:163], v[208:211], v[18:21]
	v_mfma_f32_16x16x32_bf16 v[62:65], v[156:159], v[188:191], v[62:65]
	v_mfma_f32_16x16x32_bf16 v[58:61], v[164:167], v[188:191], v[58:61]
	v_mfma_f32_16x16x32_bf16 v[54:57], v[156:159], v[196:199], v[54:57]
	v_mfma_f32_16x16x32_bf16 v[50:53], v[164:167], v[196:199], v[50:53]
	v_mfma_f32_16x16x32_bf16 v[38:41], v[156:159], v[204:207], v[38:41]
	v_mfma_f32_16x16x32_bf16 v[34:37], v[164:167], v[204:207], v[34:37]
	v_mfma_f32_16x16x32_bf16 v[22:25], v[156:159], v[212:215], v[22:25]
	v_mfma_f32_16x16x32_bf16 v[18:21], v[164:167], v[212:215], v[18:21]
	v_mfma_f32_16x16x32_bf16 v[46:49], v[168:171], v[184:187], v[46:49]
	v_mfma_f32_16x16x32_bf16 v[42:45], v[176:179], v[184:187], v[42:45]
	v_mfma_f32_16x16x32_bf16 v[30:33], v[168:171], v[192:195], v[30:33]
	v_mfma_f32_16x16x32_bf16 v[26:29], v[176:179], v[192:195], v[26:29]
	v_mfma_f32_16x16x32_bf16 v[14:17], v[168:171], v[200:203], v[14:17]
	v_mfma_f32_16x16x32_bf16 v[10:13], v[176:179], v[200:203], v[10:13]
	v_mfma_f32_16x16x32_bf16 v[6:9], v[168:171], v[208:211], v[6:9]
	v_mfma_f32_16x16x32_bf16 v[2:5], v[176:179], v[208:211], v[2:5]
	v_mfma_f32_16x16x32_bf16 v[46:49], v[172:175], v[188:191], v[46:49]
	v_mfma_f32_16x16x32_bf16 v[42:45], v[180:183], v[188:191], v[42:45]
	v_mfma_f32_16x16x32_bf16 v[30:33], v[172:175], v[196:199], v[30:33]
	v_mfma_f32_16x16x32_bf16 v[26:29], v[180:183], v[196:199], v[26:29]
	v_mfma_f32_16x16x32_bf16 v[14:17], v[172:175], v[204:207], v[14:17]
	v_mfma_f32_16x16x32_bf16 v[10:13], v[180:183], v[204:207], v[10:13]
	v_mfma_f32_16x16x32_bf16 v[6:9], v[172:175], v[212:215], v[6:9]
	v_mfma_f32_16x16x32_bf16 v[2:5], v[180:183], v[212:215], v[2:5]
	s_barrier
	s_setprio 0
	s_add_i32 s44, s44, 2
	s_add_u32 s8, s8, 0x100
	s_addc_u32 s9, s9, 0
	s_add_u32 s36, s36, 0x100
	s_addc_u32 s37, s37, 0
	s_cmp_gt_u32 s44, 5
	s_cbranch_scc0 .LBB0_674
	s_and_b64 vcc, exec, s[18:19]
	s_cbranch_vccz .LBB0_677
	s_barrier

; #define PG8_STAGE(bufoff, gbase, voff) do { _Pragma("unroll") for (int _i = 0; _i < 2; ++_i) \
;         __builtin_amdgcn_global_load_lds((const unsigned*)((const char*)(gbase) + (voff)[_i]), (PG8_LAS unsigned*)(lds + (bufoff) + ldsw + _i * 8192), 16, 0, 0); } while (0)
; #define PG8_LDA(dst, b, h) do { _Pragma("unroll") for (int m = 0; m < 4; ++m) _Pragma("unroll") for (int k = 0; k < 2; ++k) dst[m][k] = *(const PG8_LAS bf16x8*)(lds + PG8_SA(b, h) + aoff + m * 2048 + k * 1024); } while (0)
; #define PG8_LDB(dst, b, h) do { _Pragma("unroll") for (int n = 0; n < 2; ++n) _Pragma("unroll") for (int k = 0; k < 2; ++k) dst[n][k] = *(const PG8_LAS bf16x8*)(lds + PG8_SB(b, h) + boff + n * 2048 + k * 1024); } while (0)
; #define PG8_MMA(ai, bj, At, Bt) do { __builtin_amdgcn_s_setprio(1); _Pragma("unroll") for (int m = 0; m < 4; ++m) _Pragma("unroll") for (int n = 0; n < 2; ++n) _Pragma("unroll") for (int k = 0; k < 2; ++k) \
;         acc[ai][bj][m][n] = __builtin_amdgcn_mfma_f32_16x16x32_bf16(Bt[n][k], At[m][k], acc[ai][bj][m][n], 0, 0, 0); __builtin_amdgcn_s_setprio(0); } while (0)
; #define PG8_WAIT_V(n) asm volatile("s_waitcnt vmcnt(" #n ")" ::: "memory")
; #define PG8_WAIT_L(n) asm volatile("s_waitcnt lgkmcnt(" #n ")" ::: "memory")
; #define PG8_BAR __builtin_amdgcn_s_barrier()
; #define PG8_SCHED __builtin_amdgcn_sched_barrier(0)
; template <class Prob, class Epi, class Sched>
; __device__ __forceinline__ void gemm_phase(PG8_LAS unsigned char* lds, const Prob g, const Sched& S, const Epi& E) {
;     ...
;             const bool last = (t == nt - 2);
;             const char* a1 = cA + (size_t)(t + 1) * kstep;
;             const char* a2 = last ? nA : cA + (size_t)(t + 2) * kstep; const char* b2 = last ? nB : cB + (size_t)(t + 2) * kstep;
;             const char* a3 = a2 + kstep; const char* b3 = b2 + kstep;
;             PG8_LDB(B0, 0, 0); PG8_LDB(B1, 0, 1); PG8_SCHED; PG8_LDA(At, 0, 0); PG8_STAGE(PG8_SA(1, 1), a1 + hstepA, voffA);
;             PG8_WAIT_V(8); PG8_WAIT_L(0); PG8_BAR; PG8_MMA(0, 0, At, B0); PG8_MMA(0, 1, At, B1); PG8_BAR; PG8_SCHED;
;             PG8_LDA(At, 0, 1); PG8_STAGE(PG8_SB(0, 0), b2, voffB); PG8_STAGE(PG8_SB(0, 1), b2 + hstepB, voffB); PG8_STAGE(PG8_SA(0, 0), a2, voffA);
;             PG8_WAIT_V(8); PG8_WAIT_L(0); PG8_BAR; PG8_MMA(1, 0, At, B0); PG8_MMA(1, 1, At, B1); PG8_BAR; PG8_SCHED;
.LBB0_694:
	s_add_u32 s4, s26, 0xfff80080
	s_addc_u32 s5, s27, -1
	s_add_i32 s40, 0, 0x10000
	s_cmp_eq_u32 s58, 28
	s_cselect_b32 s31, s21, s5
	s_cselect_b32 s30, s56, s4
	v_add_u32_e32 v1, s40, v175
	s_cselect_b32 s29, s19, s57
	s_cselect_b32 s28, s44, s45
	s_add_i32 s41, 0, 0x14000
	ds_read_b128 v[130:133], v1
	ds_read_b128 v[134:137], v1 offset:1024
	ds_read_b128 v[138:141], v1 offset:2048
	ds_read_b128 v[142:145], v1 offset:3072
	v_add_u32_e32 v1, s41, v175
	ds_read_b128 v[146:149], v1
	ds_read_b128 v[150:153], v1 offset:1024
	ds_read_b128 v[164:167], v1 offset:2048
	ds_read_b128 v[168:171], v1 offset:3072
	s_add_i32 m0, s37, 0xc000
	ds_read_b128 v[178:181], v177
	ds_read_b128 v[182:185], v177 offset:1024
	ds_read_b128 v[186:189], v177 offset:2048
	ds_read_b128 v[190:193], v177 offset:3072
	ds_read_b128 v[194:197], v177 offset:4096
	ds_read_b128 v[198:201], v177 offset:5120
	ds_read_b128 v[202:205], v177 offset:6144
	ds_read_b128 v[206:209], v177 offset:7168
	global_load_lds_dwordx4 v160, s[26:27]
	s_add_i32 m0, s37, 0xe000
	s_nop 0
	global_load_lds_dwordx4 v162, s[26:27]
	s_waitcnt vmcnt(8)
	s_waitcnt lgkmcnt(0)
	s_setprio 1
	s_barrier
	v_mfma_f32_16x16x32_bf16 v[126:129], v[130:133], v[178:181], v[126:129]
	v_mfma_f32_16x16x32_bf16 v[122:125], v[138:141], v[178:181], v[122:125]
	v_mfma_f32_16x16x32_bf16 v[110:113], v[130:133], v[186:189], v[110:113]
	v_mfma_f32_16x16x32_bf16 v[106:109], v[138:141], v[186:189], v[106:109]
	v_mfma_f32_16x16x32_bf16 v[98:101], v[130:133], v[194:197], v[98:101]
	v_mfma_f32_16x16x32_bf16 v[90:93], v[138:141], v[194:197], v[90:93]
	v_mfma_f32_16x16x32_bf16 v[82:85], v[130:133], v[202:205], v[82:85]
	v_mfma_f32_16x16x32_bf16 v[74:77], v[138:141], v[202:205], v[74:77]
	v_mfma_f32_16x16x32_bf16 v[126:129], v[134:137], v[182:185], v[126:129]
	v_mfma_f32_16x16x32_bf16 v[122:125], v[142:145], v[182:185], v[122:125]
	v_mfma_f32_16x16x32_bf16 v[110:113], v[134:137], v[190:193], v[110:113]
	v_mfma_f32_16x16x32_bf16 v[106:109], v[142:145], v[190:193], v[106:109]
	v_mfma_f32_16x16x32_bf16 v[98:101], v[134:137], v[198:201], v[98:101]
	v_mfma_f32_16x16x32_bf16 v[90:93], v[142:145], v[198:201], v[90:93]
	v_mfma_f32_16x16x32_bf16 v[82:85], v[134:137], v[206:209], v[82:85]
	v_mfma_f32_16x16x32_bf16 v[74:77], v[142:145], v[206:209], v[74:77]
	v_mfma_f32_16x16x32_bf16 v[118:121], v[146:149], v[178:181], v[118:121]
	v_mfma_f32_16x16x32_bf16 v[114:117], v[164:167], v[178:181], v[114:117]
	v_mfma_f32_16x16x32_bf16 v[102:105], v[146:149], v[186:189], v[102:105]
	v_mfma_f32_16x16x32_bf16 v[94:97], v[164:167], v[186:189], v[94:97]
	v_mfma_f32_16x16x32_bf16 v[86:89], v[146:149], v[194:197], v[86:89]
	v_mfma_f32_16x16x32_bf16 v[78:81], v[164:167], v[194:197], v[78:81]
	v_mfma_f32_16x16x32_bf16 v[70:73], v[146:149], v[202:205], v[70:73]
	v_mfma_f32_16x16x32_bf16 v[66:69], v[164:167], v[202:205], v[66:69]
	v_mfma_f32_16x16x32_bf16 v[118:121], v[150:153], v[182:185], v[118:121]
	v_mfma_f32_16x16x32_bf16 v[114:117], v[168:171], v[182:185], v[114:117]
	v_mfma_f32_16x16x32_bf16 v[102:105], v[150:153], v[190:193], v[102:105]
	v_mfma_f32_16x16x32_bf16 v[94:97], v[168:171], v[190:193], v[94:97]
	v_mfma_f32_16x16x32_bf16 v[86:89], v[150:153], v[198:201], v[86:89]
	v_mfma_f32_16x16x32_bf16 v[78:81], v[168:171], v[198:201], v[78:81]
	v_mfma_f32_16x16x32_bf16 v[70:73], v[150:153], v[206:209], v[70:73]
	v_mfma_f32_16x16x32_bf16 v[66:69], v[168:171], v[206:209], v[66:69]
	s_barrier
	s_setprio 0
	s_add_i32 s4, s40, s36
	s_mov_b32 m0, s4
	ds_read_b128 v[178:181], v177 offset:16384
	ds_read_b128 v[182:185], v177 offset:17408
	ds_read_b128 v[186:189], v177 offset:18432
	ds_read_b128 v[190:193], v177 offset:19456
	ds_read_b128 v[194:197], v177 offset:20480
	ds_read_b128 v[198:201], v177 offset:21504
	ds_read_b128 v[202:205], v177 offset:22528
	ds_read_b128 v[206:209], v177 offset:23552
	global_load_lds_dwordx4 v226, s[28:29]
	s_add_i32 m0, s4, 0x2000
	s_add_u32 s4, s28, 0x80000
	s_addc_u32 s5, s29, 0
	s_add_i32 s40, s41, s36
	global_load_lds_dwordx4 v154, s[28:29]
	s_mov_b32 m0, s40
	s_nop 0
	global_load_lds_dwordx4 v226, s[4:5]
	s_add_i32 m0, s40, 0x2000
	s_nop 0
	global_load_lds_dwordx4 v154, s[4:5]
	s_mov_b32 m0, s37
	s_nop 0
	global_load_lds_dwordx4 v158, s[30:31]
	s_mov_b32 m0, s38
	s_nop 0
	global_load_lds_dwordx4 v156, s[30:31]
	s_waitcnt vmcnt(8)
	s_waitcnt lgkmcnt(0)
	s_setprio 1
	s_barrier
	v_mfma_f32_16x16x32_bf16 v[62:65], v[130:133], v[178:181], v[62:65]
	v_mfma_f32_16x16x32_bf16 v[58:61], v[138:141], v[178:181], v[58:61]
	v_mfma_f32_16x16x32_bf16 v[50:53], v[130:133], v[186:189], v[50:53]
	v_mfma_f32_16x16x32_bf16 v[42:45], v[138:141], v[186:189], v[42:45]
	v_mfma_f32_16x16x32_bf16 v[34:37], v[130:133], v[194:197], v[34:37]
	v_mfma_f32_16x16x32_bf16 v[26:29], v[138:141], v[194:197], v[26:29]
	v_mfma_f32_16x16x32_bf16 v[18:21], v[130:133], v[202:205], v[18:21]
	v_mfma_f32_16x16x32_bf16 v[10:13], v[138:141], v[202:205], v[10:13]
	v_mfma_f32_16x16x32_bf16 v[62:65], v[134:137], v[182:185], v[62:65]
	v_mfma_f32_16x16x32_bf16 v[58:61], v[142:145], v[182:185], v[58:61]
	v_mfma_f32_16x16x32_bf16 v[50:53], v[134:137], v[190:193], v[50:53]
	v_mfma_f32_16x16x32_bf16 v[42:45], v[142:145], v[190:193], v[42:45]
	v_mfma_f32_16x16x32_bf16 v[34:37], v[134:137], v[198:201], v[34:37]
	v_mfma_f32_16x16x32_bf16 v[26:29], v[142:145], v[198:201], v[26:29]
	v_mfma_f32_16x16x32_bf16 v[18:21], v[134:137], v[206:209], v[18:21]
	v_mfma_f32_16x16x32_bf16 v[10:13], v[142:145], v[206:209], v[10:13]
	v_mfma_f32_16x16x32_bf16 v[54:57], v[146:149], v[178:181], v[54:57]
	v_mfma_f32_16x16x32_bf16 v[46:49], v[164:167], v[178:181], v[46:49]
	v_mfma_f32_16x16x32_bf16 v[38:41], v[146:149], v[186:189], v[38:41]
	v_mfma_f32_16x16x32_bf16 v[30:33], v[164:167], v[186:189], v[30:33]
	v_mfma_f32_16x16x32_bf16 v[22:25], v[146:149], v[194:197], v[22:25]
	v_mfma_f32_16x16x32_bf16 v[14:17], v[164:167], v[194:197], v[14:17]
	v_mfma_f32_16x16x32_bf16 v[6:9], v[146:149], v[202:205], v[6:9]
	v_mfma_f32_16x16x32_bf16 v[2:5], v[164:167], v[202:205], v[2:5]
	v_mfma_f32_16x16x32_bf16 v[54:57], v[150:153], v[182:185], v[54:57]
	v_mfma_f32_16x16x32_bf16 v[46:49], v[168:171], v[182:185], v[46:49]
	v_mfma_f32_16x16x32_bf16 v[38:41], v[150:153], v[190:193], v[38:41]
	v_mfma_f32_16x16x32_bf16 v[30:33], v[168:171], v[190:193], v[30:33]
	v_mfma_f32_16x16x32_bf16 v[22:25], v[150:153], v[198:201], v[22:25]
	v_mfma_f32_16x16x32_bf16 v[14:17], v[168:171], v[198:201], v[14:17]
	v_mfma_f32_16x16x32_bf16 v[6:9], v[150:153], v[206:209], v[6:9]
	v_mfma_f32_16x16x32_bf16 v[2:5], v[168:171], v[206:209], v[2:5]
	s_barrier
; #define PG8_STAGE(bufoff, gbase, voff) do { _Pragma("unroll") for (int _i = 0; _i < 2; ++_i) \
;         __builtin_amdgcn_global_load_lds((const unsigned*)((const char*)(gbase) + (voff)[_i]), (PG8_LAS unsigned*)(lds + (bufoff) + ldsw + _i * 8192), 16, 0, 0); } while (0)
; #define PG8_LDA(dst, b, h) do { _Pragma("unroll") for (int m = 0; m < 4; ++m) _Pragma("unroll") for (int k = 0; k < 2; ++k) dst[m][k] = *(const PG8_LAS bf16x8*)(lds + PG8_SA(b, h) + aoff + m * 2048 + k * 1024); } while (0)
; #define PG8_LDB(dst, b, h) do { _Pragma("unroll") for (int n = 0; n < 2; ++n) _Pragma("unroll") for (int k = 0; k < 2; ++k) dst[n][k] = *(const PG8_LAS bf16x8*)(lds + PG8_SB(b, h) + boff + n * 2048 + k * 1024); } while (0)
; #define PG8_MMA(ai, bj, At, Bt) do { __builtin_amdgcn_s_setprio(1); _Pragma("unroll") for (int m = 0; m < 4; ++m) _Pragma("unroll") for (int n = 0; n < 2; ++n) _Pragma("unroll") for (int k = 0; k < 2; ++k) \
;         acc[ai][bj][m][n] = __builtin_amdgcn_mfma_f32_16x16x32_bf16(Bt[n][k], At[m][k], acc[ai][bj][m][n], 0, 0, 0); __builtin_amdgcn_s_setprio(0); } while (0)
; #define PG8_WAIT_V(n) asm volatile("s_waitcnt vmcnt(" #n ")" ::: "memory")
; #define PG8_WAIT_L(n) asm volatile("s_waitcnt lgkmcnt(" #n ")" ::: "memory")
; #define PG8_BAR __builtin_amdgcn_s_barrier()
; #define PG8_SCHED __builtin_amdgcn_sched_barrier(0)
; template <class Prob, class Epi, class Sched>
; __device__ __forceinline__ void gemm_phase(PG8_LAS unsigned char* lds, const Prob g, const Sched& S, const Epi& E) {
;     ...
;             PG8_LDB(B0, 1, 0); PG8_LDB(B1, 1, 1); PG8_SCHED; PG8_LDA(At, 1, 0); PG8_STAGE(PG8_SA(0, 1), a2 + hstepA, voffA);
;             PG8_WAIT_V(8); PG8_WAIT_L(0); PG8_BAR; PG8_MMA(0, 0, At, B0); PG8_MMA(0, 1, At, B1); PG8_BAR; PG8_SCHED;
;             PG8_LDA(At, 1, 1); PG8_STAGE(PG8_SB(1, 0), b3, voffB); PG8_STAGE(PG8_SB(1, 1), b3 + hstepB, voffB); PG8_STAGE(PG8_SA(1, 0), a3, voffA);
;             PG8_WAIT_V(8); PG8_WAIT_L(0); PG8_BAR; PG8_MMA(1, 0, At, B0); PG8_MMA(1, 1, At, B1); PG8_BAR; PG8_SCHED;
;         }
;         if (wr == 0) PG8_BAR;
	s_setprio 0
	s_add_i32 s40, 0, 0x18000
	v_add_u32_e32 v1, s40, v175
	s_add_i32 s41, 0, 0x1c000
	ds_read_b128 v[130:133], v1
	ds_read_b128 v[134:137], v1 offset:1024
	ds_read_b128 v[138:141], v1 offset:2048
	ds_read_b128 v[142:145], v1 offset:3072
	v_add_u32_e32 v1, s41, v175
	ds_read_b128 v[146:149], v1
	ds_read_b128 v[150:153], v1 offset:1024
	ds_read_b128 v[164:167], v1 offset:2048
	ds_read_b128 v[168:171], v1 offset:3072
	s_add_u32 s4, s30, 0x80000
	s_addc_u32 s5, s31, 0
	s_mov_b32 m0, s39
	ds_read_b128 v[178:181], v177 offset:32768
	ds_read_b128 v[182:185], v177 offset:33792
	ds_read_b128 v[186:189], v177 offset:34816
	ds_read_b128 v[190:193], v177 offset:35840
	ds_read_b128 v[194:197], v177 offset:36864
	ds_read_b128 v[198:201], v177 offset:37888
	ds_read_b128 v[202:205], v177 offset:38912
	ds_read_b128 v[206:209], v177 offset:39936
	global_load_lds_dwordx4 v158, s[4:5]
	s_mov_b32 m0, s42
	s_nop 0
	global_load_lds_dwordx4 v156, s[4:5]
	s_waitcnt vmcnt(8)
	s_waitcnt lgkmcnt(0)
	s_setprio 1
	s_barrier
	v_mfma_f32_16x16x32_bf16 v[126:129], v[130:133], v[178:181], v[126:129]
	v_mfma_f32_16x16x32_bf16 v[122:125], v[138:141], v[178:181], v[122:125]
	v_mfma_f32_16x16x32_bf16 v[110:113], v[130:133], v[186:189], v[110:113]
	v_mfma_f32_16x16x32_bf16 v[106:109], v[138:141], v[186:189], v[106:109]
	v_mfma_f32_16x16x32_bf16 v[98:101], v[130:133], v[194:197], v[98:101]
	v_mfma_f32_16x16x32_bf16 v[90:93], v[138:141], v[194:197], v[90:93]
	v_mfma_f32_16x16x32_bf16 v[82:85], v[130:133], v[202:205], v[82:85]
	v_mfma_f32_16x16x32_bf16 v[74:77], v[138:141], v[202:205], v[74:77]
	v_mfma_f32_16x16x32_bf16 v[126:129], v[134:137], v[182:185], v[126:129]
	v_mfma_f32_16x16x32_bf16 v[122:125], v[142:145], v[182:185], v[122:125]
	v_mfma_f32_16x16x32_bf16 v[110:113], v[134:137], v[190:193], v[110:113]
	v_mfma_f32_16x16x32_bf16 v[106:109], v[142:145], v[190:193], v[106:109]
	v_mfma_f32_16x16x32_bf16 v[98:101], v[134:137], v[198:201], v[98:101]
	v_mfma_f32_16x16x32_bf16 v[90:93], v[142:145], v[198:201], v[90:93]
	v_mfma_f32_16x16x32_bf16 v[82:85], v[134:137], v[206:209], v[82:85]
	v_mfma_f32_16x16x32_bf16 v[74:77], v[142:145], v[206:209], v[74:77]
	v_mfma_f32_16x16x32_bf16 v[118:121], v[146:149], v[178:181], v[118:121]
	v_mfma_f32_16x16x32_bf16 v[114:117], v[164:167], v[178:181], v[114:117]
	v_mfma_f32_16x16x32_bf16 v[102:105], v[146:149], v[186:189], v[102:105]
	v_mfma_f32_16x16x32_bf16 v[94:97], v[164:167], v[186:189], v[94:97]
	v_mfma_f32_16x16x32_bf16 v[86:89], v[146:149], v[194:197], v[86:89]
	v_mfma_f32_16x16x32_bf16 v[78:81], v[164:167], v[194:197], v[78:81]
	v_mfma_f32_16x16x32_bf16 v[70:73], v[146:149], v[202:205], v[70:73]
	v_mfma_f32_16x16x32_bf16 v[66:69], v[164:167], v[202:205], v[66:69]
	v_mfma_f32_16x16x32_bf16 v[118:121], v[150:153], v[182:185], v[118:121]
	v_mfma_f32_16x16x32_bf16 v[114:117], v[168:171], v[182:185], v[114:117]
	v_mfma_f32_16x16x32_bf16 v[102:105], v[150:153], v[190:193], v[102:105]
	v_mfma_f32_16x16x32_bf16 v[94:97], v[168:171], v[190:193], v[94:97]
	v_mfma_f32_16x16x32_bf16 v[86:89], v[150:153], v[198:201], v[86:89]
	v_mfma_f32_16x16x32_bf16 v[78:81], v[168:171], v[198:201], v[78:81]
	v_mfma_f32_16x16x32_bf16 v[70:73], v[150:153], v[206:209], v[70:73]
	v_mfma_f32_16x16x32_bf16 v[66:69], v[168:171], v[206:209], v[66:69]
	s_barrier
	s_setprio 0
	s_add_i32 s4, s40, s36
	s_mov_b32 m0, s4
	ds_read_b128 v[178:181], v177 offset:49152
	ds_read_b128 v[182:185], v177 offset:50176
	ds_read_b128 v[186:189], v177 offset:51200
	ds_read_b128 v[190:193], v177 offset:52224
	ds_read_b128 v[194:197], v177 offset:53248
	ds_read_b128 v[198:201], v177 offset:54272
	ds_read_b128 v[202:205], v177 offset:55296
	ds_read_b128 v[206:209], v177 offset:56320
	s_add_u32 s100, s28, 0x80
	s_addc_u32 s101, s29, 0
	global_load_lds_dwordx4 v226, s[100:101]
	s_add_i32 m0, s4, 0x2000
	s_add_u32 s4, s28, 0x80080
	s_addc_u32 s5, s29, 0
	s_add_i32 s28, s41, s36
	global_load_lds_dwordx4 v154, s[100:101]
	s_mov_b32 m0, s28
	s_nop 0
	global_load_lds_dwordx4 v226, s[4:5]
	s_add_i32 m0, s28, 0x2000
	s_nop 0
	global_load_lds_dwordx4 v154, s[4:5]
	s_mov_b32 m0, s43
	s_nop 0
	s_add_u32 s100, s30, 0x80
	s_addc_u32 s101, s31, 0
	global_load_lds_dwordx4 v158, s[100:101]
	s_mov_b32 m0, s51
	s_nop 0
	global_load_lds_dwordx4 v156, s[100:101]
	s_waitcnt vmcnt(8)
	s_waitcnt lgkmcnt(0)
	s_setprio 1
	s_barrier
	v_mfma_f32_16x16x32_bf16 v[62:65], v[130:133], v[178:181], v[62:65]
	v_mfma_f32_16x16x32_bf16 v[58:61], v[138:141], v[178:181], v[58:61]
	v_mfma_f32_16x16x32_bf16 v[50:53], v[130:133], v[186:189], v[50:53]
	v_mfma_f32_16x16x32_bf16 v[42:45], v[138:141], v[186:189], v[42:45]
	v_mfma_f32_16x16x32_bf16 v[34:37], v[130:133], v[194:197], v[34:37]
	v_mfma_f32_16x16x32_bf16 v[26:29], v[138:141], v[194:197], v[26:29]
	v_mfma_f32_16x16x32_bf16 v[18:21], v[130:133], v[202:205], v[18:21]
	v_mfma_f32_16x16x32_bf16 v[10:13], v[138:141], v[202:205], v[10:13]
	v_mfma_f32_16x16x32_bf16 v[62:65], v[134:137], v[182:185], v[62:65]
	v_mfma_f32_16x16x32_bf16 v[58:61], v[142:145], v[182:185], v[58:61]
	v_mfma_f32_16x16x32_bf16 v[50:53], v[134:137], v[190:193], v[50:53]
	v_mfma_f32_16x16x32_bf16 v[42:45], v[142:145], v[190:193], v[42:45]
	v_mfma_f32_16x16x32_bf16 v[34:37], v[134:137], v[198:201], v[34:37]
	v_mfma_f32_16x16x32_bf16 v[26:29], v[142:145], v[198:201], v[26:29]
	v_mfma_f32_16x16x32_bf16 v[18:21], v[134:137], v[206:209], v[18:21]
	v_mfma_f32_16x16x32_bf16 v[10:13], v[142:145], v[206:209], v[10:13]
	v_mfma_f32_16x16x32_bf16 v[54:57], v[146:149], v[178:181], v[54:57]
	v_mfma_f32_16x16x32_bf16 v[46:49], v[164:167], v[178:181], v[46:49]
	v_mfma_f32_16x16x32_bf16 v[38:41], v[146:149], v[186:189], v[38:41]
	v_mfma_f32_16x16x32_bf16 v[30:33], v[164:167], v[186:189], v[30:33]
	v_mfma_f32_16x16x32_bf16 v[22:25], v[146:149], v[194:197], v[22:25]
	v_mfma_f32_16x16x32_bf16 v[14:17], v[164:167], v[194:197], v[14:17]
	v_mfma_f32_16x16x32_bf16 v[6:9], v[146:149], v[202:205], v[6:9]
	v_mfma_f32_16x16x32_bf16 v[2:5], v[164:167], v[202:205], v[2:5]
	v_mfma_f32_16x16x32_bf16 v[54:57], v[150:153], v[182:185], v[54:57]
	v_mfma_f32_16x16x32_bf16 v[46:49], v[168:171], v[182:185], v[46:49]
	v_mfma_f32_16x16x32_bf16 v[38:41], v[150:153], v[190:193], v[38:41]
	v_mfma_f32_16x16x32_bf16 v[30:33], v[168:171], v[190:193], v[30:33]
	v_mfma_f32_16x16x32_bf16 v[22:25], v[150:153], v[198:201], v[22:25]
	v_mfma_f32_16x16x32_bf16 v[14:17], v[168:171], v[198:201], v[14:17]
	v_mfma_f32_16x16x32_bf16 v[6:9], v[150:153], v[206:209], v[6:9]
	v_mfma_f32_16x16x32_bf16 v[2:5], v[168:171], v[206:209], v[2:5]
	s_barrier
	s_setprio 0
	s_add_i32 s58, s58, 2
	s_add_u32 s26, s26, 0x100
	s_addc_u32 s27, s27, 0
	s_add_u32 s45, s45, 0x100
	s_addc_u32 s57, s57, 0
	s_cmp_gt_u32 s58, 29
	s_cbranch_scc0 .LBB0_694
	s_and_b64 vcc, exec, s[16:17]
	s_cbranch_vccz .LBB0_697
	s_barrier

; #define PG8_STAGE(bufoff, gbase, voff) do { _Pragma("unroll") for (int _i = 0; _i < 2; ++_i) \
;         __builtin_amdgcn_global_load_lds((const unsigned*)((const char*)(gbase) + (voff)[_i]), (PG8_LAS unsigned*)(lds + (bufoff) + ldsw + _i * 8192), 16, 0, 0); } while (0)
; #define PG8_LDA(dst, b, h) do { _Pragma("unroll") for (int m = 0; m < 4; ++m) _Pragma("unroll") for (int k = 0; k < 2; ++k) dst[m][k] = *(const PG8_LAS bf16x8*)(lds + PG8_SA(b, h) + aoff + m * 2048 + k * 1024); } while (0)
; #define PG8_LDB(dst, b, h) do { _Pragma("unroll") for (int n = 0; n < 2; ++n) _Pragma("unroll") for (int k = 0; k < 2; ++k) dst[n][k] = *(const PG8_LAS bf16x8*)(lds + PG8_SB(b, h) + boff + n * 2048 + k * 1024); } while (0)
; #define PG8_MMA(ai, bj, At, Bt) do { __builtin_amdgcn_s_setprio(1); _Pragma("unroll") for (int m = 0; m < 4; ++m) _Pragma("unroll") for (int n = 0; n < 2; ++n) _Pragma("unroll") for (int k = 0; k < 2; ++k) \
;         acc[ai][bj][m][n] = __builtin_amdgcn_mfma_f32_16x16x32_bf16(Bt[n][k], At[m][k], acc[ai][bj][m][n], 0, 0, 0); __builtin_amdgcn_s_setprio(0); } while (0)
; #define PG8_WAIT_V(n) asm volatile("s_waitcnt vmcnt(" #n ")" ::: "memory")
; #define PG8_WAIT_L(n) asm volatile("s_waitcnt lgkmcnt(" #n ")" ::: "memory")
; #define PG8_BAR __builtin_amdgcn_s_barrier()
; #define PG8_SCHED __builtin_amdgcn_sched_barrier(0)
; template <class Prob, class Epi, class Sched>
; __device__ __forceinline__ void gemm_phase(PG8_LAS unsigned char* lds, const Prob g, const Sched& S, const Epi& E) {
;     ...
;             const bool last = (t == nt - 2);
;             const char* a1 = cA + (size_t)(t + 1) * kstep;
;             const char* a2 = last ? nA : cA + (size_t)(t + 2) * kstep; const char* b2 = last ? nB : cB + (size_t)(t + 2) * kstep;
;             const char* a3 = a2 + kstep; const char* b3 = b2 + kstep;
;             PG8_LDB(B0, 0, 0); PG8_LDB(B1, 0, 1); PG8_SCHED; PG8_LDA(At, 0, 0); PG8_STAGE(PG8_SA(1, 1), a1 + hstepA, voffA);
;             PG8_WAIT_V(8); PG8_WAIT_L(0); PG8_BAR; PG8_MMA(0, 0, At, B0); PG8_MMA(0, 1, At, B1); PG8_BAR; PG8_SCHED;
;             PG8_LDA(At, 0, 1); PG8_STAGE(PG8_SB(0, 0), b2, voffB); PG8_STAGE(PG8_SB(0, 1), b2 + hstepB, voffB); PG8_STAGE(PG8_SA(0, 0), a2, voffA);
;             PG8_WAIT_V(8); PG8_WAIT_L(0); PG8_BAR; PG8_MMA(1, 0, At, B0); PG8_MMA(1, 1, At, B1); PG8_BAR; PG8_SCHED;
.LBB0_758:
	s_add_u32 s4, s26, 0xfffc0080
	s_addc_u32 s5, s27, -1
	s_add_i32 s40, 0, 0x10000
	s_cmp_eq_u32 s58, 12
	s_cselect_b32 s31, s21, s5
	s_cselect_b32 s30, s56, s4
	v_add_u32_e32 v1, s40, v163
	s_cselect_b32 s29, s19, s57
	s_cselect_b32 s28, s44, s45
	s_add_i32 s41, 0, 0x14000
	ds_read_b128 v[130:133], v1
	ds_read_b128 v[134:137], v1 offset:1024
	ds_read_b128 v[138:141], v1 offset:2048
	ds_read_b128 v[142:145], v1 offset:3072
	v_add_u32_e32 v1, s41, v163
	ds_read_b128 v[156:159], v1
	ds_read_b128 v[166:169], v1 offset:1024
	ds_read_b128 v[170:173], v1 offset:2048
	ds_read_b128 v[174:177], v1 offset:3072
	s_add_i32 m0, s37, 0xc000
	ds_read_b128 v[178:181], v165
	ds_read_b128 v[182:185], v165 offset:1024
	ds_read_b128 v[186:189], v165 offset:2048
	ds_read_b128 v[190:193], v165 offset:3072
	ds_read_b128 v[194:197], v165 offset:4096
	ds_read_b128 v[198:201], v165 offset:5120
	ds_read_b128 v[202:205], v165 offset:6144
	ds_read_b128 v[206:209], v165 offset:7168
	global_load_lds_dwordx4 v152, s[26:27]
	s_add_i32 m0, s37, 0xe000
	s_nop 0
	global_load_lds_dwordx4 v154, s[26:27]
	s_waitcnt vmcnt(8)
	s_waitcnt lgkmcnt(0)
	s_setprio 1
	s_barrier
	v_mfma_f32_16x16x32_bf16 v[126:129], v[130:133], v[178:181], v[126:129]
	v_mfma_f32_16x16x32_bf16 v[122:125], v[138:141], v[178:181], v[122:125]
	v_mfma_f32_16x16x32_bf16 v[110:113], v[130:133], v[186:189], v[110:113]
	v_mfma_f32_16x16x32_bf16 v[106:109], v[138:141], v[186:189], v[106:109]
	v_mfma_f32_16x16x32_bf16 v[94:97], v[130:133], v[194:197], v[94:97]
	v_mfma_f32_16x16x32_bf16 v[90:93], v[138:141], v[194:197], v[90:93]
	v_mfma_f32_16x16x32_bf16 v[78:81], v[130:133], v[202:205], v[78:81]
	v_mfma_f32_16x16x32_bf16 v[74:77], v[138:141], v[202:205], v[74:77]
	v_mfma_f32_16x16x32_bf16 v[126:129], v[134:137], v[182:185], v[126:129]
	v_mfma_f32_16x16x32_bf16 v[122:125], v[142:145], v[182:185], v[122:125]
	v_mfma_f32_16x16x32_bf16 v[110:113], v[134:137], v[190:193], v[110:113]
	v_mfma_f32_16x16x32_bf16 v[106:109], v[142:145], v[190:193], v[106:109]
	v_mfma_f32_16x16x32_bf16 v[94:97], v[134:137], v[198:201], v[94:97]
	v_mfma_f32_16x16x32_bf16 v[90:93], v[142:145], v[198:201], v[90:93]
	v_mfma_f32_16x16x32_bf16 v[78:81], v[134:137], v[206:209], v[78:81]
	v_mfma_f32_16x16x32_bf16 v[74:77], v[142:145], v[206:209], v[74:77]
	v_mfma_f32_16x16x32_bf16 v[118:121], v[156:159], v[178:181], v[118:121]
	v_mfma_f32_16x16x32_bf16 v[114:117], v[170:173], v[178:181], v[114:117]
	v_mfma_f32_16x16x32_bf16 v[102:105], v[156:159], v[186:189], v[102:105]
	v_mfma_f32_16x16x32_bf16 v[98:101], v[170:173], v[186:189], v[98:101]
	v_mfma_f32_16x16x32_bf16 v[86:89], v[156:159], v[194:197], v[86:89]
	v_mfma_f32_16x16x32_bf16 v[82:85], v[170:173], v[194:197], v[82:85]
	v_mfma_f32_16x16x32_bf16 v[70:73], v[156:159], v[202:205], v[70:73]
	v_mfma_f32_16x16x32_bf16 v[66:69], v[170:173], v[202:205], v[66:69]
	v_mfma_f32_16x16x32_bf16 v[118:121], v[166:169], v[182:185], v[118:121]
	v_mfma_f32_16x16x32_bf16 v[114:117], v[174:177], v[182:185], v[114:117]
	v_mfma_f32_16x16x32_bf16 v[102:105], v[166:169], v[190:193], v[102:105]
	v_mfma_f32_16x16x32_bf16 v[98:101], v[174:177], v[190:193], v[98:101]
	v_mfma_f32_16x16x32_bf16 v[86:89], v[166:169], v[198:201], v[86:89]
	v_mfma_f32_16x16x32_bf16 v[82:85], v[174:177], v[198:201], v[82:85]
	v_mfma_f32_16x16x32_bf16 v[70:73], v[166:169], v[206:209], v[70:73]
	v_mfma_f32_16x16x32_bf16 v[66:69], v[174:177], v[206:209], v[66:69]
	s_barrier
	s_setprio 0
	s_add_i32 s4, s40, s36
	s_mov_b32 m0, s4
	ds_read_b128 v[178:181], v165 offset:16384
	ds_read_b128 v[182:185], v165 offset:17408
	ds_read_b128 v[186:189], v165 offset:18432
	ds_read_b128 v[190:193], v165 offset:19456
	ds_read_b128 v[194:197], v165 offset:20480
	ds_read_b128 v[198:201], v165 offset:21504
	ds_read_b128 v[202:205], v165 offset:22528
	ds_read_b128 v[206:209], v165 offset:23552
	global_load_lds_dwordx4 v226, s[28:29]
	s_add_i32 m0, s4, 0x2000
	s_add_u32 s4, s28, 0x40000
	s_addc_u32 s5, s29, 0
	s_add_i32 s40, s41, s36
	global_load_lds_dwordx4 v146, s[28:29]
	s_mov_b32 m0, s40
	s_nop 0
	global_load_lds_dwordx4 v226, s[4:5]
	s_add_i32 m0, s40, 0x2000
	s_nop 0
	global_load_lds_dwordx4 v146, s[4:5]
	s_mov_b32 m0, s37
	s_nop 0
	global_load_lds_dwordx4 v150, s[30:31]
	s_mov_b32 m0, s38
	s_nop 0
	global_load_lds_dwordx4 v148, s[30:31]
	s_waitcnt vmcnt(8)
	s_waitcnt lgkmcnt(0)
	s_setprio 1
	s_barrier
	v_mfma_f32_16x16x32_bf16 v[62:65], v[130:133], v[178:181], v[62:65]
	v_mfma_f32_16x16x32_bf16 v[58:61], v[138:141], v[178:181], v[58:61]
	v_mfma_f32_16x16x32_bf16 v[46:49], v[130:133], v[186:189], v[46:49]
	v_mfma_f32_16x16x32_bf16 v[42:45], v[138:141], v[186:189], v[42:45]
	v_mfma_f32_16x16x32_bf16 v[30:33], v[130:133], v[194:197], v[30:33]
	v_mfma_f32_16x16x32_bf16 v[26:29], v[138:141], v[194:197], v[26:29]
	v_mfma_f32_16x16x32_bf16 v[14:17], v[130:133], v[202:205], v[14:17]
	v_mfma_f32_16x16x32_bf16 v[10:13], v[138:141], v[202:205], v[10:13]
	v_mfma_f32_16x16x32_bf16 v[62:65], v[134:137], v[182:185], v[62:65]
	v_mfma_f32_16x16x32_bf16 v[58:61], v[142:145], v[182:185], v[58:61]
	v_mfma_f32_16x16x32_bf16 v[46:49], v[134:137], v[190:193], v[46:49]
	v_mfma_f32_16x16x32_bf16 v[42:45], v[142:145], v[190:193], v[42:45]
	v_mfma_f32_16x16x32_bf16 v[30:33], v[134:137], v[198:201], v[30:33]
	v_mfma_f32_16x16x32_bf16 v[26:29], v[142:145], v[198:201], v[26:29]
	v_mfma_f32_16x16x32_bf16 v[14:17], v[134:137], v[206:209], v[14:17]
	v_mfma_f32_16x16x32_bf16 v[10:13], v[142:145], v[206:209], v[10:13]
	v_mfma_f32_16x16x32_bf16 v[54:57], v[156:159], v[178:181], v[54:57]
	v_mfma_f32_16x16x32_bf16 v[50:53], v[170:173], v[178:181], v[50:53]
	v_mfma_f32_16x16x32_bf16 v[38:41], v[156:159], v[186:189], v[38:41]
	v_mfma_f32_16x16x32_bf16 v[34:37], v[170:173], v[186:189], v[34:37]
	v_mfma_f32_16x16x32_bf16 v[22:25], v[156:159], v[194:197], v[22:25]
	v_mfma_f32_16x16x32_bf16 v[18:21], v[170:173], v[194:197], v[18:21]
	v_mfma_f32_16x16x32_bf16 v[6:9], v[156:159], v[202:205], v[6:9]
	v_mfma_f32_16x16x32_bf16 v[2:5], v[170:173], v[202:205], v[2:5]
	v_mfma_f32_16x16x32_bf16 v[54:57], v[166:169], v[182:185], v[54:57]
	v_mfma_f32_16x16x32_bf16 v[50:53], v[174:177], v[182:185], v[50:53]
	v_mfma_f32_16x16x32_bf16 v[38:41], v[166:169], v[190:193], v[38:41]
	v_mfma_f32_16x16x32_bf16 v[34:37], v[174:177], v[190:193], v[34:37]
	v_mfma_f32_16x16x32_bf16 v[22:25], v[166:169], v[198:201], v[22:25]
	v_mfma_f32_16x16x32_bf16 v[18:21], v[174:177], v[198:201], v[18:21]
	v_mfma_f32_16x16x32_bf16 v[6:9], v[166:169], v[206:209], v[6:9]
	v_mfma_f32_16x16x32_bf16 v[2:5], v[174:177], v[206:209], v[2:5]
	s_barrier
; #define PG8_STAGE(bufoff, gbase, voff) do { _Pragma("unroll") for (int _i = 0; _i < 2; ++_i) \
;         __builtin_amdgcn_global_load_lds((const unsigned*)((const char*)(gbase) + (voff)[_i]), (PG8_LAS unsigned*)(lds + (bufoff) + ldsw + _i * 8192), 16, 0, 0); } while (0)
; #define PG8_LDA(dst, b, h) do { _Pragma("unroll") for (int m = 0; m < 4; ++m) _Pragma("unroll") for (int k = 0; k < 2; ++k) dst[m][k] = *(const PG8_LAS bf16x8*)(lds + PG8_SA(b, h) + aoff + m * 2048 + k * 1024); } while (0)
; #define PG8_LDB(dst, b, h) do { _Pragma("unroll") for (int n = 0; n < 2; ++n) _Pragma("unroll") for (int k = 0; k < 2; ++k) dst[n][k] = *(const PG8_LAS bf16x8*)(lds + PG8_SB(b, h) + boff + n * 2048 + k * 1024); } while (0)
; #define PG8_MMA(ai, bj, At, Bt) do { __builtin_amdgcn_s_setprio(1); _Pragma("unroll") for (int m = 0; m < 4; ++m) _Pragma("unroll") for (int n = 0; n < 2; ++n) _Pragma("unroll") for (int k = 0; k < 2; ++k) \
;         acc[ai][bj][m][n] = __builtin_amdgcn_mfma_f32_16x16x32_bf16(Bt[n][k], At[m][k], acc[ai][bj][m][n], 0, 0, 0); __builtin_amdgcn_s_setprio(0); } while (0)
; #define PG8_WAIT_V(n) asm volatile("s_waitcnt vmcnt(" #n ")" ::: "memory")
; #define PG8_WAIT_L(n) asm volatile("s_waitcnt lgkmcnt(" #n ")" ::: "memory")
; #define PG8_BAR __builtin_amdgcn_s_barrier()
; #define PG8_SCHED __builtin_amdgcn_sched_barrier(0)
; template <class Prob, class Epi, class Sched>
; __device__ __forceinline__ void gemm_phase(PG8_LAS unsigned char* lds, const Prob g, const Sched& S, const Epi& E) {
;     ...
;             PG8_LDB(B0, 1, 0); PG8_LDB(B1, 1, 1); PG8_SCHED; PG8_LDA(At, 1, 0); PG8_STAGE(PG8_SA(0, 1), a2 + hstepA, voffA);
;             PG8_WAIT_V(8); PG8_WAIT_L(0); PG8_BAR; PG8_MMA(0, 0, At, B0); PG8_MMA(0, 1, At, B1); PG8_BAR; PG8_SCHED;
;             PG8_LDA(At, 1, 1); PG8_STAGE(PG8_SB(1, 0), b3, voffB); PG8_STAGE(PG8_SB(1, 1), b3 + hstepB, voffB); PG8_STAGE(PG8_SA(1, 0), a3, voffA);
;             PG8_WAIT_V(8); PG8_WAIT_L(0); PG8_BAR; PG8_MMA(1, 0, At, B0); PG8_MMA(1, 1, At, B1); PG8_BAR; PG8_SCHED;
;         }
;         if (wr == 0) PG8_BAR;
	s_setprio 0
	s_add_i32 s40, 0, 0x18000
	v_add_u32_e32 v1, s40, v163
	s_add_i32 s41, 0, 0x1c000
	ds_read_b128 v[130:133], v1
	ds_read_b128 v[134:137], v1 offset:1024
	ds_read_b128 v[138:141], v1 offset:2048
	ds_read_b128 v[142:145], v1 offset:3072
	v_add_u32_e32 v1, s41, v163
	ds_read_b128 v[156:159], v1
	ds_read_b128 v[166:169], v1 offset:1024
	ds_read_b128 v[170:173], v1 offset:2048
	ds_read_b128 v[174:177], v1 offset:3072
	s_add_u32 s4, s30, 0x40000
	s_addc_u32 s5, s31, 0
	s_mov_b32 m0, s39
	ds_read_b128 v[178:181], v165 offset:32768
	ds_read_b128 v[182:185], v165 offset:33792
	ds_read_b128 v[186:189], v165 offset:34816
	ds_read_b128 v[190:193], v165 offset:35840
	ds_read_b128 v[194:197], v165 offset:36864
	ds_read_b128 v[198:201], v165 offset:37888
	ds_read_b128 v[202:205], v165 offset:38912
	ds_read_b128 v[206:209], v165 offset:39936
	global_load_lds_dwordx4 v150, s[4:5]
	s_mov_b32 m0, s42
	s_nop 0
	global_load_lds_dwordx4 v148, s[4:5]
	s_waitcnt vmcnt(8)
	s_waitcnt lgkmcnt(0)
	s_setprio 1
	s_barrier
	v_mfma_f32_16x16x32_bf16 v[126:129], v[130:133], v[178:181], v[126:129]
	v_mfma_f32_16x16x32_bf16 v[122:125], v[138:141], v[178:181], v[122:125]
	v_mfma_f32_16x16x32_bf16 v[110:113], v[130:133], v[186:189], v[110:113]
	v_mfma_f32_16x16x32_bf16 v[106:109], v[138:141], v[186:189], v[106:109]
	v_mfma_f32_16x16x32_bf16 v[94:97], v[130:133], v[194:197], v[94:97]
	v_mfma_f32_16x16x32_bf16 v[90:93], v[138:141], v[194:197], v[90:93]
	v_mfma_f32_16x16x32_bf16 v[78:81], v[130:133], v[202:205], v[78:81]
	v_mfma_f32_16x16x32_bf16 v[74:77], v[138:141], v[202:205], v[74:77]
	v_mfma_f32_16x16x32_bf16 v[126:129], v[134:137], v[182:185], v[126:129]
	v_mfma_f32_16x16x32_bf16 v[122:125], v[142:145], v[182:185], v[122:125]
	v_mfma_f32_16x16x32_bf16 v[110:113], v[134:137], v[190:193], v[110:113]
	v_mfma_f32_16x16x32_bf16 v[106:109], v[142:145], v[190:193], v[106:109]
	v_mfma_f32_16x16x32_bf16 v[94:97], v[134:137], v[198:201], v[94:97]
	v_mfma_f32_16x16x32_bf16 v[90:93], v[142:145], v[198:201], v[90:93]
	v_mfma_f32_16x16x32_bf16 v[78:81], v[134:137], v[206:209], v[78:81]
	v_mfma_f32_16x16x32_bf16 v[74:77], v[142:145], v[206:209], v[74:77]
	v_mfma_f32_16x16x32_bf16 v[118:121], v[156:159], v[178:181], v[118:121]
	v_mfma_f32_16x16x32_bf16 v[114:117], v[170:173], v[178:181], v[114:117]
	v_mfma_f32_16x16x32_bf16 v[102:105], v[156:159], v[186:189], v[102:105]
	v_mfma_f32_16x16x32_bf16 v[98:101], v[170:173], v[186:189], v[98:101]
	v_mfma_f32_16x16x32_bf16 v[86:89], v[156:159], v[194:197], v[86:89]
	v_mfma_f32_16x16x32_bf16 v[82:85], v[170:173], v[194:197], v[82:85]
	v_mfma_f32_16x16x32_bf16 v[70:73], v[156:159], v[202:205], v[70:73]
	v_mfma_f32_16x16x32_bf16 v[66:69], v[170:173], v[202:205], v[66:69]
	v_mfma_f32_16x16x32_bf16 v[118:121], v[166:169], v[182:185], v[118:121]
	v_mfma_f32_16x16x32_bf16 v[114:117], v[174:177], v[182:185], v[114:117]
	v_mfma_f32_16x16x32_bf16 v[102:105], v[166:169], v[190:193], v[102:105]
	v_mfma_f32_16x16x32_bf16 v[98:101], v[174:177], v[190:193], v[98:101]
	v_mfma_f32_16x16x32_bf16 v[86:89], v[166:169], v[198:201], v[86:89]
	v_mfma_f32_16x16x32_bf16 v[82:85], v[174:177], v[198:201], v[82:85]
	v_mfma_f32_16x16x32_bf16 v[70:73], v[166:169], v[206:209], v[70:73]
	v_mfma_f32_16x16x32_bf16 v[66:69], v[174:177], v[206:209], v[66:69]
	s_barrier
	s_setprio 0
	s_add_i32 s4, s40, s36
	s_mov_b32 m0, s4
	ds_read_b128 v[178:181], v165 offset:49152
	ds_read_b128 v[182:185], v165 offset:50176
	ds_read_b128 v[186:189], v165 offset:51200
	ds_read_b128 v[190:193], v165 offset:52224
	ds_read_b128 v[194:197], v165 offset:53248
	ds_read_b128 v[198:201], v165 offset:54272
	ds_read_b128 v[202:205], v165 offset:55296
	ds_read_b128 v[206:209], v165 offset:56320
	s_add_u32 s100, s28, 0x80
	s_addc_u32 s101, s29, 0
	global_load_lds_dwordx4 v226, s[100:101]
	s_add_i32 m0, s4, 0x2000
	s_add_u32 s4, s28, 0x40080
	s_addc_u32 s5, s29, 0
	s_add_i32 s28, s41, s36
	global_load_lds_dwordx4 v146, s[100:101]
	s_mov_b32 m0, s28
	s_nop 0
	global_load_lds_dwordx4 v226, s[4:5]
	s_add_i32 m0, s28, 0x2000
	s_nop 0
	global_load_lds_dwordx4 v146, s[4:5]
	s_mov_b32 m0, s43
	s_nop 0
	s_add_u32 s100, s30, 0x80
	s_addc_u32 s101, s31, 0
	global_load_lds_dwordx4 v150, s[100:101]
	s_mov_b32 m0, s51
	s_nop 0
	global_load_lds_dwordx4 v148, s[100:101]
	s_waitcnt vmcnt(8)
	s_waitcnt lgkmcnt(0)
	s_setprio 1
	s_barrier
	v_mfma_f32_16x16x32_bf16 v[62:65], v[130:133], v[178:181], v[62:65]
	v_mfma_f32_16x16x32_bf16 v[58:61], v[138:141], v[178:181], v[58:61]
	v_mfma_f32_16x16x32_bf16 v[46:49], v[130:133], v[186:189], v[46:49]
	v_mfma_f32_16x16x32_bf16 v[42:45], v[138:141], v[186:189], v[42:45]
	v_mfma_f32_16x16x32_bf16 v[30:33], v[130:133], v[194:197], v[30:33]
	v_mfma_f32_16x16x32_bf16 v[26:29], v[138:141], v[194:197], v[26:29]
	v_mfma_f32_16x16x32_bf16 v[14:17], v[130:133], v[202:205], v[14:17]
	v_mfma_f32_16x16x32_bf16 v[10:13], v[138:141], v[202:205], v[10:13]
	v_mfma_f32_16x16x32_bf16 v[62:65], v[134:137], v[182:185], v[62:65]
	v_mfma_f32_16x16x32_bf16 v[58:61], v[142:145], v[182:185], v[58:61]
	v_mfma_f32_16x16x32_bf16 v[46:49], v[134:137], v[190:193], v[46:49]
	v_mfma_f32_16x16x32_bf16 v[42:45], v[142:145], v[190:193], v[42:45]
	v_mfma_f32_16x16x32_bf16 v[30:33], v[134:137], v[198:201], v[30:33]
	v_mfma_f32_16x16x32_bf16 v[26:29], v[142:145], v[198:201], v[26:29]
	v_mfma_f32_16x16x32_bf16 v[14:17], v[134:137], v[206:209], v[14:17]
	v_mfma_f32_16x16x32_bf16 v[10:13], v[142:145], v[206:209], v[10:13]
	v_mfma_f32_16x16x32_bf16 v[54:57], v[156:159], v[178:181], v[54:57]
	v_mfma_f32_16x16x32_bf16 v[50:53], v[170:173], v[178:181], v[50:53]
	v_mfma_f32_16x16x32_bf16 v[38:41], v[156:159], v[186:189], v[38:41]
	v_mfma_f32_16x16x32_bf16 v[34:37], v[170:173], v[186:189], v[34:37]
	v_mfma_f32_16x16x32_bf16 v[22:25], v[156:159], v[194:197], v[22:25]
	v_mfma_f32_16x16x32_bf16 v[18:21], v[170:173], v[194:197], v[18:21]
	v_mfma_f32_16x16x32_bf16 v[6:9], v[156:159], v[202:205], v[6:9]
	v_mfma_f32_16x16x32_bf16 v[2:5], v[170:173], v[202:205], v[2:5]
	v_mfma_f32_16x16x32_bf16 v[54:57], v[166:169], v[182:185], v[54:57]
	v_mfma_f32_16x16x32_bf16 v[50:53], v[174:177], v[182:185], v[50:53]
	v_mfma_f32_16x16x32_bf16 v[38:41], v[166:169], v[190:193], v[38:41]
	v_mfma_f32_16x16x32_bf16 v[34:37], v[174:177], v[190:193], v[34:37]
	v_mfma_f32_16x16x32_bf16 v[22:25], v[166:169], v[198:201], v[22:25]
	v_mfma_f32_16x16x32_bf16 v[18:21], v[174:177], v[198:201], v[18:21]
	v_mfma_f32_16x16x32_bf16 v[6:9], v[166:169], v[206:209], v[6:9]
	v_mfma_f32_16x16x32_bf16 v[2:5], v[174:177], v[206:209], v[2:5]
	s_barrier
	s_setprio 0
	s_add_i32 s58, s58, 2
	s_add_u32 s26, s26, 0x100
	s_addc_u32 s27, s27, 0
	s_add_u32 s45, s45, 0x100
	s_addc_u32 s57, s57, 0
	s_cmp_gt_u32 s58, 13
	s_cbranch_scc0 .LBB0_758
	s_and_b64 vcc, exec, s[14:15]
	s_cbranch_vccz .LBB0_761
	s_barrier

; #define PG8_STAGE(bufoff, gbase, voff) do { _Pragma("unroll") for (int _i = 0; _i < 2; ++_i) \
;         __builtin_amdgcn_global_load_lds((const unsigned*)((const char*)(gbase) + (voff)[_i]), (PG8_LAS unsigned*)(lds + (bufoff) + ldsw + _i * 8192), 16, 0, 0); } while (0)
; #define PG8_LDA(dst, b, h) do { _Pragma("unroll") for (int m = 0; m < 4; ++m) _Pragma("unroll") for (int k = 0; k < 2; ++k) dst[m][k] = *(const PG8_LAS bf16x8*)(lds + PG8_SA(b, h) + aoff + m * 2048 + k * 1024); } while (0)
; #define PG8_LDB(dst, b, h) do { _Pragma("unroll") for (int n = 0; n < 2; ++n) _Pragma("unroll") for (int k = 0; k < 2; ++k) dst[n][k] = *(const PG8_LAS bf16x8*)(lds + PG8_SB(b, h) + boff + n * 2048 + k * 1024); } while (0)
; #define PG8_MMA(ai, bj, At, Bt) do { __builtin_amdgcn_s_setprio(1); _Pragma("unroll") for (int m = 0; m < 4; ++m) _Pragma("unroll") for (int n = 0; n < 2; ++n) _Pragma("unroll") for (int k = 0; k < 2; ++k) \
;         acc[ai][bj][m][n] = __builtin_amdgcn_mfma_f32_16x16x32_bf16(Bt[n][k], At[m][k], acc[ai][bj][m][n], 0, 0, 0); __builtin_amdgcn_s_setprio(0); } while (0)
; #define PG8_WAIT_V(n) asm volatile("s_waitcnt vmcnt(" #n ")" ::: "memory")
; #define PG8_WAIT_L(n) asm volatile("s_waitcnt lgkmcnt(" #n ")" ::: "memory")
; #define PG8_BAR __builtin_amdgcn_s_barrier()
; #define PG8_SCHED __builtin_amdgcn_sched_barrier(0)
; template <class Prob, class Epi, class Sched>
; __device__ __forceinline__ void gemm_phase(PG8_LAS unsigned char* lds, const Prob g, const Sched& S, const Epi& E) {
;     ...
;             const bool last = (t == nt - 2);
;             const char* a1 = cA + (size_t)(t + 1) * kstep;
;             const char* a2 = last ? nA : cA + (size_t)(t + 2) * kstep; const char* b2 = last ? nB : cB + (size_t)(t + 2) * kstep;
;             const char* a3 = a2 + kstep; const char* b3 = b2 + kstep;
;             PG8_LDB(B0, 0, 0); PG8_LDB(B1, 0, 1); PG8_SCHED; PG8_LDA(At, 0, 0); PG8_STAGE(PG8_SA(1, 1), a1 + hstepA, voffA);
;             PG8_WAIT_V(8); PG8_WAIT_L(0); PG8_BAR; PG8_MMA(0, 0, At, B0); PG8_MMA(0, 1, At, B1); PG8_BAR; PG8_SCHED;
;             PG8_LDA(At, 0, 1); PG8_STAGE(PG8_SB(0, 0), b2, voffB); PG8_STAGE(PG8_SB(0, 1), b2 + hstepB, voffB); PG8_STAGE(PG8_SA(0, 0), a2, voffA);
;             PG8_WAIT_V(8); PG8_WAIT_L(0); PG8_BAR; PG8_MMA(1, 0, At, B0); PG8_MMA(1, 1, At, B1); PG8_BAR; PG8_SCHED;
.LBB0_823:
	s_add_u32 s4, s56, 0xfff80080
	s_addc_u32 s5, s57, -1
	s_add_i32 s40, 0, 0x10000
	s_cmp_eq_u32 vcc_hi, 28
	s_cselect_b32 s39, s37, s5
	s_cselect_b32 s38, s70, s4
	v_add_u32_e32 v1, s40, v191
	s_cselect_b32 s69, s35, vcc_lo
	s_cselect_b32 s68, s44, s45
	s_add_i32 s41, 0, 0x14000
	ds_read_b128 v[34:37], v1
	ds_read_b128 v[38:41], v1 offset:1024
	ds_read_b128 v[42:45], v1 offset:2048
	ds_read_b128 v[46:49], v1 offset:3072
	v_add_u32_e32 v1, s41, v191
	ds_read_b128 v[58:61], v1
	ds_read_b128 v[62:65], v1 offset:1024
	ds_read_b128 v[66:69], v1 offset:2048
	ds_read_b128 v[70:73], v1 offset:3072
	s_add_i32 m0, s43, 0xc000
	ds_read_b128 v[162:165], v194
	ds_read_b128 v[166:169], v194 offset:1024
	ds_read_b128 v[180:183], v194 offset:2048
	ds_read_b128 v[184:187], v194 offset:3072
	ds_read_b128 v[198:201], v194 offset:4096
	ds_read_b128 v[202:205], v194 offset:5120
	ds_read_b128 v[206:209], v194 offset:6144
	ds_read_b128 v[210:213], v194 offset:7168
	global_load_lds_dwordx4 v176, s[56:57]
	s_add_i32 m0, s43, 0xe000
	s_nop 0
	global_load_lds_dwordx4 v178, s[56:57]
	s_waitcnt vmcnt(8)
	s_waitcnt lgkmcnt(0)
	s_setprio 1
	s_barrier
	v_mfma_f32_16x16x32_bf16 v[158:161], v[34:37], v[162:165], v[158:161]
	v_mfma_f32_16x16x32_bf16 v[154:157], v[42:45], v[162:165], v[154:157]
	v_mfma_f32_16x16x32_bf16 v[142:145], v[34:37], v[180:183], v[142:145]
	v_mfma_f32_16x16x32_bf16 v[138:141], v[42:45], v[180:183], v[138:141]
	v_mfma_f32_16x16x32_bf16 v[126:129], v[34:37], v[198:201], v[126:129]
	v_mfma_f32_16x16x32_bf16 v[122:125], v[42:45], v[198:201], v[122:125]
	v_mfma_f32_16x16x32_bf16 v[110:113], v[34:37], v[206:209], v[110:113]
	v_mfma_f32_16x16x32_bf16 v[106:109], v[42:45], v[206:209], v[106:109]
	v_mfma_f32_16x16x32_bf16 v[158:161], v[38:41], v[166:169], v[158:161]
	v_mfma_f32_16x16x32_bf16 v[154:157], v[46:49], v[166:169], v[154:157]
	v_mfma_f32_16x16x32_bf16 v[142:145], v[38:41], v[184:187], v[142:145]
	v_mfma_f32_16x16x32_bf16 v[138:141], v[46:49], v[184:187], v[138:141]
	v_mfma_f32_16x16x32_bf16 v[126:129], v[38:41], v[202:205], v[126:129]
	v_mfma_f32_16x16x32_bf16 v[122:125], v[46:49], v[202:205], v[122:125]
	v_mfma_f32_16x16x32_bf16 v[110:113], v[38:41], v[210:213], v[110:113]
	v_mfma_f32_16x16x32_bf16 v[106:109], v[46:49], v[210:213], v[106:109]
	v_mfma_f32_16x16x32_bf16 v[150:153], v[58:61], v[162:165], v[150:153]
	v_mfma_f32_16x16x32_bf16 v[146:149], v[66:69], v[162:165], v[146:149]
	v_mfma_f32_16x16x32_bf16 v[134:137], v[58:61], v[180:183], v[134:137]
	v_mfma_f32_16x16x32_bf16 v[130:133], v[66:69], v[180:183], v[130:133]
	v_mfma_f32_16x16x32_bf16 v[118:121], v[58:61], v[198:201], v[118:121]
	v_mfma_f32_16x16x32_bf16 v[114:117], v[66:69], v[198:201], v[114:117]
	v_mfma_f32_16x16x32_bf16 v[102:105], v[58:61], v[206:209], v[102:105]
	v_mfma_f32_16x16x32_bf16 v[98:101], v[66:69], v[206:209], v[98:101]
	v_mfma_f32_16x16x32_bf16 v[150:153], v[62:65], v[166:169], v[150:153]
	v_mfma_f32_16x16x32_bf16 v[146:149], v[70:73], v[166:169], v[146:149]
	v_mfma_f32_16x16x32_bf16 v[134:137], v[62:65], v[184:187], v[134:137]
	v_mfma_f32_16x16x32_bf16 v[130:133], v[70:73], v[184:187], v[130:133]
	v_mfma_f32_16x16x32_bf16 v[118:121], v[62:65], v[202:205], v[118:121]
	v_mfma_f32_16x16x32_bf16 v[114:117], v[70:73], v[202:205], v[114:117]
	v_mfma_f32_16x16x32_bf16 v[102:105], v[62:65], v[210:213], v[102:105]
	v_mfma_f32_16x16x32_bf16 v[98:101], v[70:73], v[210:213], v[98:101]
	s_barrier
	s_setprio 0
	s_add_i32 s4, s40, s42
	s_mov_b32 m0, s4
	ds_read_b128 v[162:165], v194 offset:16384
	ds_read_b128 v[166:169], v194 offset:17408
	ds_read_b128 v[180:183], v194 offset:18432
	ds_read_b128 v[184:187], v194 offset:19456
	ds_read_b128 v[198:201], v194 offset:20480
	ds_read_b128 v[202:205], v194 offset:21504
	ds_read_b128 v[206:209], v194 offset:22528
	ds_read_b128 v[210:213], v194 offset:23552
	global_load_lds_dwordx4 v226, s[68:69]
	s_add_i32 m0, s4, 0x2000
	s_add_u32 s4, s68, 0x80000
	s_addc_u32 s5, s69, 0
	s_add_i32 s40, s41, s42
	global_load_lds_dwordx4 v170, s[68:69]
	s_mov_b32 m0, s40
	v_lshl_add_u64 v[220:221], s[38:39], 0, v[174:175]
	global_load_lds_dwordx4 v226, s[4:5]
	s_add_i32 m0, s40, 0x2000
	v_lshl_add_u64 v[222:223], s[38:39], 0, v[172:173]
	global_load_lds_dwordx4 v170, s[4:5]
	s_mov_b32 m0, s43
	s_nop 0
	global_load_lds_dwordx4 v174, s[38:39]
	s_mov_b32 m0, s84
	s_nop 0
	global_load_lds_dwordx4 v172, s[38:39]
	s_waitcnt vmcnt(8)
	s_waitcnt lgkmcnt(0)
	s_setprio 1
	s_barrier
	v_mfma_f32_16x16x32_bf16 v[94:97], v[34:37], v[162:165], v[94:97]
	v_mfma_f32_16x16x32_bf16 v[90:93], v[42:45], v[162:165], v[90:93]
	v_mfma_f32_16x16x32_bf16 v[78:81], v[34:37], v[180:183], v[78:81]
	v_mfma_f32_16x16x32_bf16 v[74:77], v[42:45], v[180:183], v[74:77]
	v_mfma_f32_16x16x32_bf16 v[30:33], v[34:37], v[198:201], v[30:33]
	v_mfma_f32_16x16x32_bf16 v[26:29], v[42:45], v[198:201], v[26:29]
	v_mfma_f32_16x16x32_bf16 v[14:17], v[34:37], v[206:209], v[14:17]
	v_mfma_f32_16x16x32_bf16 v[10:13], v[42:45], v[206:209], v[10:13]
	v_mfma_f32_16x16x32_bf16 v[94:97], v[38:41], v[166:169], v[94:97]
	v_mfma_f32_16x16x32_bf16 v[90:93], v[46:49], v[166:169], v[90:93]
	v_mfma_f32_16x16x32_bf16 v[78:81], v[38:41], v[184:187], v[78:81]
	v_mfma_f32_16x16x32_bf16 v[74:77], v[46:49], v[184:187], v[74:77]
	v_mfma_f32_16x16x32_bf16 v[30:33], v[38:41], v[202:205], v[30:33]
	v_mfma_f32_16x16x32_bf16 v[26:29], v[46:49], v[202:205], v[26:29]
	v_mfma_f32_16x16x32_bf16 v[14:17], v[38:41], v[210:213], v[14:17]
	v_mfma_f32_16x16x32_bf16 v[10:13], v[46:49], v[210:213], v[10:13]
	v_mfma_f32_16x16x32_bf16 v[22:25], v[58:61], v[198:201], v[22:25]
	v_mfma_f32_16x16x32_bf16 v[18:21], v[66:69], v[198:201], v[18:21]
	v_mfma_f32_16x16x32_bf16 v[6:9], v[58:61], v[206:209], v[6:9]
	v_mfma_f32_16x16x32_bf16 v[2:5], v[66:69], v[206:209], v[2:5]
	v_mfma_f32_16x16x32_bf16 v[34:37], v[58:61], v[162:165], v[86:89]
	v_mfma_f32_16x16x32_bf16 v[38:41], v[66:69], v[162:165], v[82:85]
	v_mfma_f32_16x16x32_bf16 v[42:45], v[58:61], v[180:183], v[54:57]
	v_mfma_f32_16x16x32_bf16 v[46:49], v[66:69], v[180:183], v[50:53]
	v_mfma_f32_16x16x32_bf16 v[22:25], v[62:65], v[202:205], v[22:25]
	v_mfma_f32_16x16x32_bf16 v[18:21], v[70:73], v[202:205], v[18:21]
	v_mfma_f32_16x16x32_bf16 v[6:9], v[62:65], v[210:213], v[6:9]
	v_mfma_f32_16x16x32_bf16 v[2:5], v[70:73], v[210:213], v[2:5]
	v_mfma_f32_16x16x32_bf16 v[34:37], v[62:65], v[166:169], v[34:37]
	v_mfma_f32_16x16x32_bf16 v[38:41], v[70:73], v[166:169], v[38:41]
	v_mfma_f32_16x16x32_bf16 v[42:45], v[62:65], v[184:187], v[42:45]
	v_mfma_f32_16x16x32_bf16 v[46:49], v[70:73], v[184:187], v[46:49]
	s_barrier
; #define PG8_STAGE(bufoff, gbase, voff) do { _Pragma("unroll") for (int _i = 0; _i < 2; ++_i) \
;         __builtin_amdgcn_global_load_lds((const unsigned*)((const char*)(gbase) + (voff)[_i]), (PG8_LAS unsigned*)(lds + (bufoff) + ldsw + _i * 8192), 16, 0, 0); } while (0)
; #define PG8_LDA(dst, b, h) do { _Pragma("unroll") for (int m = 0; m < 4; ++m) _Pragma("unroll") for (int k = 0; k < 2; ++k) dst[m][k] = *(const PG8_LAS bf16x8*)(lds + PG8_SA(b, h) + aoff + m * 2048 + k * 1024); } while (0)
; #define PG8_LDB(dst, b, h) do { _Pragma("unroll") for (int n = 0; n < 2; ++n) _Pragma("unroll") for (int k = 0; k < 2; ++k) dst[n][k] = *(const PG8_LAS bf16x8*)(lds + PG8_SB(b, h) + boff + n * 2048 + k * 1024); } while (0)
; #define PG8_MMA(ai, bj, At, Bt) do { __builtin_amdgcn_s_setprio(1); _Pragma("unroll") for (int m = 0; m < 4; ++m) _Pragma("unroll") for (int n = 0; n < 2; ++n) _Pragma("unroll") for (int k = 0; k < 2; ++k) \
;         acc[ai][bj][m][n] = __builtin_amdgcn_mfma_f32_16x16x32_bf16(Bt[n][k], At[m][k], acc[ai][bj][m][n], 0, 0, 0); __builtin_amdgcn_s_setprio(0); } while (0)
; #define PG8_WAIT_V(n) asm volatile("s_waitcnt vmcnt(" #n ")" ::: "memory")
; #define PG8_WAIT_L(n) asm volatile("s_waitcnt lgkmcnt(" #n ")" ::: "memory")
; #define PG8_BAR __builtin_amdgcn_s_barrier()
; #define PG8_SCHED __builtin_amdgcn_sched_barrier(0)
; template <class Prob, class Epi, class Sched>
; __device__ __forceinline__ void gemm_phase(PG8_LAS unsigned char* lds, const Prob g, const Sched& S, const Epi& E) {
;     ...
;             PG8_LDB(B0, 1, 0); PG8_LDB(B1, 1, 1); PG8_SCHED; PG8_LDA(At, 1, 0); PG8_STAGE(PG8_SA(0, 1), a2 + hstepA, voffA);
;             PG8_WAIT_V(8); PG8_WAIT_L(0); PG8_BAR; PG8_MMA(0, 0, At, B0); PG8_MMA(0, 1, At, B1); PG8_BAR; PG8_SCHED;
;             PG8_LDA(At, 1, 1); PG8_STAGE(PG8_SB(1, 0), b3, voffB); PG8_STAGE(PG8_SB(1, 1), b3 + hstepB, voffB); PG8_STAGE(PG8_SA(1, 0), a3, voffA);
;             PG8_WAIT_V(8); PG8_WAIT_L(0); PG8_BAR; PG8_MMA(1, 0, At, B0); PG8_MMA(1, 1, At, B1); PG8_BAR; PG8_SCHED;
;         }
;         if (wr == 0) PG8_BAR;
	s_setprio 0
	s_add_i32 s40, 0, 0x18000
	v_add_u32_e32 v1, s40, v191
	s_add_i32 s41, 0, 0x1c000
	ds_read_b128 v[50:53], v1
	ds_read_b128 v[54:57], v1 offset:1024
	ds_read_b128 v[58:61], v1 offset:2048
	ds_read_b128 v[62:65], v1 offset:3072
	v_add_u32_e32 v1, s41, v191
	ds_read_b128 v[66:69], v1
	ds_read_b128 v[70:73], v1 offset:1024
	ds_read_b128 v[162:165], v1 offset:2048
	ds_read_b128 v[166:169], v1 offset:3072
	s_add_u32 s4, s38, 0x80000
	s_addc_u32 s5, s39, 0
	s_mov_b32 m0, s87
	ds_read_b128 v[82:85], v194 offset:32768
	ds_read_b128 v[86:89], v194 offset:33792
	ds_read_b128 v[180:183], v194 offset:34816
	ds_read_b128 v[184:187], v194 offset:35840
	ds_read_b128 v[198:201], v194 offset:36864
	ds_read_b128 v[202:205], v194 offset:37888
	ds_read_b128 v[206:209], v194 offset:38912
	ds_read_b128 v[210:213], v194 offset:39936
	global_load_lds_dwordx4 v174, s[4:5]
	s_mov_b32 m0, s64
	s_nop 0
	global_load_lds_dwordx4 v172, s[4:5]
	s_waitcnt vmcnt(8)
	s_waitcnt lgkmcnt(0)
	s_setprio 1
	s_barrier
	v_mfma_f32_16x16x32_bf16 v[158:161], v[50:53], v[82:85], v[158:161]
	v_mfma_f32_16x16x32_bf16 v[154:157], v[58:61], v[82:85], v[154:157]
	v_mfma_f32_16x16x32_bf16 v[142:145], v[50:53], v[180:183], v[142:145]
	v_mfma_f32_16x16x32_bf16 v[138:141], v[58:61], v[180:183], v[138:141]
	v_mfma_f32_16x16x32_bf16 v[126:129], v[50:53], v[198:201], v[126:129]
	v_mfma_f32_16x16x32_bf16 v[122:125], v[58:61], v[198:201], v[122:125]
	v_mfma_f32_16x16x32_bf16 v[110:113], v[50:53], v[206:209], v[110:113]
	v_mfma_f32_16x16x32_bf16 v[106:109], v[58:61], v[206:209], v[106:109]
	v_mfma_f32_16x16x32_bf16 v[158:161], v[54:57], v[86:89], v[158:161]
	v_mfma_f32_16x16x32_bf16 v[154:157], v[62:65], v[86:89], v[154:157]
	v_mfma_f32_16x16x32_bf16 v[142:145], v[54:57], v[184:187], v[142:145]
	v_mfma_f32_16x16x32_bf16 v[138:141], v[62:65], v[184:187], v[138:141]
	v_mfma_f32_16x16x32_bf16 v[126:129], v[54:57], v[202:205], v[126:129]
	v_mfma_f32_16x16x32_bf16 v[122:125], v[62:65], v[202:205], v[122:125]
	v_mfma_f32_16x16x32_bf16 v[110:113], v[54:57], v[210:213], v[110:113]
	v_mfma_f32_16x16x32_bf16 v[106:109], v[62:65], v[210:213], v[106:109]
	v_mfma_f32_16x16x32_bf16 v[150:153], v[66:69], v[82:85], v[150:153]
	v_mfma_f32_16x16x32_bf16 v[82:85], v[162:165], v[82:85], v[146:149]
	v_mfma_f32_16x16x32_bf16 v[146:149], v[166:169], v[86:89], v[82:85]
	v_mfma_f32_16x16x32_bf16 v[82:85], v[66:69], v[180:183], v[134:137]
	v_mfma_f32_16x16x32_bf16 v[134:137], v[70:73], v[184:187], v[82:85]
	v_mfma_f32_16x16x32_bf16 v[82:85], v[162:165], v[180:183], v[130:133]
	v_mfma_f32_16x16x32_bf16 v[130:133], v[166:169], v[184:187], v[82:85]
	v_mfma_f32_16x16x32_bf16 v[82:85], v[66:69], v[198:201], v[118:121]
	v_mfma_f32_16x16x32_bf16 v[118:121], v[70:73], v[202:205], v[82:85]
	v_mfma_f32_16x16x32_bf16 v[82:85], v[162:165], v[198:201], v[114:117]
	v_mfma_f32_16x16x32_bf16 v[114:117], v[166:169], v[202:205], v[82:85]
	v_mfma_f32_16x16x32_bf16 v[82:85], v[66:69], v[206:209], v[102:105]
	v_mfma_f32_16x16x32_bf16 v[102:105], v[70:73], v[210:213], v[82:85]
	v_mfma_f32_16x16x32_bf16 v[82:85], v[162:165], v[206:209], v[98:101]
	v_mfma_f32_16x16x32_bf16 v[150:153], v[70:73], v[86:89], v[150:153]
	v_mfma_f32_16x16x32_bf16 v[98:101], v[166:169], v[210:213], v[82:85]
	s_barrier
	s_setprio 0
	s_add_i32 s4, s40, s42
	s_mov_b32 m0, s4
	s_nop 0
	ds_read_b128 v[82:85], v194 offset:49152
	ds_read_b128 v[180:183], v194 offset:50176
	ds_read_b128 v[184:187], v194 offset:51200
	ds_read_b128 v[198:201], v194 offset:52224
	ds_read_b128 v[202:205], v194 offset:53248
	ds_read_b128 v[206:209], v194 offset:54272
	ds_read_b128 v[210:213], v194 offset:55296
	ds_read_b128 v[214:217], v194 offset:56320
	s_add_u32 s100, s68, 0x80
	s_addc_u32 s101, s69, 0
	global_load_lds_dwordx4 v226, s[100:101]
	s_add_i32 m0, s4, 0x2000
	s_add_u32 s4, s68, 0x80080
	s_addc_u32 s5, s69, 0
	s_add_i32 s38, s41, s42
	global_load_lds_dwordx4 v170, s[100:101]
	s_mov_b32 m0, s38
	s_nop 0
	global_load_lds_dwordx4 v226, s[4:5]
	s_add_i32 m0, s38, 0x2000
	s_nop 0
	global_load_lds_dwordx4 v170, s[4:5]
	v_lshl_add_u64 v[86:87], v[220:221], 0, s[88:89]
	s_mov_b32 m0, s66
	s_nop 0
	global_load_lds_dwordx4 v[86:87], off
	v_lshl_add_u64 v[86:87], v[222:223], 0, s[88:89]
	s_mov_b32 m0, s71
	s_nop 0
	global_load_lds_dwordx4 v[86:87], off
	s_waitcnt vmcnt(8)
	s_waitcnt lgkmcnt(0)
	s_setprio 1
	s_barrier
	v_mfma_f32_16x16x32_bf16 v[86:89], v[50:53], v[82:85], v[94:97]
	v_mfma_f32_16x16x32_bf16 v[94:97], v[54:57], v[180:183], v[86:89]
	v_mfma_f32_16x16x32_bf16 v[86:89], v[58:61], v[82:85], v[90:93]
	v_mfma_f32_16x16x32_bf16 v[78:81], v[50:53], v[184:187], v[78:81]
	v_mfma_f32_16x16x32_bf16 v[74:77], v[58:61], v[184:187], v[74:77]
	v_mfma_f32_16x16x32_bf16 v[30:33], v[50:53], v[202:205], v[30:33]
	v_mfma_f32_16x16x32_bf16 v[26:29], v[58:61], v[202:205], v[26:29]
	v_mfma_f32_16x16x32_bf16 v[14:17], v[50:53], v[210:213], v[14:17]
	v_mfma_f32_16x16x32_bf16 v[10:13], v[58:61], v[210:213], v[10:13]
	v_mfma_f32_16x16x32_bf16 v[90:93], v[62:65], v[180:183], v[86:89]
	v_mfma_f32_16x16x32_bf16 v[78:81], v[54:57], v[198:201], v[78:81]
	v_mfma_f32_16x16x32_bf16 v[74:77], v[62:65], v[198:201], v[74:77]
	v_mfma_f32_16x16x32_bf16 v[30:33], v[54:57], v[206:209], v[30:33]
	v_mfma_f32_16x16x32_bf16 v[26:29], v[62:65], v[206:209], v[26:29]
	v_mfma_f32_16x16x32_bf16 v[14:17], v[54:57], v[214:217], v[14:17]
	v_mfma_f32_16x16x32_bf16 v[10:13], v[62:65], v[214:217], v[10:13]
	v_mfma_f32_16x16x32_bf16 v[34:37], v[66:69], v[82:85], v[34:37]
	v_mfma_f32_16x16x32_bf16 v[86:89], v[70:73], v[180:183], v[34:37]
	v_mfma_f32_16x16x32_bf16 v[34:37], v[162:165], v[82:85], v[38:41]
	v_mfma_f32_16x16x32_bf16 v[82:85], v[166:169], v[180:183], v[34:37]
	v_mfma_f32_16x16x32_bf16 v[34:37], v[66:69], v[184:187], v[42:45]
	v_mfma_f32_16x16x32_bf16 v[54:57], v[70:73], v[198:201], v[34:37]
	v_mfma_f32_16x16x32_bf16 v[34:37], v[162:165], v[184:187], v[46:49]
	v_mfma_f32_16x16x32_bf16 v[22:25], v[66:69], v[202:205], v[22:25]
	v_mfma_f32_16x16x32_bf16 v[18:21], v[162:165], v[202:205], v[18:21]
	v_mfma_f32_16x16x32_bf16 v[6:9], v[66:69], v[210:213], v[6:9]
	v_mfma_f32_16x16x32_bf16 v[2:5], v[162:165], v[210:213], v[2:5]
	v_mfma_f32_16x16x32_bf16 v[50:53], v[166:169], v[198:201], v[34:37]
	v_mfma_f32_16x16x32_bf16 v[22:25], v[70:73], v[206:209], v[22:25]
	v_mfma_f32_16x16x32_bf16 v[18:21], v[166:169], v[206:209], v[18:21]
	v_mfma_f32_16x16x32_bf16 v[6:9], v[70:73], v[214:217], v[6:9]
	v_mfma_f32_16x16x32_bf16 v[2:5], v[166:169], v[214:217], v[2:5]
	s_barrier
	s_setprio 0
	s_add_i32 vcc_hi, vcc_hi, 2
	s_add_u32 s56, s56, 0x100
	s_addc_u32 s57, s57, 0
	s_add_u32 s45, s45, 0x100
	s_addc_u32 vcc_lo, vcc_lo, 0
	s_cmp_gt_u32 vcc_hi, 29
	s_cbranch_scc0 .LBB0_823
	s_and_b64 vcc, exec, s[28:29]
	s_cbranch_vccz .LBB0_826
	s_barrier

; #define PG8_STAGE(bufoff, gbase, voff) do { _Pragma("unroll") for (int _i = 0; _i < 2; ++_i) \
;         __builtin_amdgcn_global_load_lds((const unsigned*)((const char*)(gbase) + (voff)[_i]), (PG8_LAS unsigned*)(lds + (bufoff) + ldsw + _i * 8192), 16, 0, 0); } while (0)
; #define PG8_LDA(dst, b, h) do { _Pragma("unroll") for (int m = 0; m < 4; ++m) _Pragma("unroll") for (int k = 0; k < 2; ++k) dst[m][k] = *(const PG8_LAS bf16x8*)(lds + PG8_SA(b, h) + aoff + m * 2048 + k * 1024); } while (0)
; #define PG8_LDB(dst, b, h) do { _Pragma("unroll") for (int n = 0; n < 2; ++n) _Pragma("unroll") for (int k = 0; k < 2; ++k) dst[n][k] = *(const PG8_LAS bf16x8*)(lds + PG8_SB(b, h) + boff + n * 2048 + k * 1024); } while (0)
; #define PG8_MMA(ai, bj, At, Bt) do { __builtin_amdgcn_s_setprio(1); _Pragma("unroll") for (int m = 0; m < 4; ++m) _Pragma("unroll") for (int n = 0; n < 2; ++n) _Pragma("unroll") for (int k = 0; k < 2; ++k) \
;         acc[ai][bj][m][n] = __builtin_amdgcn_mfma_f32_16x16x32_bf16(Bt[n][k], At[m][k], acc[ai][bj][m][n], 0, 0, 0); __builtin_amdgcn_s_setprio(0); } while (0)
; #define PG8_WAIT_V(n) asm volatile("s_waitcnt vmcnt(" #n ")" ::: "memory")
; #define PG8_WAIT_L(n) asm volatile("s_waitcnt lgkmcnt(" #n ")" ::: "memory")
; #define PG8_BAR __builtin_amdgcn_s_barrier()
; #define PG8_SCHED __builtin_amdgcn_sched_barrier(0)
; template <class Prob, class Epi, class Sched>
; __device__ __forceinline__ void gemm_phase(PG8_LAS unsigned char* lds, const Prob g, const Sched& S, const Epi& E) {
;     ...
;             const bool last = (t == nt - 2);
;             const char* a1 = cA + (size_t)(t + 1) * kstep;
;             const char* a2 = last ? nA : cA + (size_t)(t + 2) * kstep; const char* b2 = last ? nB : cB + (size_t)(t + 2) * kstep;
;             const char* a3 = a2 + kstep; const char* b3 = b2 + kstep;
;             PG8_LDB(B0, 0, 0); PG8_LDB(B1, 0, 1); PG8_SCHED; PG8_LDA(At, 0, 0); PG8_STAGE(PG8_SA(1, 1), a1 + hstepA, voffA);
;             PG8_WAIT_V(8); PG8_WAIT_L(0); PG8_BAR; PG8_MMA(0, 0, At, B0); PG8_MMA(0, 1, At, B1); PG8_BAR; PG8_SCHED;
;             PG8_LDA(At, 0, 1); PG8_STAGE(PG8_SB(0, 0), b2, voffB); PG8_STAGE(PG8_SB(0, 1), b2 + hstepB, voffB); PG8_STAGE(PG8_SA(0, 0), a2, voffA);
;             PG8_WAIT_V(8); PG8_WAIT_L(0); PG8_BAR; PG8_MMA(1, 0, At, B0); PG8_MMA(1, 1, At, B1); PG8_BAR; PG8_SCHED;
.LBB0_867:
	s_add_u32 s4, s54, 0xfff80080
	s_addc_u32 s5, s55, -1
	s_add_i32 s40, 0, 0x10000
	s_cmp_eq_u32 vcc_hi, 28
	s_cselect_b32 s39, s37, s5
	s_cselect_b32 s38, s70, s4
	v_add_u32_e32 v1, s40, v177
	s_cselect_b32 s57, s35, vcc_lo
	s_cselect_b32 s56, s44, s45
	s_add_i32 s41, 0, 0x14000
	ds_read_b128 v[66:69], v1
	ds_read_b128 v[70:73], v1 offset:1024
	ds_read_b128 v[74:77], v1 offset:2048
	ds_read_b128 v[78:81], v1 offset:3072
	v_add_u32_e32 v1, s41, v177
	ds_read_b128 v[82:85], v1
	ds_read_b128 v[86:89], v1 offset:1024
	ds_read_b128 v[90:93], v1 offset:2048
	ds_read_b128 v[94:97], v1 offset:3072
	s_add_i32 m0, s66, 0xc000
	ds_read_b128 v[172:175], v180
	ds_read_b128 v[184:187], v180 offset:1024
	ds_read_b128 v[188:191], v180 offset:2048
	ds_read_b128 v[192:195], v180 offset:3072
	ds_read_b128 v[196:199], v180 offset:4096
	ds_read_b128 v[200:203], v180 offset:5120
	ds_read_b128 v[204:207], v180 offset:6144
	ds_read_b128 v[208:211], v180 offset:7168
	global_load_lds_dwordx4 v168, s[54:55]
	s_add_i32 m0, s66, 0xe000
	s_nop 0
	global_load_lds_dwordx4 v170, s[54:55]
	s_waitcnt vmcnt(8)
	s_waitcnt lgkmcnt(0)
	s_setprio 1
	s_barrier
	v_mfma_f32_16x16x32_bf16 v[158:161], v[66:69], v[172:175], v[158:161]
	v_mfma_f32_16x16x32_bf16 v[154:157], v[74:77], v[172:175], v[154:157]
	v_mfma_f32_16x16x32_bf16 v[142:145], v[66:69], v[188:191], v[142:145]
	v_mfma_f32_16x16x32_bf16 v[138:141], v[74:77], v[188:191], v[138:141]
	v_mfma_f32_16x16x32_bf16 v[126:129], v[66:69], v[196:199], v[126:129]
	v_mfma_f32_16x16x32_bf16 v[122:125], v[74:77], v[196:199], v[122:125]
	v_mfma_f32_16x16x32_bf16 v[110:113], v[66:69], v[204:207], v[110:113]
	v_mfma_f32_16x16x32_bf16 v[106:109], v[74:77], v[204:207], v[106:109]
	v_mfma_f32_16x16x32_bf16 v[158:161], v[70:73], v[184:187], v[158:161]
	v_mfma_f32_16x16x32_bf16 v[154:157], v[78:81], v[184:187], v[154:157]
	v_mfma_f32_16x16x32_bf16 v[142:145], v[70:73], v[192:195], v[142:145]
	v_mfma_f32_16x16x32_bf16 v[138:141], v[78:81], v[192:195], v[138:141]
	v_mfma_f32_16x16x32_bf16 v[126:129], v[70:73], v[200:203], v[126:129]
	v_mfma_f32_16x16x32_bf16 v[122:125], v[78:81], v[200:203], v[122:125]
	v_mfma_f32_16x16x32_bf16 v[110:113], v[70:73], v[208:211], v[110:113]
	v_mfma_f32_16x16x32_bf16 v[106:109], v[78:81], v[208:211], v[106:109]
	v_mfma_f32_16x16x32_bf16 v[150:153], v[82:85], v[172:175], v[150:153]
	v_mfma_f32_16x16x32_bf16 v[146:149], v[90:93], v[172:175], v[146:149]
	v_mfma_f32_16x16x32_bf16 v[134:137], v[82:85], v[188:191], v[134:137]
	v_mfma_f32_16x16x32_bf16 v[130:133], v[90:93], v[188:191], v[130:133]
	v_mfma_f32_16x16x32_bf16 v[118:121], v[82:85], v[196:199], v[118:121]
	v_mfma_f32_16x16x32_bf16 v[114:117], v[90:93], v[196:199], v[114:117]
	v_mfma_f32_16x16x32_bf16 v[102:105], v[82:85], v[204:207], v[102:105]
	v_mfma_f32_16x16x32_bf16 v[98:101], v[90:93], v[204:207], v[98:101]
	v_mfma_f32_16x16x32_bf16 v[150:153], v[86:89], v[184:187], v[150:153]
	v_mfma_f32_16x16x32_bf16 v[146:149], v[94:97], v[184:187], v[146:149]
	v_mfma_f32_16x16x32_bf16 v[134:137], v[86:89], v[192:195], v[134:137]
	v_mfma_f32_16x16x32_bf16 v[130:133], v[94:97], v[192:195], v[130:133]
	v_mfma_f32_16x16x32_bf16 v[118:121], v[86:89], v[200:203], v[118:121]
	v_mfma_f32_16x16x32_bf16 v[114:117], v[94:97], v[200:203], v[114:117]
	v_mfma_f32_16x16x32_bf16 v[102:105], v[86:89], v[208:211], v[102:105]
	v_mfma_f32_16x16x32_bf16 v[98:101], v[94:97], v[208:211], v[98:101]
	s_barrier
	s_setprio 0
	s_add_i32 s4, s40, s64
	s_mov_b32 m0, s4
	ds_read_b128 v[172:175], v180 offset:16384
	ds_read_b128 v[184:187], v180 offset:17408
	ds_read_b128 v[188:191], v180 offset:18432
	ds_read_b128 v[192:195], v180 offset:19456
	ds_read_b128 v[196:199], v180 offset:20480
	ds_read_b128 v[200:203], v180 offset:21504
	ds_read_b128 v[204:207], v180 offset:22528
	ds_read_b128 v[208:211], v180 offset:23552
	global_load_lds_dwordx4 v226, s[56:57]
	s_add_i32 m0, s4, 0x2000
	s_add_u32 s4, s56, 0x80000
	s_addc_u32 s5, s57, 0
	s_add_i32 s40, s41, s64
	global_load_lds_dwordx4 v162, s[56:57]
	s_mov_b32 m0, s40
	v_lshl_add_u64 v[218:219], s[38:39], 0, v[164:165]
	global_load_lds_dwordx4 v226, s[4:5]
	s_add_i32 m0, s40, 0x2000
	s_nop 0
	global_load_lds_dwordx4 v162, s[4:5]
	v_lshl_add_u64 v[216:217], s[38:39], 0, v[166:167]
	s_mov_b32 m0, s66
	s_nop 0
	global_load_lds_dwordx4 v166, s[38:39]
	s_mov_b32 m0, s68
	s_nop 0
	global_load_lds_dwordx4 v164, s[38:39]
	s_waitcnt vmcnt(8)
	s_waitcnt lgkmcnt(0)
	s_setprio 1
	s_barrier
	v_mfma_f32_16x16x32_bf16 v[62:65], v[66:69], v[172:175], v[62:65]
	v_mfma_f32_16x16x32_bf16 v[58:61], v[74:77], v[172:175], v[58:61]
	v_mfma_f32_16x16x32_bf16 v[46:49], v[66:69], v[188:191], v[46:49]
	v_mfma_f32_16x16x32_bf16 v[42:45], v[74:77], v[188:191], v[42:45]
	v_mfma_f32_16x16x32_bf16 v[30:33], v[66:69], v[196:199], v[30:33]
	v_mfma_f32_16x16x32_bf16 v[26:29], v[74:77], v[196:199], v[26:29]
	v_mfma_f32_16x16x32_bf16 v[14:17], v[66:69], v[204:207], v[14:17]
	v_mfma_f32_16x16x32_bf16 v[10:13], v[74:77], v[204:207], v[10:13]
	v_mfma_f32_16x16x32_bf16 v[62:65], v[70:73], v[184:187], v[62:65]
	v_mfma_f32_16x16x32_bf16 v[58:61], v[78:81], v[184:187], v[58:61]
	v_mfma_f32_16x16x32_bf16 v[46:49], v[70:73], v[192:195], v[46:49]
	v_mfma_f32_16x16x32_bf16 v[42:45], v[78:81], v[192:195], v[42:45]
	v_mfma_f32_16x16x32_bf16 v[30:33], v[70:73], v[200:203], v[30:33]
	v_mfma_f32_16x16x32_bf16 v[26:29], v[78:81], v[200:203], v[26:29]
	v_mfma_f32_16x16x32_bf16 v[14:17], v[70:73], v[208:211], v[14:17]
	v_mfma_f32_16x16x32_bf16 v[10:13], v[78:81], v[208:211], v[10:13]
	v_mfma_f32_16x16x32_bf16 v[54:57], v[82:85], v[172:175], v[54:57]
	v_mfma_f32_16x16x32_bf16 v[50:53], v[90:93], v[172:175], v[50:53]
	v_mfma_f32_16x16x32_bf16 v[38:41], v[82:85], v[188:191], v[38:41]
	v_mfma_f32_16x16x32_bf16 v[34:37], v[90:93], v[188:191], v[34:37]
	v_mfma_f32_16x16x32_bf16 v[22:25], v[82:85], v[196:199], v[22:25]
	v_mfma_f32_16x16x32_bf16 v[18:21], v[90:93], v[196:199], v[18:21]
	v_mfma_f32_16x16x32_bf16 v[6:9], v[82:85], v[204:207], v[6:9]
	v_mfma_f32_16x16x32_bf16 v[2:5], v[90:93], v[204:207], v[2:5]
	v_mfma_f32_16x16x32_bf16 v[54:57], v[86:89], v[184:187], v[54:57]
	v_mfma_f32_16x16x32_bf16 v[50:53], v[94:97], v[184:187], v[50:53]
	v_mfma_f32_16x16x32_bf16 v[38:41], v[86:89], v[192:195], v[38:41]
	v_mfma_f32_16x16x32_bf16 v[34:37], v[94:97], v[192:195], v[34:37]
	v_mfma_f32_16x16x32_bf16 v[22:25], v[86:89], v[200:203], v[22:25]
	v_mfma_f32_16x16x32_bf16 v[18:21], v[94:97], v[200:203], v[18:21]
	v_mfma_f32_16x16x32_bf16 v[6:9], v[86:89], v[208:211], v[6:9]
	v_mfma_f32_16x16x32_bf16 v[2:5], v[94:97], v[208:211], v[2:5]
	s_barrier
; #define PG8_STAGE(bufoff, gbase, voff) do { _Pragma("unroll") for (int _i = 0; _i < 2; ++_i) \
;         __builtin_amdgcn_global_load_lds((const unsigned*)((const char*)(gbase) + (voff)[_i]), (PG8_LAS unsigned*)(lds + (bufoff) + ldsw + _i * 8192), 16, 0, 0); } while (0)
; #define PG8_LDA(dst, b, h) do { _Pragma("unroll") for (int m = 0; m < 4; ++m) _Pragma("unroll") for (int k = 0; k < 2; ++k) dst[m][k] = *(const PG8_LAS bf16x8*)(lds + PG8_SA(b, h) + aoff + m * 2048 + k * 1024); } while (0)
; #define PG8_LDB(dst, b, h) do { _Pragma("unroll") for (int n = 0; n < 2; ++n) _Pragma("unroll") for (int k = 0; k < 2; ++k) dst[n][k] = *(const PG8_LAS bf16x8*)(lds + PG8_SB(b, h) + boff + n * 2048 + k * 1024); } while (0)
; #define PG8_MMA(ai, bj, At, Bt) do { __builtin_amdgcn_s_setprio(1); _Pragma("unroll") for (int m = 0; m < 4; ++m) _Pragma("unroll") for (int n = 0; n < 2; ++n) _Pragma("unroll") for (int k = 0; k < 2; ++k) \
;         acc[ai][bj][m][n] = __builtin_amdgcn_mfma_f32_16x16x32_bf16(Bt[n][k], At[m][k], acc[ai][bj][m][n], 0, 0, 0); __builtin_amdgcn_s_setprio(0); } while (0)
; #define PG8_WAIT_V(n) asm volatile("s_waitcnt vmcnt(" #n ")" ::: "memory")
; #define PG8_WAIT_L(n) asm volatile("s_waitcnt lgkmcnt(" #n ")" ::: "memory")
; #define PG8_BAR __builtin_amdgcn_s_barrier()
; #define PG8_SCHED __builtin_amdgcn_sched_barrier(0)
; template <class Prob, class Epi, class Sched>
; __device__ __forceinline__ void gemm_phase(PG8_LAS unsigned char* lds, const Prob g, const Sched& S, const Epi& E) {
;     ...
;             PG8_LDB(B0, 1, 0); PG8_LDB(B1, 1, 1); PG8_SCHED; PG8_LDA(At, 1, 0); PG8_STAGE(PG8_SA(0, 1), a2 + hstepA, voffA);
;             PG8_WAIT_V(8); PG8_WAIT_L(0); PG8_BAR; PG8_MMA(0, 0, At, B0); PG8_MMA(0, 1, At, B1); PG8_BAR; PG8_SCHED;
;             PG8_LDA(At, 1, 1); PG8_STAGE(PG8_SB(1, 0), b3, voffB); PG8_STAGE(PG8_SB(1, 1), b3 + hstepB, voffB); PG8_STAGE(PG8_SA(1, 0), a3, voffA);
;             PG8_WAIT_V(8); PG8_WAIT_L(0); PG8_BAR; PG8_MMA(1, 0, At, B0); PG8_MMA(1, 1, At, B1); PG8_BAR; PG8_SCHED;
;         }
;         if (wr == 0) PG8_BAR;
	s_setprio 0
	s_add_i32 s40, 0, 0x18000
	v_add_u32_e32 v1, s40, v177
	s_add_i32 s41, 0, 0x1c000
	ds_read_b128 v[66:69], v1
	ds_read_b128 v[70:73], v1 offset:1024
	ds_read_b128 v[74:77], v1 offset:2048
	ds_read_b128 v[78:81], v1 offset:3072
	v_add_u32_e32 v1, s41, v177
	ds_read_b128 v[82:85], v1
	ds_read_b128 v[86:89], v1 offset:1024
	ds_read_b128 v[90:93], v1 offset:2048
	ds_read_b128 v[94:97], v1 offset:3072
	s_add_u32 s4, s38, 0x80000
	s_addc_u32 s5, s39, 0
	s_mov_b32 m0, s69
	ds_read_b128 v[172:175], v180 offset:32768
	ds_read_b128 v[184:187], v180 offset:33792
	ds_read_b128 v[188:191], v180 offset:34816
	ds_read_b128 v[192:195], v180 offset:35840
	ds_read_b128 v[196:199], v180 offset:36864
	ds_read_b128 v[200:203], v180 offset:37888
	ds_read_b128 v[204:207], v180 offset:38912
	ds_read_b128 v[208:211], v180 offset:39936
	global_load_lds_dwordx4 v166, s[4:5]
	s_mov_b32 m0, s71
	s_nop 0
	global_load_lds_dwordx4 v164, s[4:5]
	s_waitcnt vmcnt(8)
	s_waitcnt lgkmcnt(0)
	s_setprio 1
	s_barrier
	v_mfma_f32_16x16x32_bf16 v[158:161], v[66:69], v[172:175], v[158:161]
	v_mfma_f32_16x16x32_bf16 v[154:157], v[74:77], v[172:175], v[154:157]
	v_mfma_f32_16x16x32_bf16 v[142:145], v[66:69], v[188:191], v[142:145]
	v_mfma_f32_16x16x32_bf16 v[138:141], v[74:77], v[188:191], v[138:141]
	v_mfma_f32_16x16x32_bf16 v[126:129], v[66:69], v[196:199], v[126:129]
	v_mfma_f32_16x16x32_bf16 v[122:125], v[74:77], v[196:199], v[122:125]
	v_mfma_f32_16x16x32_bf16 v[110:113], v[66:69], v[204:207], v[110:113]
	v_mfma_f32_16x16x32_bf16 v[106:109], v[74:77], v[204:207], v[106:109]
	v_mfma_f32_16x16x32_bf16 v[158:161], v[70:73], v[184:187], v[158:161]
	v_mfma_f32_16x16x32_bf16 v[154:157], v[78:81], v[184:187], v[154:157]
	v_mfma_f32_16x16x32_bf16 v[142:145], v[70:73], v[192:195], v[142:145]
	v_mfma_f32_16x16x32_bf16 v[138:141], v[78:81], v[192:195], v[138:141]
	v_mfma_f32_16x16x32_bf16 v[126:129], v[70:73], v[200:203], v[126:129]
	v_mfma_f32_16x16x32_bf16 v[122:125], v[78:81], v[200:203], v[122:125]
	v_mfma_f32_16x16x32_bf16 v[110:113], v[70:73], v[208:211], v[110:113]
	v_mfma_f32_16x16x32_bf16 v[106:109], v[78:81], v[208:211], v[106:109]
	v_mfma_f32_16x16x32_bf16 v[150:153], v[82:85], v[172:175], v[150:153]
	v_mfma_f32_16x16x32_bf16 v[146:149], v[90:93], v[172:175], v[146:149]
	v_mfma_f32_16x16x32_bf16 v[134:137], v[82:85], v[188:191], v[134:137]
	v_mfma_f32_16x16x32_bf16 v[130:133], v[90:93], v[188:191], v[130:133]
	v_mfma_f32_16x16x32_bf16 v[118:121], v[82:85], v[196:199], v[118:121]
	v_mfma_f32_16x16x32_bf16 v[114:117], v[90:93], v[196:199], v[114:117]
	v_mfma_f32_16x16x32_bf16 v[102:105], v[82:85], v[204:207], v[102:105]
	v_mfma_f32_16x16x32_bf16 v[98:101], v[90:93], v[204:207], v[98:101]
	v_mfma_f32_16x16x32_bf16 v[150:153], v[86:89], v[184:187], v[150:153]
	v_mfma_f32_16x16x32_bf16 v[146:149], v[94:97], v[184:187], v[146:149]
	v_mfma_f32_16x16x32_bf16 v[134:137], v[86:89], v[192:195], v[134:137]
	v_mfma_f32_16x16x32_bf16 v[130:133], v[94:97], v[192:195], v[130:133]
	v_mfma_f32_16x16x32_bf16 v[118:121], v[86:89], v[200:203], v[118:121]
	v_mfma_f32_16x16x32_bf16 v[114:117], v[94:97], v[200:203], v[114:117]
	v_mfma_f32_16x16x32_bf16 v[102:105], v[86:89], v[208:211], v[102:105]
	v_mfma_f32_16x16x32_bf16 v[98:101], v[94:97], v[208:211], v[98:101]
	s_barrier
	s_setprio 0
	s_add_i32 s4, s40, s64
	s_mov_b32 m0, s4
	ds_read_b128 v[172:175], v180 offset:49152
	ds_read_b128 v[184:187], v180 offset:50176
	ds_read_b128 v[188:191], v180 offset:51200
	ds_read_b128 v[192:195], v180 offset:52224
	ds_read_b128 v[196:199], v180 offset:53248
	ds_read_b128 v[200:203], v180 offset:54272
	ds_read_b128 v[204:207], v180 offset:55296
	ds_read_b128 v[208:211], v180 offset:56320
	s_add_u32 s100, s56, 0x80
	s_addc_u32 s101, s57, 0
	global_load_lds_dwordx4 v226, s[100:101]
	s_add_i32 m0, s4, 0x2000
	s_add_u32 s4, s56, 0x80080
	s_addc_u32 s5, s57, 0
	s_add_i32 s38, s41, s64
	global_load_lds_dwordx4 v162, s[100:101]
	s_mov_b32 m0, s38
	s_nop 0
	global_load_lds_dwordx4 v226, s[4:5]
	s_add_i32 m0, s38, 0x2000
	s_nop 0
	global_load_lds_dwordx4 v162, s[4:5]
	v_lshl_add_u64 v[212:213], v[216:217], 0, s[88:89]
	s_mov_b32 m0, s73
	s_nop 0
	global_load_lds_dwordx4 v[212:213], off
	v_lshl_add_u64 v[212:213], v[218:219], 0, s[88:89]
	s_mov_b32 m0, s74
	s_nop 0
	global_load_lds_dwordx4 v[212:213], off
	s_waitcnt vmcnt(8)
	s_waitcnt lgkmcnt(0)
	s_setprio 1
	s_barrier
	v_mfma_f32_16x16x32_bf16 v[62:65], v[66:69], v[172:175], v[62:65]
	v_mfma_f32_16x16x32_bf16 v[58:61], v[74:77], v[172:175], v[58:61]
	v_mfma_f32_16x16x32_bf16 v[46:49], v[66:69], v[188:191], v[46:49]
	v_mfma_f32_16x16x32_bf16 v[42:45], v[74:77], v[188:191], v[42:45]
	v_mfma_f32_16x16x32_bf16 v[30:33], v[66:69], v[196:199], v[30:33]
	v_mfma_f32_16x16x32_bf16 v[26:29], v[74:77], v[196:199], v[26:29]
	v_mfma_f32_16x16x32_bf16 v[14:17], v[66:69], v[204:207], v[14:17]
	v_mfma_f32_16x16x32_bf16 v[10:13], v[74:77], v[204:207], v[10:13]
	v_mfma_f32_16x16x32_bf16 v[62:65], v[70:73], v[184:187], v[62:65]
	v_mfma_f32_16x16x32_bf16 v[58:61], v[78:81], v[184:187], v[58:61]
	v_mfma_f32_16x16x32_bf16 v[46:49], v[70:73], v[192:195], v[46:49]
	v_mfma_f32_16x16x32_bf16 v[42:45], v[78:81], v[192:195], v[42:45]
	v_mfma_f32_16x16x32_bf16 v[30:33], v[70:73], v[200:203], v[30:33]
	v_mfma_f32_16x16x32_bf16 v[26:29], v[78:81], v[200:203], v[26:29]
	v_mfma_f32_16x16x32_bf16 v[14:17], v[70:73], v[208:211], v[14:17]
	v_mfma_f32_16x16x32_bf16 v[10:13], v[78:81], v[208:211], v[10:13]
	v_mfma_f32_16x16x32_bf16 v[54:57], v[82:85], v[172:175], v[54:57]
	v_mfma_f32_16x16x32_bf16 v[50:53], v[90:93], v[172:175], v[50:53]
	v_mfma_f32_16x16x32_bf16 v[38:41], v[82:85], v[188:191], v[38:41]
	v_mfma_f32_16x16x32_bf16 v[34:37], v[90:93], v[188:191], v[34:37]
	v_mfma_f32_16x16x32_bf16 v[22:25], v[82:85], v[196:199], v[22:25]
	v_mfma_f32_16x16x32_bf16 v[18:21], v[90:93], v[196:199], v[18:21]
	v_mfma_f32_16x16x32_bf16 v[6:9], v[82:85], v[204:207], v[6:9]
	v_mfma_f32_16x16x32_bf16 v[2:5], v[90:93], v[204:207], v[2:5]
	v_mfma_f32_16x16x32_bf16 v[54:57], v[86:89], v[184:187], v[54:57]
	v_mfma_f32_16x16x32_bf16 v[50:53], v[94:97], v[184:187], v[50:53]
	v_mfma_f32_16x16x32_bf16 v[38:41], v[86:89], v[192:195], v[38:41]
	v_mfma_f32_16x16x32_bf16 v[34:37], v[94:97], v[192:195], v[34:37]
	v_mfma_f32_16x16x32_bf16 v[22:25], v[86:89], v[200:203], v[22:25]
	v_mfma_f32_16x16x32_bf16 v[18:21], v[94:97], v[200:203], v[18:21]
	v_mfma_f32_16x16x32_bf16 v[6:9], v[86:89], v[208:211], v[6:9]
	v_mfma_f32_16x16x32_bf16 v[2:5], v[94:97], v[208:211], v[2:5]
	s_barrier
	s_setprio 0
	s_add_i32 vcc_hi, vcc_hi, 2
	s_add_u32 s54, s54, 0x100
	s_addc_u32 s55, s55, 0
	s_add_u32 s45, s45, 0x100
	s_addc_u32 vcc_lo, vcc_lo, 0
	s_cmp_gt_u32 vcc_hi, 29
	s_cbranch_scc0 .LBB0_867
	s_and_b64 vcc, exec, s[28:29]
	s_cbranch_vccz .LBB0_870
	s_barrier

; #define PG8_STAGE(bufoff, gbase, voff) do { _Pragma("unroll") for (int _i = 0; _i < 2; ++_i) \
;         __builtin_amdgcn_global_load_lds((const unsigned*)((const char*)(gbase) + (voff)[_i]), (PG8_LAS unsigned*)(lds + (bufoff) + ldsw + _i * 8192), 16, 0, 0); } while (0)
; #define PG8_LDA(dst, b, h) do { _Pragma("unroll") for (int m = 0; m < 4; ++m) _Pragma("unroll") for (int k = 0; k < 2; ++k) dst[m][k] = *(const PG8_LAS bf16x8*)(lds + PG8_SA(b, h) + aoff + m * 2048 + k * 1024); } while (0)
; #define PG8_LDB(dst, b, h) do { _Pragma("unroll") for (int n = 0; n < 2; ++n) _Pragma("unroll") for (int k = 0; k < 2; ++k) dst[n][k] = *(const PG8_LAS bf16x8*)(lds + PG8_SB(b, h) + boff + n * 2048 + k * 1024); } while (0)
; #define PG8_MMA(ai, bj, At, Bt) do { __builtin_amdgcn_s_setprio(1); _Pragma("unroll") for (int m = 0; m < 4; ++m) _Pragma("unroll") for (int n = 0; n < 2; ++n) _Pragma("unroll") for (int k = 0; k < 2; ++k) \
;         acc[ai][bj][m][n] = __builtin_amdgcn_mfma_f32_16x16x32_bf16(Bt[n][k], At[m][k], acc[ai][bj][m][n], 0, 0, 0); __builtin_amdgcn_s_setprio(0); } while (0)
; #define PG8_WAIT_V(n) asm volatile("s_waitcnt vmcnt(" #n ")" ::: "memory")
; #define PG8_WAIT_L(n) asm volatile("s_waitcnt lgkmcnt(" #n ")" ::: "memory")
; #define PG8_BAR __builtin_amdgcn_s_barrier()
; #define PG8_SCHED __builtin_amdgcn_sched_barrier(0)
; template <class Prob, class Epi, class Sched>
; __device__ __forceinline__ void gemm_phase(PG8_LAS unsigned char* lds, const Prob g, const Sched& S, const Epi& E) {
;     ...
;             const bool last = (t == nt - 2);
;             const char* a1 = cA + (size_t)(t + 1) * kstep;
;             const char* a2 = last ? nA : cA + (size_t)(t + 2) * kstep; const char* b2 = last ? nB : cB + (size_t)(t + 2) * kstep;
;             const char* a3 = a2 + kstep; const char* b3 = b2 + kstep;
;             PG8_LDB(B0, 0, 0); PG8_LDB(B1, 0, 1); PG8_SCHED; PG8_LDA(At, 0, 0); PG8_STAGE(PG8_SA(1, 1), a1 + hstepA, voffA);
;             PG8_WAIT_V(8); PG8_WAIT_L(0); PG8_BAR; PG8_MMA(0, 0, At, B0); PG8_MMA(0, 1, At, B1); PG8_BAR; PG8_SCHED;
;             PG8_LDA(At, 0, 1); PG8_STAGE(PG8_SB(0, 0), b2, voffB); PG8_STAGE(PG8_SB(0, 1), b2 + hstepB, voffB); PG8_STAGE(PG8_SA(0, 0), a2, voffA);
;             PG8_WAIT_V(8); PG8_WAIT_L(0); PG8_BAR; PG8_MMA(1, 0, At, B0); PG8_MMA(1, 1, At, B1); PG8_BAR; PG8_SCHED;
.LBB0_953:
	s_add_u32 s4, s30, 0xfff80080
	s_addc_u32 s5, s31, -1
	s_add_i32 s40, 0, 0x10000
	s_cmp_eq_u32 s69, 28
	s_cselect_b32 s37, s25, s5
	s_cselect_b32 s36, s66, s4
	v_add_u32_e32 v1, s40, v207
	s_cselect_b32 s35, s23, s68
	s_cselect_b32 s34, s44, s45
	s_add_i32 s41, 0, 0x14000
	ds_read_b128 v[54:57], v1
	ds_read_b128 v[62:65], v1 offset:1024
	ds_read_b128 v[66:69], v1 offset:2048
	ds_read_b128 v[70:73], v1 offset:3072
	v_add_u32_e32 v1, s41, v207
	ds_read_b128 v[78:81], v1
	ds_read_b128 v[82:85], v1 offset:1024
	ds_read_b128 v[90:93], v1 offset:2048
	ds_read_b128 v[94:97], v1 offset:3072
	s_add_i32 m0, s51, 0xc000
	ds_read_b128 v[172:175], v209
	ds_read_b128 v[176:179], v209 offset:1024
	ds_read_b128 v[180:183], v209 offset:2048
	ds_read_b128 v[184:187], v209 offset:3072
	ds_read_b128 v[188:191], v209 offset:4096
	ds_read_b128 v[192:195], v209 offset:5120
	ds_read_b128 v[196:199], v209 offset:6144
	ds_read_b128 v[200:203], v209 offset:7168
	global_load_lds_dwordx4 v168, s[30:31]
	s_add_i32 m0, s51, 0xe000
	s_nop 0
	global_load_lds_dwordx4 v170, s[30:31]
	s_waitcnt vmcnt(8)
	s_waitcnt lgkmcnt(0)
	s_setprio 1
	s_barrier
	v_mfma_f32_16x16x32_bf16 v[158:161], v[54:57], v[172:175], v[158:161]
	v_mfma_f32_16x16x32_bf16 v[150:153], v[66:69], v[172:175], v[150:153]
	v_mfma_f32_16x16x32_bf16 v[142:145], v[54:57], v[180:183], v[142:145]
	v_mfma_f32_16x16x32_bf16 v[134:137], v[66:69], v[180:183], v[134:137]
	v_mfma_f32_16x16x32_bf16 v[126:129], v[54:57], v[188:191], v[126:129]
	v_mfma_f32_16x16x32_bf16 v[118:121], v[66:69], v[188:191], v[118:121]
	v_mfma_f32_16x16x32_bf16 v[110:113], v[54:57], v[196:199], v[110:113]
	v_mfma_f32_16x16x32_bf16 v[102:105], v[66:69], v[196:199], v[102:105]
	v_mfma_f32_16x16x32_bf16 v[158:161], v[62:65], v[176:179], v[158:161]
	v_mfma_f32_16x16x32_bf16 v[150:153], v[70:73], v[176:179], v[150:153]
	v_mfma_f32_16x16x32_bf16 v[142:145], v[62:65], v[184:187], v[142:145]
	v_mfma_f32_16x16x32_bf16 v[134:137], v[70:73], v[184:187], v[134:137]
	v_mfma_f32_16x16x32_bf16 v[126:129], v[62:65], v[192:195], v[126:129]
	v_mfma_f32_16x16x32_bf16 v[118:121], v[70:73], v[192:195], v[118:121]
	v_mfma_f32_16x16x32_bf16 v[110:113], v[62:65], v[200:203], v[110:113]
	v_mfma_f32_16x16x32_bf16 v[102:105], v[70:73], v[200:203], v[102:105]
	v_mfma_f32_16x16x32_bf16 v[154:157], v[78:81], v[172:175], v[154:157]
	v_mfma_f32_16x16x32_bf16 v[146:149], v[90:93], v[172:175], v[146:149]
	v_mfma_f32_16x16x32_bf16 v[138:141], v[78:81], v[180:183], v[138:141]
	v_mfma_f32_16x16x32_bf16 v[130:133], v[90:93], v[180:183], v[130:133]
	v_mfma_f32_16x16x32_bf16 v[122:125], v[78:81], v[188:191], v[122:125]
	v_mfma_f32_16x16x32_bf16 v[114:117], v[90:93], v[188:191], v[114:117]
	v_mfma_f32_16x16x32_bf16 v[106:109], v[78:81], v[196:199], v[106:109]
	v_mfma_f32_16x16x32_bf16 v[98:101], v[90:93], v[196:199], v[98:101]
	v_mfma_f32_16x16x32_bf16 v[154:157], v[82:85], v[176:179], v[154:157]
	v_mfma_f32_16x16x32_bf16 v[146:149], v[94:97], v[176:179], v[146:149]
	v_mfma_f32_16x16x32_bf16 v[138:141], v[82:85], v[184:187], v[138:141]
	v_mfma_f32_16x16x32_bf16 v[130:133], v[94:97], v[184:187], v[130:133]
	v_mfma_f32_16x16x32_bf16 v[122:125], v[82:85], v[192:195], v[122:125]
	v_mfma_f32_16x16x32_bf16 v[114:117], v[94:97], v[192:195], v[114:117]
	v_mfma_f32_16x16x32_bf16 v[106:109], v[82:85], v[200:203], v[106:109]
	v_mfma_f32_16x16x32_bf16 v[98:101], v[94:97], v[200:203], v[98:101]
	s_barrier
	s_setprio 0
	s_add_i32 s4, s40, s43
	s_mov_b32 m0, s4
	ds_read_b128 v[172:175], v209 offset:16384
	ds_read_b128 v[176:179], v209 offset:17408
	ds_read_b128 v[180:183], v209 offset:18432
	ds_read_b128 v[184:187], v209 offset:19456
	ds_read_b128 v[188:191], v209 offset:20480
	ds_read_b128 v[192:195], v209 offset:21504
	ds_read_b128 v[196:199], v209 offset:22528
	ds_read_b128 v[200:203], v209 offset:23552
	global_load_lds_dwordx4 v226, s[34:35]
	s_add_i32 m0, s4, 0x2000
	s_add_u32 s4, s34, 0x80000
	s_addc_u32 s5, s35, 0
	s_add_i32 s40, s41, s43
	global_load_lds_dwordx4 v162, s[34:35]
	s_mov_b32 m0, s40
	s_nop 0
	global_load_lds_dwordx4 v226, s[4:5]
	s_add_i32 m0, s40, 0x2000
	s_nop 0
	global_load_lds_dwordx4 v162, s[4:5]
	s_mov_b32 m0, s51
	s_nop 0
	global_load_lds_dwordx4 v166, s[36:37]
	s_mov_b32 m0, s52
	s_nop 0
	global_load_lds_dwordx4 v164, s[36:37]
	s_waitcnt vmcnt(8)
	s_waitcnt lgkmcnt(0)
	s_setprio 1
	s_barrier
	v_mfma_f32_16x16x32_bf16 v[86:89], v[54:57], v[172:175], v[86:89]
	v_mfma_f32_16x16x32_bf16 v[58:61], v[66:69], v[172:175], v[58:61]
	v_mfma_f32_16x16x32_bf16 v[46:49], v[54:57], v[180:183], v[46:49]
	v_mfma_f32_16x16x32_bf16 v[38:41], v[66:69], v[180:183], v[38:41]
	v_mfma_f32_16x16x32_bf16 v[30:33], v[54:57], v[188:191], v[30:33]
	v_mfma_f32_16x16x32_bf16 v[22:25], v[66:69], v[188:191], v[22:25]
	v_mfma_f32_16x16x32_bf16 v[14:17], v[54:57], v[196:199], v[14:17]
	v_mfma_f32_16x16x32_bf16 v[6:9], v[66:69], v[196:199], v[6:9]
	v_mfma_f32_16x16x32_bf16 v[86:89], v[62:65], v[176:179], v[86:89]
	v_mfma_f32_16x16x32_bf16 v[58:61], v[70:73], v[176:179], v[58:61]
	v_mfma_f32_16x16x32_bf16 v[46:49], v[62:65], v[184:187], v[46:49]
	v_mfma_f32_16x16x32_bf16 v[38:41], v[70:73], v[184:187], v[38:41]
	v_mfma_f32_16x16x32_bf16 v[30:33], v[62:65], v[192:195], v[30:33]
	v_mfma_f32_16x16x32_bf16 v[22:25], v[70:73], v[192:195], v[22:25]
	v_mfma_f32_16x16x32_bf16 v[14:17], v[62:65], v[200:203], v[14:17]
	v_mfma_f32_16x16x32_bf16 v[6:9], v[70:73], v[200:203], v[6:9]
	v_mfma_f32_16x16x32_bf16 v[50:53], v[90:93], v[172:175], v[50:53]
	v_mfma_f32_16x16x32_bf16 v[42:45], v[78:81], v[180:183], v[42:45]
	v_mfma_f32_16x16x32_bf16 v[34:37], v[90:93], v[180:183], v[34:37]
	v_mfma_f32_16x16x32_bf16 v[26:29], v[78:81], v[188:191], v[26:29]
	v_mfma_f32_16x16x32_bf16 v[18:21], v[90:93], v[188:191], v[18:21]
	v_mfma_f32_16x16x32_bf16 v[10:13], v[78:81], v[196:199], v[10:13]
	v_mfma_f32_16x16x32_bf16 v[2:5], v[90:93], v[196:199], v[2:5]
	v_mfma_f32_16x16x32_bf16 v[54:57], v[78:81], v[172:175], v[74:77]
	v_mfma_f32_16x16x32_bf16 v[50:53], v[94:97], v[176:179], v[50:53]
	v_mfma_f32_16x16x32_bf16 v[42:45], v[82:85], v[184:187], v[42:45]
	v_mfma_f32_16x16x32_bf16 v[34:37], v[94:97], v[184:187], v[34:37]
	v_mfma_f32_16x16x32_bf16 v[26:29], v[82:85], v[192:195], v[26:29]
	v_mfma_f32_16x16x32_bf16 v[18:21], v[94:97], v[192:195], v[18:21]
	v_mfma_f32_16x16x32_bf16 v[10:13], v[82:85], v[200:203], v[10:13]
	v_mfma_f32_16x16x32_bf16 v[2:5], v[94:97], v[200:203], v[2:5]
	v_mfma_f32_16x16x32_bf16 v[54:57], v[82:85], v[176:179], v[54:57]
	s_barrier
; #define PG8_STAGE(bufoff, gbase, voff) do { _Pragma("unroll") for (int _i = 0; _i < 2; ++_i) \
;         __builtin_amdgcn_global_load_lds((const unsigned*)((const char*)(gbase) + (voff)[_i]), (PG8_LAS unsigned*)(lds + (bufoff) + ldsw + _i * 8192), 16, 0, 0); } while (0)
; #define PG8_LDA(dst, b, h) do { _Pragma("unroll") for (int m = 0; m < 4; ++m) _Pragma("unroll") for (int k = 0; k < 2; ++k) dst[m][k] = *(const PG8_LAS bf16x8*)(lds + PG8_SA(b, h) + aoff + m * 2048 + k * 1024); } while (0)
; #define PG8_LDB(dst, b, h) do { _Pragma("unroll") for (int n = 0; n < 2; ++n) _Pragma("unroll") for (int k = 0; k < 2; ++k) dst[n][k] = *(const PG8_LAS bf16x8*)(lds + PG8_SB(b, h) + boff + n * 2048 + k * 1024); } while (0)
; #define PG8_MMA(ai, bj, At, Bt) do { __builtin_amdgcn_s_setprio(1); _Pragma("unroll") for (int m = 0; m < 4; ++m) _Pragma("unroll") for (int n = 0; n < 2; ++n) _Pragma("unroll") for (int k = 0; k < 2; ++k) \
;         acc[ai][bj][m][n] = __builtin_amdgcn_mfma_f32_16x16x32_bf16(Bt[n][k], At[m][k], acc[ai][bj][m][n], 0, 0, 0); __builtin_amdgcn_s_setprio(0); } while (0)
; #define PG8_WAIT_V(n) asm volatile("s_waitcnt vmcnt(" #n ")" ::: "memory")
; #define PG8_WAIT_L(n) asm volatile("s_waitcnt lgkmcnt(" #n ")" ::: "memory")
; #define PG8_BAR __builtin_amdgcn_s_barrier()
; #define PG8_SCHED __builtin_amdgcn_sched_barrier(0)
; template <class Prob, class Epi, class Sched>
; __device__ __forceinline__ void gemm_phase(PG8_LAS unsigned char* lds, const Prob g, const Sched& S, const Epi& E) {
;     ...
;             PG8_LDB(B0, 1, 0); PG8_LDB(B1, 1, 1); PG8_SCHED; PG8_LDA(At, 1, 0); PG8_STAGE(PG8_SA(0, 1), a2 + hstepA, voffA);
;             PG8_WAIT_V(8); PG8_WAIT_L(0); PG8_BAR; PG8_MMA(0, 0, At, B0); PG8_MMA(0, 1, At, B1); PG8_BAR; PG8_SCHED;
;             PG8_LDA(At, 1, 1); PG8_STAGE(PG8_SB(1, 0), b3, voffB); PG8_STAGE(PG8_SB(1, 1), b3 + hstepB, voffB); PG8_STAGE(PG8_SA(1, 0), a3, voffA);
;             PG8_WAIT_V(8); PG8_WAIT_L(0); PG8_BAR; PG8_MMA(1, 0, At, B0); PG8_MMA(1, 1, At, B1); PG8_BAR; PG8_SCHED;
;         }
;         if (wr == 0) PG8_BAR;
	s_setprio 0
	s_add_i32 s40, 0, 0x18000
	v_add_u32_e32 v1, s40, v207
	s_add_i32 s41, 0, 0x1c000
	ds_read_b128 v[62:65], v1
	ds_read_b128 v[66:69], v1 offset:1024
	ds_read_b128 v[70:73], v1 offset:2048
	ds_read_b128 v[74:77], v1 offset:3072
	v_add_u32_e32 v1, s41, v207
	ds_read_b128 v[78:81], v1
	ds_read_b128 v[82:85], v1 offset:1024
	ds_read_b128 v[90:93], v1 offset:2048
	ds_read_b128 v[94:97], v1 offset:3072
	s_add_u32 s4, s36, 0x80000
	s_addc_u32 s5, s37, 0
	s_mov_b32 m0, s53
	ds_read_b128 v[172:175], v209 offset:32768
	ds_read_b128 v[176:179], v209 offset:33792
	ds_read_b128 v[180:183], v209 offset:34816
	ds_read_b128 v[184:187], v209 offset:35840
	ds_read_b128 v[188:191], v209 offset:36864
	ds_read_b128 v[192:195], v209 offset:37888
	ds_read_b128 v[196:199], v209 offset:38912
	ds_read_b128 v[200:203], v209 offset:39936
	global_load_lds_dwordx4 v166, s[4:5]
	s_mov_b32 m0, s54
	s_nop 0
	global_load_lds_dwordx4 v164, s[4:5]
	s_waitcnt vmcnt(8)
	s_waitcnt lgkmcnt(0)
	s_setprio 1
	s_barrier
	v_mfma_f32_16x16x32_bf16 v[158:161], v[62:65], v[172:175], v[158:161]
	v_mfma_f32_16x16x32_bf16 v[150:153], v[70:73], v[172:175], v[150:153]
	v_mfma_f32_16x16x32_bf16 v[142:145], v[62:65], v[180:183], v[142:145]
	v_mfma_f32_16x16x32_bf16 v[134:137], v[70:73], v[180:183], v[134:137]
	v_mfma_f32_16x16x32_bf16 v[126:129], v[62:65], v[188:191], v[126:129]
	v_mfma_f32_16x16x32_bf16 v[118:121], v[70:73], v[188:191], v[118:121]
	v_mfma_f32_16x16x32_bf16 v[110:113], v[62:65], v[196:199], v[110:113]
	v_mfma_f32_16x16x32_bf16 v[102:105], v[70:73], v[196:199], v[102:105]
	v_mfma_f32_16x16x32_bf16 v[158:161], v[66:69], v[176:179], v[158:161]
	v_mfma_f32_16x16x32_bf16 v[150:153], v[74:77], v[176:179], v[150:153]
	v_mfma_f32_16x16x32_bf16 v[142:145], v[66:69], v[184:187], v[142:145]
	v_mfma_f32_16x16x32_bf16 v[134:137], v[74:77], v[184:187], v[134:137]
	v_mfma_f32_16x16x32_bf16 v[126:129], v[66:69], v[192:195], v[126:129]
	v_mfma_f32_16x16x32_bf16 v[118:121], v[74:77], v[192:195], v[118:121]
	v_mfma_f32_16x16x32_bf16 v[110:113], v[66:69], v[200:203], v[110:113]
	v_mfma_f32_16x16x32_bf16 v[102:105], v[74:77], v[200:203], v[102:105]
	v_mfma_f32_16x16x32_bf16 v[154:157], v[78:81], v[172:175], v[154:157]
	v_mfma_f32_16x16x32_bf16 v[146:149], v[90:93], v[172:175], v[146:149]
	v_mfma_f32_16x16x32_bf16 v[138:141], v[78:81], v[180:183], v[138:141]
	v_mfma_f32_16x16x32_bf16 v[130:133], v[90:93], v[180:183], v[130:133]
	v_mfma_f32_16x16x32_bf16 v[122:125], v[78:81], v[188:191], v[122:125]
	v_mfma_f32_16x16x32_bf16 v[114:117], v[90:93], v[188:191], v[114:117]
	v_mfma_f32_16x16x32_bf16 v[106:109], v[78:81], v[196:199], v[106:109]
	v_mfma_f32_16x16x32_bf16 v[98:101], v[90:93], v[196:199], v[98:101]
	v_mfma_f32_16x16x32_bf16 v[154:157], v[82:85], v[176:179], v[154:157]
	v_mfma_f32_16x16x32_bf16 v[146:149], v[94:97], v[176:179], v[146:149]
	v_mfma_f32_16x16x32_bf16 v[138:141], v[82:85], v[184:187], v[138:141]
	v_mfma_f32_16x16x32_bf16 v[130:133], v[94:97], v[184:187], v[130:133]
	v_mfma_f32_16x16x32_bf16 v[122:125], v[82:85], v[192:195], v[122:125]
	v_mfma_f32_16x16x32_bf16 v[114:117], v[94:97], v[192:195], v[114:117]
	v_mfma_f32_16x16x32_bf16 v[106:109], v[82:85], v[200:203], v[106:109]
	v_mfma_f32_16x16x32_bf16 v[98:101], v[94:97], v[200:203], v[98:101]
	s_barrier
	s_setprio 0
	s_add_i32 s4, s40, s43
	s_mov_b32 m0, s4
	ds_read_b128 v[172:175], v209 offset:49152
	ds_read_b128 v[176:179], v209 offset:50176
	ds_read_b128 v[180:183], v209 offset:51200
	ds_read_b128 v[184:187], v209 offset:52224
	ds_read_b128 v[188:191], v209 offset:53248
	ds_read_b128 v[192:195], v209 offset:54272
	ds_read_b128 v[196:199], v209 offset:55296
	ds_read_b128 v[200:203], v209 offset:56320
	s_add_u32 s100, s34, 0x80
	s_addc_u32 s101, s35, 0
	global_load_lds_dwordx4 v226, s[100:101]
	s_add_i32 m0, s4, 0x2000
	s_add_u32 s4, s34, 0x80080
	s_addc_u32 s5, s35, 0
	s_add_i32 s34, s41, s43
	global_load_lds_dwordx4 v162, s[100:101]
	s_mov_b32 m0, s34
	s_nop 0
	global_load_lds_dwordx4 v226, s[4:5]
	s_add_i32 m0, s34, 0x2000
	s_nop 0
	global_load_lds_dwordx4 v162, s[4:5]
	s_mov_b32 m0, s55
	s_nop 0
	s_add_u32 s100, s36, 0x80
	s_addc_u32 s101, s37, 0
	global_load_lds_dwordx4 v166, s[100:101]
	s_mov_b32 m0, s56
	s_nop 0
	global_load_lds_dwordx4 v164, s[100:101]
	s_waitcnt vmcnt(8)
	s_waitcnt lgkmcnt(0)
	s_setprio 1
	s_barrier
	v_mfma_f32_16x16x32_bf16 v[86:89], v[62:65], v[172:175], v[86:89]
	v_mfma_f32_16x16x32_bf16 v[58:61], v[70:73], v[172:175], v[58:61]
	v_mfma_f32_16x16x32_bf16 v[46:49], v[62:65], v[180:183], v[46:49]
	v_mfma_f32_16x16x32_bf16 v[38:41], v[70:73], v[180:183], v[38:41]
	v_mfma_f32_16x16x32_bf16 v[30:33], v[62:65], v[188:191], v[30:33]
	v_mfma_f32_16x16x32_bf16 v[22:25], v[70:73], v[188:191], v[22:25]
	v_mfma_f32_16x16x32_bf16 v[14:17], v[62:65], v[196:199], v[14:17]
	v_mfma_f32_16x16x32_bf16 v[6:9], v[70:73], v[196:199], v[6:9]
	v_mfma_f32_16x16x32_bf16 v[86:89], v[66:69], v[176:179], v[86:89]
	v_mfma_f32_16x16x32_bf16 v[58:61], v[74:77], v[176:179], v[58:61]
	v_mfma_f32_16x16x32_bf16 v[46:49], v[66:69], v[184:187], v[46:49]
	v_mfma_f32_16x16x32_bf16 v[38:41], v[74:77], v[184:187], v[38:41]
	v_mfma_f32_16x16x32_bf16 v[30:33], v[66:69], v[192:195], v[30:33]
	v_mfma_f32_16x16x32_bf16 v[22:25], v[74:77], v[192:195], v[22:25]
	v_mfma_f32_16x16x32_bf16 v[14:17], v[66:69], v[200:203], v[14:17]
	v_mfma_f32_16x16x32_bf16 v[6:9], v[74:77], v[200:203], v[6:9]
	v_mfma_f32_16x16x32_bf16 v[54:57], v[78:81], v[172:175], v[54:57]
	v_mfma_f32_16x16x32_bf16 v[50:53], v[90:93], v[172:175], v[50:53]
	v_mfma_f32_16x16x32_bf16 v[42:45], v[78:81], v[180:183], v[42:45]
	v_mfma_f32_16x16x32_bf16 v[34:37], v[90:93], v[180:183], v[34:37]
	v_mfma_f32_16x16x32_bf16 v[26:29], v[78:81], v[188:191], v[26:29]
	v_mfma_f32_16x16x32_bf16 v[18:21], v[90:93], v[188:191], v[18:21]
	v_mfma_f32_16x16x32_bf16 v[10:13], v[78:81], v[196:199], v[10:13]
	v_mfma_f32_16x16x32_bf16 v[2:5], v[90:93], v[196:199], v[2:5]
	v_mfma_f32_16x16x32_bf16 v[74:77], v[82:85], v[176:179], v[54:57]
	v_mfma_f32_16x16x32_bf16 v[50:53], v[94:97], v[176:179], v[50:53]
	v_mfma_f32_16x16x32_bf16 v[42:45], v[82:85], v[184:187], v[42:45]
	v_mfma_f32_16x16x32_bf16 v[34:37], v[94:97], v[184:187], v[34:37]
	v_mfma_f32_16x16x32_bf16 v[26:29], v[82:85], v[192:195], v[26:29]
	v_mfma_f32_16x16x32_bf16 v[18:21], v[94:97], v[192:195], v[18:21]
	v_mfma_f32_16x16x32_bf16 v[10:13], v[82:85], v[200:203], v[10:13]
	v_mfma_f32_16x16x32_bf16 v[2:5], v[94:97], v[200:203], v[2:5]
	s_barrier
	s_setprio 0
	s_add_i32 s69, s69, 2
	s_add_u32 s30, s30, 0x100
	s_addc_u32 s31, s31, 0
	s_add_u32 s45, s45, 0x100
	s_addc_u32 s68, s68, 0
	s_cmp_gt_u32 s69, 29
	s_cbranch_scc0 .LBB0_953
	s_and_b64 vcc, exec, s[20:21]
	s_cbranch_vccz .LBB0_956
	s_barrier

; #define PG8_STAGE(bufoff, gbase, voff) do { _Pragma("unroll") for (int _i = 0; _i < 2; ++_i) \
;         __builtin_amdgcn_global_load_lds((const unsigned*)((const char*)(gbase) + (voff)[_i]), (PG8_LAS unsigned*)(lds + (bufoff) + ldsw + _i * 8192), 16, 0, 0); } while (0)
; #define PG8_LDA(dst, b, h) do { _Pragma("unroll") for (int m = 0; m < 4; ++m) _Pragma("unroll") for (int k = 0; k < 2; ++k) dst[m][k] = *(const PG8_LAS bf16x8*)(lds + PG8_SA(b, h) + aoff + m * 2048 + k * 1024); } while (0)
; #define PG8_LDB(dst, b, h) do { _Pragma("unroll") for (int n = 0; n < 2; ++n) _Pragma("unroll") for (int k = 0; k < 2; ++k) dst[n][k] = *(const PG8_LAS bf16x8*)(lds + PG8_SB(b, h) + boff + n * 2048 + k * 1024); } while (0)
; #define PG8_MMA(ai, bj, At, Bt) do { __builtin_amdgcn_s_setprio(1); _Pragma("unroll") for (int m = 0; m < 4; ++m) _Pragma("unroll") for (int n = 0; n < 2; ++n) _Pragma("unroll") for (int k = 0; k < 2; ++k) \
;         acc[ai][bj][m][n] = __builtin_amdgcn_mfma_f32_16x16x32_bf16(Bt[n][k], At[m][k], acc[ai][bj][m][n], 0, 0, 0); __builtin_amdgcn_s_setprio(0); } while (0)
; #define PG8_WAIT_V(n) asm volatile("s_waitcnt vmcnt(" #n ")" ::: "memory")
; #define PG8_WAIT_L(n) asm volatile("s_waitcnt lgkmcnt(" #n ")" ::: "memory")
; #define PG8_BAR __builtin_amdgcn_s_barrier()
; #define PG8_SCHED __builtin_amdgcn_sched_barrier(0)
; template <class Prob, class Epi, class Sched>
; __device__ __forceinline__ void gemm_phase(PG8_LAS unsigned char* lds, const Prob g, const Sched& S, const Epi& E) {
;     ...
;             const bool last = (t == nt - 2);
;             const char* a1 = cA + (size_t)(t + 1) * kstep;
;             const char* a2 = last ? nA : cA + (size_t)(t + 2) * kstep; const char* b2 = last ? nB : cB + (size_t)(t + 2) * kstep;
;             const char* a3 = a2 + kstep; const char* b3 = b2 + kstep;
;             PG8_LDB(B0, 0, 0); PG8_LDB(B1, 0, 1); PG8_SCHED; PG8_LDA(At, 0, 0); PG8_STAGE(PG8_SA(1, 1), a1 + hstepA, voffA);
;             PG8_WAIT_V(8); PG8_WAIT_L(0); PG8_BAR; PG8_MMA(0, 0, At, B0); PG8_MMA(0, 1, At, B1); PG8_BAR; PG8_SCHED;
;             PG8_LDA(At, 0, 1); PG8_STAGE(PG8_SB(0, 0), b2, voffB); PG8_STAGE(PG8_SB(0, 1), b2 + hstepB, voffB); PG8_STAGE(PG8_SA(0, 0), a2, voffA);
;             PG8_WAIT_V(8); PG8_WAIT_L(0); PG8_BAR; PG8_MMA(1, 0, At, B0); PG8_MMA(1, 1, At, B1); PG8_BAR; PG8_SCHED;
.LBB0_1021:
	s_add_u32 s28, s26, 0x100
	s_addc_u32 s29, s27, 0
	s_add_i32 s40, 0, 0x10000
	s_cmpk_eq_i32 s64, 0x54
	s_cselect_b32 s35, s7, s29
	s_cselect_b32 s34, s6, s28
	v_add_u32_e32 v1, s40, v223
	s_cselect_b32 s31, s25, s45
	s_cselect_b32 s30, s24, s44
	s_add_i32 s41, 0, 0x14000
	ds_read_b128 v[114:117], v1
	ds_read_b128 v[118:121], v1 offset:1024
	ds_read_b128 v[126:129], v1 offset:2048
	ds_read_b128 v[130:133], v1 offset:3072
	v_add_u32_e32 v1, s41, v223
	ds_read_b128 v[138:141], v1
	ds_read_b128 v[142:145], v1 offset:1024
	ds_read_b128 v[146:149], v1 offset:2048
	ds_read_b128 v[150:153], v1 offset:3072
	s_add_i32 m0, s39, 0xc000
	ds_read_b128 v[162:165], v225
	ds_read_b128 v[166:169], v225 offset:1024
	ds_read_b128 v[170:173], v225 offset:2048
	ds_read_b128 v[174:177], v225 offset:3072
	ds_read_b128 v[178:181], v225 offset:4096
	ds_read_b128 v[182:185], v225 offset:5120
	ds_read_b128 v[186:189], v225 offset:6144
	ds_read_b128 v[200:203], v225 offset:7168
	global_load_lds_dwordx4 v196, s[26:27]
	s_add_i32 m0, s39, 0xe000
	s_nop 0
	global_load_lds_dwordx4 v198, s[26:27]
	s_waitcnt vmcnt(8)
	s_waitcnt lgkmcnt(0)
	s_setprio 1
	s_barrier
	v_mfma_f32_16x16x32_bf16 v[158:161], v[114:117], v[162:165], v[158:161]
	v_mfma_f32_16x16x32_bf16 v[154:157], v[126:129], v[162:165], v[154:157]
	v_mfma_f32_16x16x32_bf16 v[110:113], v[114:117], v[170:173], v[110:113]
	v_mfma_f32_16x16x32_bf16 v[106:109], v[126:129], v[170:173], v[106:109]
	v_mfma_f32_16x16x32_bf16 v[94:97], v[114:117], v[178:181], v[94:97]
	v_mfma_f32_16x16x32_bf16 v[90:93], v[126:129], v[178:181], v[90:93]
	v_mfma_f32_16x16x32_bf16 v[78:81], v[114:117], v[186:189], v[78:81]
	v_mfma_f32_16x16x32_bf16 v[74:77], v[126:129], v[186:189], v[74:77]
	v_mfma_f32_16x16x32_bf16 v[158:161], v[118:121], v[166:169], v[158:161]
	v_mfma_f32_16x16x32_bf16 v[154:157], v[130:133], v[166:169], v[154:157]
	v_mfma_f32_16x16x32_bf16 v[110:113], v[118:121], v[174:177], v[110:113]
	v_mfma_f32_16x16x32_bf16 v[106:109], v[130:133], v[174:177], v[106:109]
	v_mfma_f32_16x16x32_bf16 v[94:97], v[118:121], v[182:185], v[94:97]
	v_mfma_f32_16x16x32_bf16 v[90:93], v[130:133], v[182:185], v[90:93]
	v_mfma_f32_16x16x32_bf16 v[78:81], v[118:121], v[200:203], v[78:81]
	v_mfma_f32_16x16x32_bf16 v[74:77], v[130:133], v[200:203], v[74:77]
	v_mfma_f32_16x16x32_bf16 v[134:137], v[138:141], v[162:165], v[134:137]
	v_mfma_f32_16x16x32_bf16 v[122:125], v[146:149], v[162:165], v[122:125]
	v_mfma_f32_16x16x32_bf16 v[102:105], v[138:141], v[170:173], v[102:105]
	v_mfma_f32_16x16x32_bf16 v[98:101], v[146:149], v[170:173], v[98:101]
	v_mfma_f32_16x16x32_bf16 v[86:89], v[138:141], v[178:181], v[86:89]
	v_mfma_f32_16x16x32_bf16 v[82:85], v[146:149], v[178:181], v[82:85]
	v_mfma_f32_16x16x32_bf16 v[70:73], v[138:141], v[186:189], v[70:73]
	v_mfma_f32_16x16x32_bf16 v[66:69], v[146:149], v[186:189], v[66:69]
	v_mfma_f32_16x16x32_bf16 v[134:137], v[142:145], v[166:169], v[134:137]
	v_mfma_f32_16x16x32_bf16 v[122:125], v[150:153], v[166:169], v[122:125]
	v_mfma_f32_16x16x32_bf16 v[102:105], v[142:145], v[174:177], v[102:105]
	v_mfma_f32_16x16x32_bf16 v[98:101], v[150:153], v[174:177], v[98:101]
	v_mfma_f32_16x16x32_bf16 v[86:89], v[142:145], v[182:185], v[86:89]
	v_mfma_f32_16x16x32_bf16 v[82:85], v[150:153], v[182:185], v[82:85]
	v_mfma_f32_16x16x32_bf16 v[70:73], v[142:145], v[200:203], v[70:73]
	v_mfma_f32_16x16x32_bf16 v[66:69], v[150:153], v[200:203], v[66:69]
	s_barrier
	s_setprio 0
	s_add_i32 s26, s40, s38
	s_mov_b32 m0, s26
	ds_read_b128 v[162:165], v225 offset:16384
	ds_read_b128 v[166:169], v225 offset:17408
	ds_read_b128 v[170:173], v225 offset:18432
	ds_read_b128 v[174:177], v225 offset:19456
	ds_read_b128 v[178:181], v225 offset:20480
	ds_read_b128 v[182:185], v225 offset:21504
	ds_read_b128 v[186:189], v225 offset:22528
	ds_read_b128 v[200:203], v225 offset:23552
	global_load_lds_dwordx4 v226, s[30:31]
	s_add_i32 m0, s26, 0x2000
	s_add_u32 s26, s30, 0x160000
	s_addc_u32 s27, s31, 0
	s_add_i32 s40, s41, s38
	global_load_lds_dwordx4 v190, s[30:31]
	s_mov_b32 m0, s40
	s_nop 0
	global_load_lds_dwordx4 v226, s[26:27]
	s_add_i32 m0, s40, 0x2000
	s_nop 0
	global_load_lds_dwordx4 v190, s[26:27]
	s_mov_b32 m0, s39
	s_nop 0
	global_load_lds_dwordx4 v194, s[34:35]
	s_mov_b32 m0, s42
	s_nop 0
	global_load_lds_dwordx4 v192, s[34:35]
	s_waitcnt vmcnt(8)
	s_waitcnt lgkmcnt(0)
	s_setprio 1
	s_barrier
	v_mfma_f32_16x16x32_bf16 v[62:65], v[114:117], v[162:165], v[62:65]
	v_mfma_f32_16x16x32_bf16 v[58:61], v[126:129], v[162:165], v[58:61]
	v_mfma_f32_16x16x32_bf16 v[46:49], v[114:117], v[170:173], v[46:49]
	v_mfma_f32_16x16x32_bf16 v[42:45], v[126:129], v[170:173], v[42:45]
	v_mfma_f32_16x16x32_bf16 v[30:33], v[114:117], v[178:181], v[30:33]
	v_mfma_f32_16x16x32_bf16 v[26:29], v[126:129], v[178:181], v[26:29]
	v_mfma_f32_16x16x32_bf16 v[14:17], v[114:117], v[186:189], v[14:17]
	v_mfma_f32_16x16x32_bf16 v[10:13], v[126:129], v[186:189], v[10:13]
	v_mfma_f32_16x16x32_bf16 v[62:65], v[118:121], v[166:169], v[62:65]
	v_mfma_f32_16x16x32_bf16 v[58:61], v[130:133], v[166:169], v[58:61]
	v_mfma_f32_16x16x32_bf16 v[46:49], v[118:121], v[174:177], v[46:49]
	v_mfma_f32_16x16x32_bf16 v[42:45], v[130:133], v[174:177], v[42:45]
	v_mfma_f32_16x16x32_bf16 v[30:33], v[118:121], v[182:185], v[30:33]
	v_mfma_f32_16x16x32_bf16 v[26:29], v[130:133], v[182:185], v[26:29]
	v_mfma_f32_16x16x32_bf16 v[14:17], v[118:121], v[200:203], v[14:17]
	v_mfma_f32_16x16x32_bf16 v[10:13], v[130:133], v[200:203], v[10:13]
	v_mfma_f32_16x16x32_bf16 v[54:57], v[138:141], v[162:165], v[54:57]
	v_mfma_f32_16x16x32_bf16 v[50:53], v[146:149], v[162:165], v[50:53]
	v_mfma_f32_16x16x32_bf16 v[38:41], v[138:141], v[170:173], v[38:41]
	v_mfma_f32_16x16x32_bf16 v[34:37], v[146:149], v[170:173], v[34:37]
	v_mfma_f32_16x16x32_bf16 v[22:25], v[138:141], v[178:181], v[22:25]
	v_mfma_f32_16x16x32_bf16 v[18:21], v[146:149], v[178:181], v[18:21]
	v_mfma_f32_16x16x32_bf16 v[6:9], v[138:141], v[186:189], v[6:9]
	v_mfma_f32_16x16x32_bf16 v[2:5], v[146:149], v[186:189], v[2:5]
	v_mfma_f32_16x16x32_bf16 v[54:57], v[142:145], v[166:169], v[54:57]
	v_mfma_f32_16x16x32_bf16 v[50:53], v[150:153], v[166:169], v[50:53]
	v_mfma_f32_16x16x32_bf16 v[38:41], v[142:145], v[174:177], v[38:41]
	v_mfma_f32_16x16x32_bf16 v[34:37], v[150:153], v[174:177], v[34:37]
	v_mfma_f32_16x16x32_bf16 v[22:25], v[142:145], v[182:185], v[22:25]
	v_mfma_f32_16x16x32_bf16 v[18:21], v[150:153], v[182:185], v[18:21]
	v_mfma_f32_16x16x32_bf16 v[6:9], v[142:145], v[200:203], v[6:9]
	v_mfma_f32_16x16x32_bf16 v[2:5], v[150:153], v[200:203], v[2:5]
	s_barrier
; #define PG8_STAGE(bufoff, gbase, voff) do { _Pragma("unroll") for (int _i = 0; _i < 2; ++_i) \
;         __builtin_amdgcn_global_load_lds((const unsigned*)((const char*)(gbase) + (voff)[_i]), (PG8_LAS unsigned*)(lds + (bufoff) + ldsw + _i * 8192), 16, 0, 0); } while (0)
; #define PG8_LDA(dst, b, h) do { _Pragma("unroll") for (int m = 0; m < 4; ++m) _Pragma("unroll") for (int k = 0; k < 2; ++k) dst[m][k] = *(const PG8_LAS bf16x8*)(lds + PG8_SA(b, h) + aoff + m * 2048 + k * 1024); } while (0)
; #define PG8_LDB(dst, b, h) do { _Pragma("unroll") for (int n = 0; n < 2; ++n) _Pragma("unroll") for (int k = 0; k < 2; ++k) dst[n][k] = *(const PG8_LAS bf16x8*)(lds + PG8_SB(b, h) + boff + n * 2048 + k * 1024); } while (0)
; #define PG8_MMA(ai, bj, At, Bt) do { __builtin_amdgcn_s_setprio(1); _Pragma("unroll") for (int m = 0; m < 4; ++m) _Pragma("unroll") for (int n = 0; n < 2; ++n) _Pragma("unroll") for (int k = 0; k < 2; ++k) \
;         acc[ai][bj][m][n] = __builtin_amdgcn_mfma_f32_16x16x32_bf16(Bt[n][k], At[m][k], acc[ai][bj][m][n], 0, 0, 0); __builtin_amdgcn_s_setprio(0); } while (0)
; #define PG8_WAIT_V(n) asm volatile("s_waitcnt vmcnt(" #n ")" ::: "memory")
; #define PG8_WAIT_L(n) asm volatile("s_waitcnt lgkmcnt(" #n ")" ::: "memory")
; #define PG8_BAR __builtin_amdgcn_s_barrier()
; #define PG8_SCHED __builtin_amdgcn_sched_barrier(0)
; template <class Prob, class Epi, class Sched>
; __device__ __forceinline__ void gemm_phase(PG8_LAS unsigned char* lds, const Prob g, const Sched& S, const Epi& E) {
;     ...
;             PG8_LDB(B0, 1, 0); PG8_LDB(B1, 1, 1); PG8_SCHED; PG8_LDA(At, 1, 0); PG8_STAGE(PG8_SA(0, 1), a2 + hstepA, voffA);
;             PG8_WAIT_V(8); PG8_WAIT_L(0); PG8_BAR; PG8_MMA(0, 0, At, B0); PG8_MMA(0, 1, At, B1); PG8_BAR; PG8_SCHED;
;             PG8_LDA(At, 1, 1); PG8_STAGE(PG8_SB(1, 0), b3, voffB); PG8_STAGE(PG8_SB(1, 1), b3 + hstepB, voffB); PG8_STAGE(PG8_SA(1, 0), a3, voffA);
;             PG8_WAIT_V(8); PG8_WAIT_L(0); PG8_BAR; PG8_MMA(1, 0, At, B0); PG8_MMA(1, 1, At, B1); PG8_BAR; PG8_SCHED;
;         }
;         if (wr == 0) PG8_BAR;
	s_setprio 0
	s_add_i32 s40, 0, 0x18000
	v_add_u32_e32 v1, s40, v223
	s_add_i32 s41, 0, 0x1c000
	ds_read_b128 v[114:117], v1
	ds_read_b128 v[118:121], v1 offset:1024
	ds_read_b128 v[126:129], v1 offset:2048
	ds_read_b128 v[130:133], v1 offset:3072
	v_add_u32_e32 v1, s41, v223
	ds_read_b128 v[138:141], v1
	ds_read_b128 v[142:145], v1 offset:1024
	ds_read_b128 v[146:149], v1 offset:2048
	ds_read_b128 v[150:153], v1 offset:3072
	s_add_u32 s26, s34, 0x160000
	s_addc_u32 s27, s35, 0
	s_mov_b32 m0, s43
	ds_read_b128 v[162:165], v225 offset:32768
	ds_read_b128 v[166:169], v225 offset:33792
	ds_read_b128 v[170:173], v225 offset:34816
	ds_read_b128 v[174:177], v225 offset:35840
	ds_read_b128 v[178:181], v225 offset:36864
	ds_read_b128 v[182:185], v225 offset:37888
	ds_read_b128 v[186:189], v225 offset:38912
	ds_read_b128 v[200:203], v225 offset:39936
	global_load_lds_dwordx4 v194, s[26:27]
	s_mov_b32 m0, s51
	s_nop 0
	global_load_lds_dwordx4 v192, s[26:27]
	s_waitcnt vmcnt(8)
	s_waitcnt lgkmcnt(0)
	s_setprio 1
	s_barrier
	v_mfma_f32_16x16x32_bf16 v[158:161], v[114:117], v[162:165], v[158:161]
	v_mfma_f32_16x16x32_bf16 v[154:157], v[126:129], v[162:165], v[154:157]
	v_mfma_f32_16x16x32_bf16 v[110:113], v[114:117], v[170:173], v[110:113]
	v_mfma_f32_16x16x32_bf16 v[106:109], v[126:129], v[170:173], v[106:109]
	v_mfma_f32_16x16x32_bf16 v[94:97], v[114:117], v[178:181], v[94:97]
	v_mfma_f32_16x16x32_bf16 v[90:93], v[126:129], v[178:181], v[90:93]
	v_mfma_f32_16x16x32_bf16 v[78:81], v[114:117], v[186:189], v[78:81]
	v_mfma_f32_16x16x32_bf16 v[74:77], v[126:129], v[186:189], v[74:77]
	v_mfma_f32_16x16x32_bf16 v[158:161], v[118:121], v[166:169], v[158:161]
	v_mfma_f32_16x16x32_bf16 v[154:157], v[130:133], v[166:169], v[154:157]
	v_mfma_f32_16x16x32_bf16 v[110:113], v[118:121], v[174:177], v[110:113]
	v_mfma_f32_16x16x32_bf16 v[106:109], v[130:133], v[174:177], v[106:109]
	v_mfma_f32_16x16x32_bf16 v[94:97], v[118:121], v[182:185], v[94:97]
	v_mfma_f32_16x16x32_bf16 v[90:93], v[130:133], v[182:185], v[90:93]
	v_mfma_f32_16x16x32_bf16 v[78:81], v[118:121], v[200:203], v[78:81]
	v_mfma_f32_16x16x32_bf16 v[74:77], v[130:133], v[200:203], v[74:77]
	v_mfma_f32_16x16x32_bf16 v[134:137], v[138:141], v[162:165], v[134:137]
	v_mfma_f32_16x16x32_bf16 v[122:125], v[146:149], v[162:165], v[122:125]
	v_mfma_f32_16x16x32_bf16 v[102:105], v[138:141], v[170:173], v[102:105]
	v_mfma_f32_16x16x32_bf16 v[98:101], v[146:149], v[170:173], v[98:101]
	v_mfma_f32_16x16x32_bf16 v[86:89], v[138:141], v[178:181], v[86:89]
	v_mfma_f32_16x16x32_bf16 v[82:85], v[146:149], v[178:181], v[82:85]
	v_mfma_f32_16x16x32_bf16 v[70:73], v[138:141], v[186:189], v[70:73]
	v_mfma_f32_16x16x32_bf16 v[66:69], v[146:149], v[186:189], v[66:69]
	v_mfma_f32_16x16x32_bf16 v[134:137], v[142:145], v[166:169], v[134:137]
	v_mfma_f32_16x16x32_bf16 v[122:125], v[150:153], v[166:169], v[122:125]
	v_mfma_f32_16x16x32_bf16 v[102:105], v[142:145], v[174:177], v[102:105]
	v_mfma_f32_16x16x32_bf16 v[98:101], v[150:153], v[174:177], v[98:101]
	v_mfma_f32_16x16x32_bf16 v[86:89], v[142:145], v[182:185], v[86:89]
	v_mfma_f32_16x16x32_bf16 v[82:85], v[150:153], v[182:185], v[82:85]
	v_mfma_f32_16x16x32_bf16 v[70:73], v[142:145], v[200:203], v[70:73]
	v_mfma_f32_16x16x32_bf16 v[66:69], v[150:153], v[200:203], v[66:69]
	s_barrier
	s_setprio 0
	s_add_i32 s26, s40, s38
	s_mov_b32 m0, s26
	ds_read_b128 v[162:165], v225 offset:49152
	ds_read_b128 v[166:169], v225 offset:50176
	ds_read_b128 v[170:173], v225 offset:51200
	ds_read_b128 v[174:177], v225 offset:52224
	ds_read_b128 v[178:181], v225 offset:53248
	ds_read_b128 v[182:185], v225 offset:54272
	ds_read_b128 v[186:189], v225 offset:55296
	ds_read_b128 v[200:203], v225 offset:56320
	s_add_u32 s100, s30, 0x80
	s_addc_u32 s101, s31, 0
	global_load_lds_dwordx4 v226, s[100:101]
	s_add_i32 m0, s26, 0x2000
	s_add_u32 s26, s30, 0x160080
	s_addc_u32 s27, s31, 0
	s_add_i32 s30, s41, s38
	global_load_lds_dwordx4 v190, s[100:101]
	s_mov_b32 m0, s30
	s_nop 0
	global_load_lds_dwordx4 v226, s[26:27]
	s_add_i32 m0, s30, 0x2000
	s_nop 0
	global_load_lds_dwordx4 v190, s[26:27]
	s_mov_b32 m0, s52
	s_nop 0
	s_add_u32 s100, s34, 0x80
	s_addc_u32 s101, s35, 0
	global_load_lds_dwordx4 v194, s[100:101]
	s_mov_b32 m0, s53
	s_nop 0
	global_load_lds_dwordx4 v192, s[100:101]
	s_waitcnt vmcnt(8)
	s_waitcnt lgkmcnt(0)
	s_setprio 1
	s_barrier
	v_mfma_f32_16x16x32_bf16 v[62:65], v[114:117], v[162:165], v[62:65]
	v_mfma_f32_16x16x32_bf16 v[58:61], v[126:129], v[162:165], v[58:61]
	v_mfma_f32_16x16x32_bf16 v[46:49], v[114:117], v[170:173], v[46:49]
	v_mfma_f32_16x16x32_bf16 v[42:45], v[126:129], v[170:173], v[42:45]
	v_mfma_f32_16x16x32_bf16 v[30:33], v[114:117], v[178:181], v[30:33]
	v_mfma_f32_16x16x32_bf16 v[26:29], v[126:129], v[178:181], v[26:29]
	v_mfma_f32_16x16x32_bf16 v[14:17], v[114:117], v[186:189], v[14:17]
	v_mfma_f32_16x16x32_bf16 v[10:13], v[126:129], v[186:189], v[10:13]
	v_mfma_f32_16x16x32_bf16 v[62:65], v[118:121], v[166:169], v[62:65]
	v_mfma_f32_16x16x32_bf16 v[58:61], v[130:133], v[166:169], v[58:61]
	v_mfma_f32_16x16x32_bf16 v[46:49], v[118:121], v[174:177], v[46:49]
	v_mfma_f32_16x16x32_bf16 v[42:45], v[130:133], v[174:177], v[42:45]
	v_mfma_f32_16x16x32_bf16 v[30:33], v[118:121], v[182:185], v[30:33]
	v_mfma_f32_16x16x32_bf16 v[26:29], v[130:133], v[182:185], v[26:29]
	v_mfma_f32_16x16x32_bf16 v[14:17], v[118:121], v[200:203], v[14:17]
	v_mfma_f32_16x16x32_bf16 v[10:13], v[130:133], v[200:203], v[10:13]
	v_mfma_f32_16x16x32_bf16 v[54:57], v[138:141], v[162:165], v[54:57]
	v_mfma_f32_16x16x32_bf16 v[50:53], v[146:149], v[162:165], v[50:53]
	v_mfma_f32_16x16x32_bf16 v[38:41], v[138:141], v[170:173], v[38:41]
	v_mfma_f32_16x16x32_bf16 v[34:37], v[146:149], v[170:173], v[34:37]
	v_mfma_f32_16x16x32_bf16 v[22:25], v[138:141], v[178:181], v[22:25]
	v_mfma_f32_16x16x32_bf16 v[18:21], v[146:149], v[178:181], v[18:21]
	v_mfma_f32_16x16x32_bf16 v[6:9], v[138:141], v[186:189], v[6:9]
	v_mfma_f32_16x16x32_bf16 v[2:5], v[146:149], v[186:189], v[2:5]
	v_mfma_f32_16x16x32_bf16 v[54:57], v[142:145], v[166:169], v[54:57]
	v_mfma_f32_16x16x32_bf16 v[50:53], v[150:153], v[166:169], v[50:53]
	v_mfma_f32_16x16x32_bf16 v[38:41], v[142:145], v[174:177], v[38:41]
	v_mfma_f32_16x16x32_bf16 v[34:37], v[150:153], v[174:177], v[34:37]
	v_mfma_f32_16x16x32_bf16 v[22:25], v[142:145], v[182:185], v[22:25]
	v_mfma_f32_16x16x32_bf16 v[18:21], v[150:153], v[182:185], v[18:21]
	v_mfma_f32_16x16x32_bf16 v[6:9], v[142:145], v[200:203], v[6:9]
	v_mfma_f32_16x16x32_bf16 v[2:5], v[150:153], v[200:203], v[2:5]
	s_barrier
	s_setprio 0
	s_add_i32 s64, s64, 2
	s_add_u32 s44, s44, 0x100
	s_addc_u32 s45, s45, 0
	s_cmpk_gt_u32 s64, 0x55
	s_mov_b64 s[26:27], s[28:29]
	s_cbranch_scc0 .LBB0_1021
	s_and_b64 vcc, exec, s[22:23]
	s_cbranch_vccz .LBB0_1024
	s_barrier
